# v75 + attention code: packed f32 adds between MFMAs split into two single-lane VOP2 ops (bit-identical)
# baseline (speedup 1.0000x reference)
.LBB0_795:
	v_sub_f32_e32 v50, v158, v2
	v_sub_f32_e32 v51, v159, v2
	v_sub_f32_e32 v156, v156, v2
	v_sub_f32_e32 v157, v157, v2
	v_exp_f32_e32 v66, v50
	v_exp_f32_e32 v67, v51
	v_exp_f32_e32 v50, v156
	v_exp_f32_e32 v51, v157
	v_sub_f32_e32 v52, v52, v2
	v_sub_f32_e32 v53, v53, v2
	v_sub_f32_e32 v36, v36, v2
	v_sub_f32_e32 v37, v37, v2
	v_exp_f32_e32 v52, v52
	v_exp_f32_e32 v53, v53
	v_exp_f32_e32 v36, v36
	v_exp_f32_e32 v37, v37
	v_sub_f32_e32 v54, v54, v2
	v_sub_f32_e32 v55, v55, v2
	v_sub_f32_e32 v38, v38, v2
	v_sub_f32_e32 v39, v39, v2
	v_exp_f32_e32 v54, v54
	v_exp_f32_e32 v55, v55
	v_exp_f32_e32 v38, v38
	v_exp_f32_e32 v39, v39
	v_add_f32_e32 v156, v50, v66
	v_add_f32_e32 v157, v51, v67
	v_add_f32_e32 v158, v36, v52
	v_add_f32_e32 v159, v37, v53
	v_pk_add_f32 v[156:157], v[156:157], 0 op_sel_hi:[1,0]
	v_sub_f32_e32 v56, v56, v2
	v_sub_f32_e32 v57, v57, v2
	v_add_f32_e32 v156, v158, v156
	v_add_f32_e32 v157, v159, v157
	v_add_f32_e32 v158, v38, v54
	v_add_f32_e32 v159, v39, v55
	v_sub_f32_e32 v40, v40, v2
	v_sub_f32_e32 v41, v41, v2
	v_add_f32_e32 v156, v158, v156
	v_add_f32_e32 v157, v159, v157
	v_exp_f32_e32 v56, v56
	v_exp_f32_e32 v57, v57
	v_exp_f32_e32 v158, v40
	v_exp_f32_e32 v159, v41
	v_sub_f32_e32 v58, v58, v2
	v_sub_f32_e32 v59, v59, v2
	v_sub_f32_e32 v42, v42, v2
	v_sub_f32_e32 v43, v43, v2
	v_exp_f32_e32 v58, v58
	v_add_f32_e32 v40, v158, v56
	v_add_f32_e32 v41, v159, v57
	v_exp_f32_e32 v59, v59
	v_add_f32_e32 v40, v40, v156
	v_add_f32_e32 v41, v41, v157
	v_exp_f32_e32 v156, v42
	v_exp_f32_e32 v157, v43
	v_sub_f32_e32 v44, v44, v2
	v_sub_f32_e32 v45, v45, v2
	s_add_i32 s5, s79, 2
	v_exp_f32_e32 v194, v44
	v_add_f32_e32 v42, v156, v58
	v_add_f32_e32 v43, v157, v59
	v_exp_f32_e32 v195, v45
	v_add_f32_e32 v40, v42, v40
	v_add_f32_e32 v41, v43, v41
	v_sub_f32_e32 v42, v60, v2
	v_sub_f32_e32 v43, v61, v2
	v_sub_f32_e32 v44, v46, v2
	v_sub_f32_e32 v45, v47, v2
	v_exp_f32_e32 v60, v42
	v_exp_f32_e32 v61, v43
	s_add_i32 s4, s79, -2
	v_add_u32_e32 v189, 0xf8, v189
	v_add_u32_e32 v190, 0x2d00, v190
	v_add_f32_e32 v42, v194, v60
	v_add_f32_e32 v43, v195, v61
	v_add_u32_e32 v191, 0xa0, v191
	v_add_f32_e32 v40, v42, v40
	v_add_f32_e32 v41, v43, v41
	v_sub_f32_e32 v42, v62, v2
	v_sub_f32_e32 v43, v63, v2
	v_exp_f32_e32 v62, v44
	v_exp_f32_e32 v46, v42
	v_exp_f32_e32 v47, v43
	v_exp_f32_e32 v63, v45
	v_sub_f32_e32 v44, v48, v2
	v_sub_f32_e32 v45, v49, v2
	v_add_u32_e32 v192, 0xa0, v192
	s_cmp_lt_u32 s4, s9
	v_add_f32_e32 v42, v62, v46
	v_add_f32_e32 v43, v63, v47
	v_cvt_pk_bf16_f32 v46, v46, v47
	v_add_f32_e32 v40, v42, v40
	v_add_f32_e32 v41, v43, v41
	v_sub_f32_e32 v42, v64, v2
	v_sub_f32_e32 v43, v65, v2
	v_exp_f32_e32 v64, v44
	v_exp_f32_e32 v48, v42
	v_exp_f32_e32 v49, v43
	v_exp_f32_e32 v65, v45
	v_cvt_pk_bf16_f32 v44, v58, v59
	v_cvt_pk_bf16_f32 v45, v60, v61
	v_cvt_pk_bf16_f32 v47, v48, v49
	v_add_f32_e32 v42, v64, v48
	v_add_f32_e32 v43, v65, v49
	v_cvt_pk_bf16_f32 v48, v50, v51
	v_add_f32_e32 v40, v42, v40
	v_add_f32_e32 v41, v43, v41
	v_cvt_pk_bf16_f32 v42, v54, v55
	v_add_f32_e32 v0, v40, v41
	v_cvt_pk_bf16_f32 v40, v66, v67
	v_cvt_pk_bf16_f32 v41, v52, v53
	v_cvt_pk_bf16_f32 v43, v56, v57
	v_cvt_pk_bf16_f32 v49, v36, v37
	v_cvt_pk_bf16_f32 v50, v38, v39
	s_waitcnt lgkmcnt(11)
	v_mfma_f32_32x32x16_bf16 v[20:35], v[128:131], v[40:43], v[20:35]
	v_cvt_pk_bf16_f32 v51, v158, v159
	v_cvt_pk_bf16_f32 v36, v156, v157
	v_cvt_pk_bf16_f32 v37, v194, v195
	v_cvt_pk_bf16_f32 v38, v62, v63
	v_cvt_pk_bf16_f32 v39, v64, v65
	v_add_f32_e32 v164, v164, v0
	s_waitcnt lgkmcnt(10)
	v_mfma_f32_32x32x16_bf16 v[4:19], v[124:127], v[40:43], v[4:19]
	s_waitcnt lgkmcnt(6)
	v_mfma_f32_32x32x16_bf16 v[20:35], v[120:123], v[44:47], v[20:35]
	s_waitcnt lgkmcnt(4)
	v_mfma_f32_32x32x16_bf16 v[4:19], v[116:119], v[44:47], v[4:19]
	v_mfma_f32_32x32x16_bf16 v[20:35], v[112:115], v[48:51], v[20:35]
	v_mfma_f32_32x32x16_bf16 v[4:19], v[108:111], v[48:51], v[4:19]
	s_waitcnt lgkmcnt(2)
	v_mfma_f32_32x32x16_bf16 v[20:35], v[104:107], v[36:39], v[20:35]
	s_waitcnt lgkmcnt(0)
	v_mfma_f32_32x32x16_bf16 v[4:19], v[100:103], v[36:39], v[4:19]
	s_cbranch_scc0 .LBB0_798
	s_mov_b32 s79, s5
	s_branch .LBB0_728

.LBB0_844:
	v_sub_f32_e32 v60, v60, v116
	v_sub_f32_e32 v61, v61, v116
	v_sub_f32_e32 v118, v44, v116
	v_sub_f32_e32 v119, v45, v116
	v_exp_f32_e32 v44, v60
	v_exp_f32_e32 v45, v61
	v_sub_f32_e32 v60, v62, v116
	v_sub_f32_e32 v61, v63, v116
	v_sub_f32_e32 v46, v46, v116
	v_sub_f32_e32 v47, v47, v116
	v_exp_f32_e32 v120, v60
	v_exp_f32_e32 v121, v61
	v_sub_f32_e32 v60, v64, v116
	v_sub_f32_e32 v61, v65, v116
	v_sub_f32_e32 v64, v68, v116
	v_sub_f32_e32 v65, v69, v116
	v_exp_f32_e32 v122, v60
	v_exp_f32_e32 v123, v61
	v_sub_f32_e32 v60, v66, v116
	v_sub_f32_e32 v61, v67, v116
	v_exp_f32_e32 v130, v64
	v_exp_f32_e32 v128, v60
	v_exp_f32_e32 v129, v61
	v_cvt_pk_bf16_f32 v60, v44, v45
	v_cvt_pk_bf16_f32 v61, v120, v121
	v_cvt_pk_bf16_f32 v62, v122, v123
	v_cvt_pk_bf16_f32 v63, v128, v129
	v_exp_f32_e32 v131, v65
	v_sub_f32_e32 v64, v70, v116
	v_sub_f32_e32 v65, v71, v116
	s_waitcnt lgkmcnt(5)
	v_mfma_f32_32x32x16_bf16 v[4:19], v[108:111], v[60:63], v[4:19]
	v_exp_f32_e32 v118, v118
	v_exp_f32_e32 v119, v119
	v_sub_f32_e32 v52, v52, v116
	v_sub_f32_e32 v53, v53, v116
	v_sub_f32_e32 v54, v54, v116
	v_sub_f32_e32 v55, v55, v116
	v_sub_f32_e32 v56, v56, v116
	v_sub_f32_e32 v57, v57, v116
	v_mfma_f32_32x32x16_bf16 v[20:35], v[112:115], v[60:63], v[20:35]
	v_exp_f32_e32 v112, v64
	v_exp_f32_e32 v113, v65
	v_sub_f32_e32 v64, v72, v116
	v_sub_f32_e32 v65, v73, v116
	v_sub_f32_e32 v60, v74, v116
	v_sub_f32_e32 v61, v75, v116
	v_exp_f32_e32 v114, v64
	v_exp_f32_e32 v115, v65
	v_exp_f32_e32 v108, v60
	v_exp_f32_e32 v109, v61
	v_cvt_pk_bf16_f32 v60, v130, v131
	v_cvt_pk_bf16_f32 v61, v112, v113
	v_cvt_pk_bf16_f32 v62, v114, v115
	v_cvt_pk_bf16_f32 v63, v108, v109
	s_waitcnt lgkmcnt(2)
	s_nop 0
	v_mfma_f32_32x32x16_bf16 v[4:19], v[100:103], v[60:63], v[4:19]
	v_mfma_f32_32x32x16_bf16 v[20:35], v[104:107], v[60:63], v[20:35]
	v_exp_f32_e32 v104, v46
	v_exp_f32_e32 v105, v47
	v_sub_f32_e32 v46, v48, v116
	v_sub_f32_e32 v47, v49, v116
	v_add_f32_e32 v120, v104, v120
	v_add_f32_e32 v121, v105, v121
	v_exp_f32_e32 v110, v46
	v_exp_f32_e32 v111, v47
	v_sub_f32_e32 v46, v50, v116
	v_sub_f32_e32 v47, v51, v116
	v_cvt_pk_bf16_f32 v48, v110, v111
	v_exp_f32_e32 v138, v46
	v_exp_f32_e32 v139, v47
	v_cvt_pk_bf16_f32 v46, v118, v119
	v_cvt_pk_bf16_f32 v47, v104, v105
	v_add_f32_e32 v110, v110, v122
	v_add_f32_e32 v111, v111, v123
	v_cvt_pk_bf16_f32 v49, v138, v139
	s_nop 1
	v_mfma_f32_32x32x16_bf16 v[4:19], v[36:39], v[46:49], v[4:19]
	ds_read_b128 v[36:39], v124 offset:9216
	ds_read_b128 v[100:103], v124 offset:9248
	ds_read_b128 v[104:107], v124 offset:13856
	s_waitcnt lgkmcnt(2)
	v_mfma_f32_32x32x16_bf16 v[60:75], v[36:39], v[96:99], 0
	ds_read_b128 v[36:39], v124 offset:13824
	v_mfma_f32_32x32x16_bf16 v[20:35], v[40:43], v[46:49], v[20:35]
	v_add_f32_e64 v40, v118, v44
	v_add_f32_e64 v41, v119, v45
	v_add_f32_e64 v118, v40, 0
	v_add_f32_e64 v119, v41, 0
	v_add_f32_e64 v118, v120, v118
	v_add_f32_e64 v119, v121, v119
	v_add_f32_e32 v110, v110, v118
	v_add_f32_e32 v111, v111, v119
	v_exp_f32_e32 v118, v52
	v_exp_f32_e32 v119, v53
	v_add_f32_e32 v52, v138, v128
	v_add_f32_e32 v53, v139, v129
	s_waitcnt lgkmcnt(2)
	v_mfma_f32_32x32x16_bf16 v[60:75], v[100:103], v[92:95], v[60:75]
	v_add_f32_e64 v52, v52, v110
	v_add_f32_e64 v53, v53, v111
	v_add_f32_e64 v100, v118, v130
	v_add_f32_e64 v101, v119, v131
	v_exp_f32_e32 v110, v54
	v_exp_f32_e32 v111, v55
	v_add_f32_e32 v120, v100, v52
	v_add_f32_e32 v121, v101, v53
	ds_read_b128 v[52:55], v124 offset:9280
	v_cvt_pk_bf16_f32 v128, v118, v119
	s_waitcnt lgkmcnt(1)
	v_mfma_f32_32x32x16_bf16 v[36:51], v[36:39], v[96:99], 0
	v_cvt_pk_bf16_f32 v129, v110, v111
	v_mfma_f32_32x32x16_bf16 v[36:51], v[104:107], v[92:95], v[36:51]
	v_add_f32_e64 v104, v110, v112
	v_add_f32_e64 v105, v111, v113
	v_exp_f32_e32 v112, v56
	v_exp_f32_e32 v113, v57
	v_sub_f32_e32 v106, v58, v116
	v_sub_f32_e32 v107, v59, v116
	ds_read_b128 v[56:59], v124 offset:13888
	ds_read_b128 v[100:103], v124 offset:9312
	v_cvt_pk_bf16_f32 v130, v112, v113
	s_waitcnt lgkmcnt(2)
	v_mfma_f32_32x32x16_bf16 v[60:75], v[52:55], v[88:91], v[60:75]
	v_add_f32_e64 v54, v104, v120
	v_add_f32_e64 v55, v105, v121
	v_add_f32_e64 v104, v112, v114
	v_add_f32_e64 v105, v113, v115
	v_exp_f32_e32 v52, v106
	v_exp_f32_e32 v53, v107
	v_add_f32_e32 v54, v104, v54
	v_add_f32_e32 v55, v105, v55
	ds_read_b128 v[104:107], v124 offset:13920
	v_add_f32_e32 v108, v52, v108
	v_add_f32_e32 v109, v53, v109
	s_waitcnt lgkmcnt(2)
	v_mfma_f32_32x32x16_bf16 v[36:51], v[56:59], v[88:91], v[36:51]
	v_add_f32_e64 v54, v108, v54
	v_add_f32_e64 v55, v109, v55
	v_cvt_pk_bf16_f32 v131, v52, v53
	v_add_f32_e32 v0, v54, v55
	v_add_f32_e32 v127, v164, v0
	s_waitcnt lgkmcnt(1)
	v_mfma_f32_32x32x16_bf16 v[60:75], v[100:103], v[84:87], v[60:75]
	ds_read2_b64 v[120:123], v125 offset0:16 offset1:18
	ds_read2_b64 v[108:111], v125 offset0:20 offset1:22
	ds_read2_b64 v[116:119], v126 offset0:48 offset1:50
	ds_read2_b64 v[56:59], v125 offset0:24 offset1:26
	ds_read2_b64 v[52:55], v126 offset0:56 offset1:58
	ds_read2_b64 v[100:103], v126 offset0:52 offset1:54
	ds_read2_b64 v[112:115], v125 offset0:28 offset1:30
	s_waitcnt lgkmcnt(7)
	v_mfma_f32_32x32x16_bf16 v[36:51], v[104:107], v[84:87], v[36:51]
	ds_read2_b64 v[104:107], v126 offset0:60 offset1:62
	v_mfma_f32_32x32x16_bf16 v[20:35], v[80:83], v[128:131], v[20:35]
	s_nop 9
	v_maximum3_f32 v0, v61, v37, v37
	v_maximum3_f32 v0, v60, v36, v0
	v_maximum3_f32 v1, v62, v38, v38
	v_maximum3_f32 v134, v63, v39, v39
	v_maximum3_f32 v0, v0, v1, v134
	v_maximum3_f32 v1, v64, v40, v40
	v_maximum3_f32 v80, v65, v41, v41
	v_maximum3_f32 v0, v0, v1, v80
	v_maximum3_f32 v1, v66, v42, v42
	v_maximum3_f32 v80, v67, v43, v43
	v_maximum3_f32 v0, v0, v1, v80
	v_maximum3_f32 v1, v68, v44, v44
	v_maximum3_f32 v80, v69, v45, v45
	v_mfma_f32_32x32x16_bf16 v[4:19], v[76:79], v[128:131], v[4:19]
	v_maximum3_f32 v0, v0, v1, v80
	v_maximum3_f32 v1, v70, v46, v46
	v_maximum3_f32 v76, v71, v47, v47
	v_maximum3_f32 v0, v0, v1, v76
	v_maximum3_f32 v1, v72, v48, v48
	v_maximum3_f32 v76, v73, v49, v49
	v_maximum3_f32 v0, v0, v1, v76
	v_maximum3_f32 v1, v74, v50, v50
	v_maximum3_f32 v76, v75, v51, v51
	v_maximum3_f32 v0, v0, v1, v76
	v_mov_b32_e32 v1, v0
	s_nop 1
	v_permlane32_swap_b32_e32 v0, v1
	s_nop 0
	v_maximum3_f32 v76, v0, v1, v1
	v_cmp_gt_f32_e32 vcc, v76, v135
	s_cbranch_vccz .LBB0_846
	v_maximum3_f32 v2, v135, v76, v76
	v_sub_f32_e32 v0, v135, v2
	v_exp_f32_e32 v76, v0
	v_mov_b32_e32 v135, v2
	v_mul_f32_e32 v127, v127, v76
	v_pk_mul_f32 v[34:35], v[34:35], v[76:77] op_sel_hi:[1,0]
	v_pk_mul_f32 v[32:33], v[32:33], v[76:77] op_sel_hi:[1,0]
	v_pk_mul_f32 v[30:31], v[30:31], v[76:77] op_sel_hi:[1,0]
	v_pk_mul_f32 v[28:29], v[28:29], v[76:77] op_sel_hi:[1,0]
	v_pk_mul_f32 v[26:27], v[26:27], v[76:77] op_sel_hi:[1,0]
	v_pk_mul_f32 v[24:25], v[24:25], v[76:77] op_sel_hi:[1,0]
	v_pk_mul_f32 v[22:23], v[22:23], v[76:77] op_sel_hi:[1,0]
	v_pk_mul_f32 v[20:21], v[20:21], v[76:77] op_sel_hi:[1,0]
	v_pk_mul_f32 v[18:19], v[18:19], v[76:77] op_sel_hi:[1,0]
	v_pk_mul_f32 v[16:17], v[16:17], v[76:77] op_sel_hi:[1,0]
	v_pk_mul_f32 v[14:15], v[14:15], v[76:77] op_sel_hi:[1,0]
	v_pk_mul_f32 v[12:13], v[12:13], v[76:77] op_sel_hi:[1,0]
	v_pk_mul_f32 v[10:11], v[10:11], v[76:77] op_sel_hi:[1,0]
	v_pk_mul_f32 v[8:9], v[8:9], v[76:77] op_sel_hi:[1,0]
	v_pk_mul_f32 v[6:7], v[6:7], v[76:77] op_sel_hi:[1,0]
	v_pk_mul_f32 v[4:5], v[4:5], v[76:77] op_sel_hi:[1,0]
.LBB0_846:
	v_sub_f32_e32 v62, v62, v2
	v_sub_f32_e32 v63, v63, v2
	v_sub_f32_e32 v60, v60, v2
	v_sub_f32_e32 v61, v61, v2
	v_exp_f32_e32 v128, v62
	v_exp_f32_e32 v129, v63
	v_sub_f32_e32 v62, v64, v2
	v_sub_f32_e32 v63, v65, v2
	v_sub_f32_e32 v76, v36, v2
	v_sub_f32_e32 v77, v37, v2
	v_exp_f32_e32 v130, v62
	v_exp_f32_e32 v131, v63
	v_sub_f32_e32 v62, v66, v2
	v_sub_f32_e32 v63, v67, v2
	v_exp_f32_e32 v36, v60
	v_exp_f32_e32 v37, v61
	v_exp_f32_e32 v138, v62
	v_exp_f32_e32 v139, v63
	v_cvt_pk_bf16_f32 v63, v128, v129
	v_cvt_pk_bf16_f32 v62, v36, v37
	v_cvt_pk_bf16_f32 v64, v130, v131
	v_cvt_pk_bf16_f32 v65, v138, v139
	v_sub_f32_e32 v66, v68, v2
	v_sub_f32_e32 v67, v69, v2
	v_sub_f32_e32 v38, v38, v2
	v_sub_f32_e32 v39, v39, v2
	s_waitcnt lgkmcnt(7)
	v_mfma_f32_32x32x16_bf16 v[20:35], v[120:123], v[62:65], v[20:35]
	v_exp_f32_e32 v140, v66
	v_exp_f32_e32 v141, v67
	v_sub_f32_e32 v66, v70, v2
	v_sub_f32_e32 v67, v71, v2
	v_exp_f32_e32 v60, v76
	v_exp_f32_e32 v120, v66
	v_exp_f32_e32 v121, v67
	v_sub_f32_e32 v66, v72, v2
	v_sub_f32_e32 v67, v73, v2
	s_waitcnt lgkmcnt(5)
	v_mfma_f32_32x32x16_bf16 v[4:19], v[116:119], v[62:65], v[4:19]
	v_add_f32_e64 v62, v74, -v2
	v_add_f32_e64 v63, v75, -v2
	v_exp_f32_e32 v122, v66
	v_exp_f32_e32 v123, v67
	v_exp_f32_e32 v116, v62
	v_exp_f32_e32 v117, v63
	v_cvt_pk_bf16_f32 v62, v140, v141
	v_cvt_pk_bf16_f32 v63, v120, v121
	v_cvt_pk_bf16_f32 v64, v122, v123
	v_cvt_pk_bf16_f32 v65, v116, v117
	v_exp_f32_e32 v66, v38
	v_exp_f32_e32 v67, v39
	v_mfma_f32_32x32x16_bf16 v[20:35], v[108:111], v[62:65], v[20:35]
	v_add_f32_e64 v38, v40, -v2
	v_add_f32_e64 v39, v41, -v2
	v_exp_f32_e32 v61, v77
	v_exp_f32_e32 v118, v38
	v_exp_f32_e32 v119, v39
	v_sub_f32_e32 v38, v42, v2
	v_sub_f32_e32 v39, v43, v2
	v_add_f32_e32 v36, v60, v36
	v_add_f32_e32 v37, v61, v37
	v_exp_f32_e32 v42, v38
	s_waitcnt lgkmcnt(2)
	v_mfma_f32_32x32x16_bf16 v[4:19], v[100:103], v[62:65], v[4:19]
	v_exp_f32_e32 v43, v39
	v_cvt_pk_bf16_f32 v38, v60, v61
	v_cvt_pk_bf16_f32 v39, v66, v67
	v_cvt_pk_bf16_f32 v40, v118, v119
	v_cvt_pk_bf16_f32 v41, v42, v43
	v_pk_add_f32 v[36:37], v[36:37], 0 op_sel_hi:[1,0]
	v_add_f32_e32 v128, v66, v128
	v_add_f32_e32 v129, v67, v129
	v_mfma_f32_32x32x16_bf16 v[20:35], v[56:59], v[38:41], v[20:35]
	v_add_f32_e64 v36, v128, v36
	v_add_f32_e64 v37, v129, v37
	v_add_f32_e64 v50, v50, -v2
	v_add_f32_e64 v51, v51, -v2
	v_mfma_f32_32x32x16_bf16 v[4:19], v[52:55], v[38:41], v[4:19]
	ds_read_b128 v[38:41], v124 offset:18432
	ds_read_b128 v[100:103], v124 offset:18464
	ds_read_b128 v[108:111], v124 offset:23072
	s_waitcnt lgkmcnt(2)
	v_mfma_f32_32x32x16_bf16 v[68:83], v[38:41], v[96:99], 0
	ds_read_b128 v[38:41], v124 offset:23040
	s_waitcnt lgkmcnt(0)
	v_mfma_f32_32x32x16_bf16 v[52:67], v[38:41], v[96:99], 0
	v_add_f32_e64 v38, v118, v130
	v_add_f32_e64 v39, v119, v131
	v_add_f32_e64 v40, v46, -v2
	v_add_f32_e64 v41, v47, -v2
	v_add_f32_e64 v36, v38, v36
	v_add_f32_e64 v37, v39, v37
	v_sub_f32_e32 v38, v44, v2
	v_sub_f32_e32 v39, v45, v2
	v_exp_f32_e32 v130, v40
	v_exp_f32_e32 v118, v38
	v_exp_f32_e32 v119, v39
	v_add_f32_e32 v38, v42, v138
	v_add_f32_e32 v39, v43, v139
	v_mfma_f32_32x32x16_bf16 v[68:83], v[100:103], v[92:95], v[68:83]
	v_add_f32_e64 v36, v38, v36
	v_add_f32_e64 v37, v39, v37
	v_add_f32_e64 v38, v118, v140
	v_add_f32_e64 v39, v119, v141
	v_exp_f32_e32 v131, v41
	v_add_f32_e32 v100, v38, v36
	v_add_f32_e32 v101, v39, v37
	ds_read_b128 v[36:39], v124 offset:18496
	v_sub_f32_e32 v40, v48, v2
	v_sub_f32_e32 v41, v49, v2
	v_add_f32_e32 v102, v130, v120
	v_add_f32_e32 v103, v131, v121
	v_mfma_f32_32x32x16_bf16 v[52:67], v[108:111], v[92:95], v[52:67]
	v_exp_f32_e32 v48, v40
	v_exp_f32_e32 v49, v41
	ds_read_b128 v[40:43], v124 offset:23104
	ds_read_b128 v[44:47], v124 offset:18528
	v_cvt_pk_bf16_f32 v128, v118, v119
	v_cvt_pk_bf16_f32 v129, v130, v131
	v_cvt_pk_bf16_f32 v130, v48, v49
	s_waitcnt lgkmcnt(2)
	v_mfma_f32_32x32x16_bf16 v[68:83], v[36:39], v[88:91], v[68:83]
	v_add_f32_e64 v38, v102, v100
	v_add_f32_e64 v39, v103, v101
	ds_read_b128 v[100:103], v124 offset:23136
	v_exp_f32_e32 v36, v50
	v_exp_f32_e32 v37, v51
	v_add_f32_e32 v50, v48, v122
	v_add_f32_e32 v51, v49, v123
	v_cvt_pk_bf16_f32 v131, v36, v37
	s_waitcnt lgkmcnt(2)
	v_mfma_f32_32x32x16_bf16 v[52:67], v[40:43], v[88:91], v[52:67]
	v_add_f32_e64 v38, v50, v38
	v_add_f32_e64 v39, v51, v39
	v_add_f32_e64 v50, v36, v116
	v_add_f32_e64 v51, v37, v117
	v_add_f32_e64 v38, v50, v38
	v_add_f32_e64 v39, v51, v39
	v_add_f32_e32 v0, v38, v39
	v_add_f32_e32 v127, v127, v0
	s_waitcnt lgkmcnt(1)
	v_mfma_f32_32x32x16_bf16 v[68:83], v[44:47], v[84:87], v[68:83]
	ds_read2_b64 v[120:123], v125 offset0:32 offset1:34
	ds_read2_b64 v[48:51], v125 offset0:36 offset1:38
	ds_read2_b64 v[116:119], v126 offset0:64 offset1:66
	ds_read2_b64 v[40:43], v125 offset0:40 offset1:42
	ds_read2_b64 v[36:39], v126 offset0:72 offset1:74
	ds_read2_b64 v[44:47], v126 offset0:68 offset1:70
	ds_read2_b64 v[108:111], v125 offset0:44 offset1:46
	s_waitcnt lgkmcnt(7)
	v_mfma_f32_32x32x16_bf16 v[52:67], v[100:103], v[84:87], v[52:67]
	ds_read2_b64 v[100:103], v126 offset0:76 offset1:78
	v_mfma_f32_32x32x16_bf16 v[20:35], v[112:115], v[128:131], v[20:35]
	s_nop 9
	v_maximum3_f32 v0, v69, v53, v53
	v_maximum3_f32 v0, v68, v52, v0
	v_maximum3_f32 v1, v70, v54, v54
	v_maximum3_f32 v134, v71, v55, v55
	v_maximum3_f32 v0, v0, v1, v134
	v_maximum3_f32 v1, v72, v56, v56
	v_maximum3_f32 v112, v73, v57, v57
	v_maximum3_f32 v0, v0, v1, v112
	v_maximum3_f32 v1, v74, v58, v58
	v_maximum3_f32 v112, v75, v59, v59
	v_maximum3_f32 v0, v0, v1, v112
	v_maximum3_f32 v1, v76, v60, v60
	v_maximum3_f32 v112, v77, v61, v61
	v_mfma_f32_32x32x16_bf16 v[4:19], v[104:107], v[128:131], v[4:19]
	v_maximum3_f32 v0, v0, v1, v112
	v_maximum3_f32 v1, v78, v62, v62
	v_maximum3_f32 v104, v79, v63, v63
	v_maximum3_f32 v0, v0, v1, v104
	v_maximum3_f32 v1, v80, v64, v64
	v_maximum3_f32 v104, v81, v65, v65
	v_maximum3_f32 v0, v0, v1, v104
	v_maximum3_f32 v1, v82, v66, v66
	v_maximum3_f32 v104, v83, v67, v67
	v_maximum3_f32 v0, v0, v1, v104
	v_mov_b32_e32 v1, v0
	s_nop 1
	v_permlane32_swap_b32_e32 v0, v1
	s_nop 0
	v_maximum3_f32 v104, v0, v1, v1
	v_cmp_gt_f32_e32 vcc, v104, v135
	s_cbranch_vccz .LBB0_848
	v_maximum3_f32 v2, v135, v104, v104
	v_sub_f32_e32 v0, v135, v2
	v_exp_f32_e32 v104, v0
	v_mov_b32_e32 v135, v2
	v_mul_f32_e32 v127, v127, v104
	v_pk_mul_f32 v[34:35], v[34:35], v[104:105] op_sel_hi:[1,0]
	v_pk_mul_f32 v[32:33], v[32:33], v[104:105] op_sel_hi:[1,0]
	v_pk_mul_f32 v[30:31], v[30:31], v[104:105] op_sel_hi:[1,0]
	v_pk_mul_f32 v[28:29], v[28:29], v[104:105] op_sel_hi:[1,0]
	v_pk_mul_f32 v[26:27], v[26:27], v[104:105] op_sel_hi:[1,0]
	v_pk_mul_f32 v[24:25], v[24:25], v[104:105] op_sel_hi:[1,0]
	v_pk_mul_f32 v[22:23], v[22:23], v[104:105] op_sel_hi:[1,0]
	v_pk_mul_f32 v[20:21], v[20:21], v[104:105] op_sel_hi:[1,0]
	v_pk_mul_f32 v[18:19], v[18:19], v[104:105] op_sel_hi:[1,0]
	v_pk_mul_f32 v[16:17], v[16:17], v[104:105] op_sel_hi:[1,0]
	v_pk_mul_f32 v[14:15], v[14:15], v[104:105] op_sel_hi:[1,0]
	v_pk_mul_f32 v[12:13], v[12:13], v[104:105] op_sel_hi:[1,0]
	v_pk_mul_f32 v[10:11], v[10:11], v[104:105] op_sel_hi:[1,0]
	v_pk_mul_f32 v[8:9], v[8:9], v[104:105] op_sel_hi:[1,0]
	v_pk_mul_f32 v[6:7], v[6:7], v[104:105] op_sel_hi:[1,0]
	v_pk_mul_f32 v[4:5], v[4:5], v[104:105] op_sel_hi:[1,0]
.LBB0_848:
	v_sub_f32_e32 v68, v68, v2
	v_sub_f32_e32 v69, v69, v2
	v_sub_f32_e32 v104, v52, v2
	v_sub_f32_e32 v105, v53, v2
	v_exp_f32_e32 v52, v68
	v_exp_f32_e32 v53, v69
	v_sub_f32_e32 v68, v70, v2
	v_sub_f32_e32 v69, v71, v2
	v_exp_f32_e32 v104, v104
	v_exp_f32_e32 v106, v68
	v_exp_f32_e32 v107, v69
	v_sub_f32_e32 v68, v72, v2
	v_sub_f32_e32 v69, v73, v2
	v_sub_f32_e32 v72, v76, v2
	v_sub_f32_e32 v73, v77, v2
	v_exp_f32_e32 v112, v68
	v_exp_f32_e32 v113, v69
	v_sub_f32_e32 v68, v74, v2
	v_sub_f32_e32 v69, v75, v2
	v_exp_f32_e32 v128, v72
	v_exp_f32_e32 v114, v68
	v_exp_f32_e32 v115, v69
	v_cvt_pk_bf16_f32 v68, v52, v53
	v_cvt_pk_bf16_f32 v69, v106, v107
	v_cvt_pk_bf16_f32 v70, v112, v113
	v_cvt_pk_bf16_f32 v71, v114, v115
	v_exp_f32_e32 v129, v73
	v_sub_f32_e32 v72, v78, v2
	v_sub_f32_e32 v73, v79, v2
	s_waitcnt lgkmcnt(5)
	v_mfma_f32_32x32x16_bf16 v[4:19], v[116:119], v[68:71], v[4:19]
	v_exp_f32_e32 v105, v105
	v_sub_f32_e32 v60, v60, v2
	v_sub_f32_e32 v61, v61, v2
	v_sub_f32_e32 v66, v66, v2
	v_sub_f32_e32 v67, v67, v2
	s_nop 0
	v_exp_f32_e32 v66, v66
	v_exp_f32_e32 v67, v67
	v_mfma_f32_32x32x16_bf16 v[20:35], v[120:123], v[68:71], v[20:35]
	v_exp_f32_e32 v120, v72
	v_exp_f32_e32 v121, v73
	v_sub_f32_e32 v72, v80, v2
	v_sub_f32_e32 v73, v81, v2
	v_sub_f32_e32 v68, v82, v2
	v_sub_f32_e32 v69, v83, v2
	v_exp_f32_e32 v122, v72
	v_exp_f32_e32 v123, v73
	v_exp_f32_e32 v116, v68
	v_exp_f32_e32 v117, v69
	v_cvt_pk_bf16_f32 v68, v128, v129
	v_cvt_pk_bf16_f32 v69, v120, v121
	v_cvt_pk_bf16_f32 v70, v122, v123
	v_cvt_pk_bf16_f32 v71, v116, v117
	s_waitcnt lgkmcnt(2)
	s_nop 0
	v_mfma_f32_32x32x16_bf16 v[4:19], v[44:47], v[68:71], v[4:19]
	v_add_f32_e64 v44, v58, -v2
	v_add_f32_e64 v45, v59, -v2
	v_exp_f32_e32 v58, v44
	v_exp_f32_e32 v59, v45
	v_cvt_pk_bf16_f32 v44, v104, v105
	v_cvt_pk_bf16_f32 v47, v58, v59
	v_mfma_f32_32x32x16_bf16 v[20:35], v[48:51], v[68:71], v[20:35]
	v_add_f32_e64 v48, v54, -v2
	v_add_f32_e64 v49, v55, -v2
	v_add_f32_e64 v50, v56, -v2
	v_add_f32_e64 v51, v57, -v2
	v_exp_f32_e32 v48, v48
	v_exp_f32_e32 v49, v49
	v_exp_f32_e32 v118, v50
	v_exp_f32_e32 v119, v51
	v_add_f32_e32 v58, v58, v114
	v_add_f32_e32 v59, v59, v115
	v_cvt_pk_bf16_f32 v45, v48, v49
	v_add_f32_e32 v130, v48, v106
	v_add_f32_e32 v131, v49, v107
	v_cvt_pk_bf16_f32 v46, v118, v119
	s_nop 1
	v_mfma_f32_32x32x16_bf16 v[4:19], v[36:39], v[44:47], v[4:19]
	ds_read_b128 v[36:39], v124 offset:27648
	ds_read_b128 v[54:57], v124 offset:27680
	s_waitcnt lgkmcnt(1)
	v_mfma_f32_32x32x16_bf16 v[68:83], v[36:39], v[96:99], 0
	ds_read_b128 v[36:39], v124 offset:32256
	v_mfma_f32_32x32x16_bf16 v[20:35], v[40:43], v[44:47], v[20:35]
	v_add_f32_e64 v40, v104, v52
	v_add_f32_e64 v41, v105, v53
	ds_read_b128 v[104:107], v124 offset:32288
	v_add_f32_e64 v52, v40, 0
	v_add_f32_e64 v53, v41, 0
	v_add_f32_e32 v52, v130, v52
	v_add_f32_e32 v53, v131, v53
	s_waitcnt lgkmcnt(1)
	v_mfma_f32_32x32x16_bf16 v[36:51], v[36:39], v[96:99], 0
	v_add_f32_e64 v96, v118, v112
	v_add_f32_e64 v97, v119, v113
	v_add_f32_e64 v52, v96, v52
	v_add_f32_e64 v53, v97, v53
	v_exp_f32_e32 v96, v60
	v_exp_f32_e32 v97, v61
	v_add_f32_e32 v52, v58, v52
	v_add_f32_e32 v53, v59, v53
	v_cvt_pk_bf16_f32 v114, v96, v97
	v_mfma_f32_32x32x16_bf16 v[68:83], v[54:57], v[92:95], v[68:83]
	v_add_f32_e64 v54, v96, v128
	v_add_f32_e64 v55, v97, v129
	v_add_f32_e64 v56, v62, -v2
	v_add_f32_e64 v57, v63, -v2
	v_add_f32_e64 v112, v54, v52
	v_add_f32_e64 v113, v55, v53
	ds_read_b128 v[52:55], v124 offset:27712
	v_exp_f32_e32 v98, v56
	v_exp_f32_e32 v99, v57
	v_sub_f32_e32 v56, v64, v2
	v_sub_f32_e32 v57, v65, v2
	s_waitcnt lgkmcnt(1)
	v_mfma_f32_32x32x16_bf16 v[36:51], v[104:107], v[92:95], v[36:51]
	v_exp_f32_e32 v64, v56
	v_exp_f32_e32 v65, v57
	ds_read_b128 v[56:59], v124 offset:32320
	ds_read_b128 v[60:63], v124 offset:27744
	v_add_f32_e32 v92, v98, v120
	v_add_f32_e32 v93, v99, v121
	v_add_f32_e32 v94, v66, v116
	v_add_f32_e32 v95, v67, v117
	v_cvt_pk_bf16_f32 v115, v98, v99
	v_cvt_pk_bf16_f32 v116, v64, v65
	s_waitcnt lgkmcnt(2)
	v_mfma_f32_32x32x16_bf16 v[68:83], v[52:55], v[88:91], v[68:83]
	v_add_f32_e64 v52, v92, v112
	v_add_f32_e64 v53, v93, v113
	v_add_f32_e64 v54, v64, v122
	v_add_f32_e64 v55, v65, v123
	v_cvt_pk_bf16_f32 v117, v66, v67
	v_add_f32_e32 v92, v54, v52
	v_add_f32_e32 v93, v55, v53
	ds_read_b128 v[52:55], v124 offset:32352
	s_waitcnt lgkmcnt(2)
	v_mfma_f32_32x32x16_bf16 v[36:51], v[56:59], v[88:91], v[36:51]
	v_add_f32_e64 v56, v94, v92
	v_add_f32_e64 v57, v95, v93
	v_add_f32_e32 v0, v56, v57
	v_add_f32_e32 v112, v127, v0
	s_waitcnt lgkmcnt(1)
	v_mfma_f32_32x32x16_bf16 v[68:83], v[60:63], v[84:87], v[68:83]
	ds_read2_b64 v[104:107], v125 offset0:48 offset1:50
	ds_read2_b64 v[92:95], v125 offset0:52 offset1:54
	ds_read2_b64 v[96:99], v126 offset0:80 offset1:82
	ds_read2_b64 v[64:67], v125 offset0:56 offset1:58
	ds_read2_b64 v[60:63], v126 offset0:88 offset1:90
	ds_read2_b64 v[88:91], v126 offset0:84 offset1:86
	ds_read2_b64 v[56:59], v125 offset0:60 offset1:62
	s_waitcnt lgkmcnt(7)
	v_mfma_f32_32x32x16_bf16 v[36:51], v[52:55], v[84:87], v[36:51]
	ds_read2_b64 v[52:55], v126 offset0:92 offset1:94
	v_mfma_f32_32x32x16_bf16 v[20:35], v[108:111], v[114:117], v[20:35]
	s_nop 9
	v_maximum3_f32 v0, v69, v37, v37
	v_maximum3_f32 v0, v68, v36, v0
	v_maximum3_f32 v1, v70, v38, v38
	v_maximum3_f32 v84, v71, v39, v39
	v_maximum3_f32 v0, v0, v1, v84
	v_maximum3_f32 v1, v72, v40, v40
	v_maximum3_f32 v84, v73, v41, v41
	v_maximum3_f32 v0, v0, v1, v84
	v_maximum3_f32 v1, v74, v42, v42
	v_maximum3_f32 v84, v75, v43, v43
	v_maximum3_f32 v0, v0, v1, v84
	v_maximum3_f32 v1, v76, v44, v44
	v_maximum3_f32 v84, v77, v45, v45
	v_maximum3_f32 v0, v0, v1, v84
	v_maximum3_f32 v1, v78, v46, v46
	v_maximum3_f32 v84, v79, v47, v47
	v_mfma_f32_32x32x16_bf16 v[4:19], v[100:103], v[114:117], v[4:19]
	v_maximum3_f32 v0, v0, v1, v84
	v_maximum3_f32 v1, v80, v48, v48
	v_maximum3_f32 v84, v81, v49, v49
	v_maximum3_f32 v0, v0, v1, v84
	v_maximum3_f32 v1, v82, v50, v50
	v_maximum3_f32 v84, v83, v51, v51
	v_maximum3_f32 v0, v0, v1, v84
	v_mov_b32_e32 v1, v0
	s_nop 1
	v_permlane32_swap_b32_e32 v0, v1
	s_nop 0
	v_maximum3_f32 v84, v0, v1, v1
	v_cmp_gt_f32_e32 vcc, v84, v135
	s_cbranch_vccz .LBB0_850
	v_maximum3_f32 v2, v135, v84, v84
	v_sub_f32_e32 v0, v135, v2
	v_exp_f32_e32 v84, v0
	s_nop 0
	v_mul_f32_e32 v112, v112, v84
	v_pk_mul_f32 v[34:35], v[34:35], v[84:85] op_sel_hi:[1,0]
	v_pk_mul_f32 v[32:33], v[32:33], v[84:85] op_sel_hi:[1,0]
	v_pk_mul_f32 v[30:31], v[30:31], v[84:85] op_sel_hi:[1,0]
	v_pk_mul_f32 v[28:29], v[28:29], v[84:85] op_sel_hi:[1,0]
	v_pk_mul_f32 v[26:27], v[26:27], v[84:85] op_sel_hi:[1,0]
	v_pk_mul_f32 v[24:25], v[24:25], v[84:85] op_sel_hi:[1,0]
	v_pk_mul_f32 v[22:23], v[22:23], v[84:85] op_sel_hi:[1,0]
	v_pk_mul_f32 v[20:21], v[20:21], v[84:85] op_sel_hi:[1,0]
	v_pk_mul_f32 v[18:19], v[18:19], v[84:85] op_sel_hi:[1,0]
	v_pk_mul_f32 v[16:17], v[16:17], v[84:85] op_sel_hi:[1,0]
	v_pk_mul_f32 v[14:15], v[14:15], v[84:85] op_sel_hi:[1,0]
	v_pk_mul_f32 v[12:13], v[12:13], v[84:85] op_sel_hi:[1,0]
	v_pk_mul_f32 v[10:11], v[10:11], v[84:85] op_sel_hi:[1,0]
	v_pk_mul_f32 v[8:9], v[8:9], v[84:85] op_sel_hi:[1,0]
	v_pk_mul_f32 v[6:7], v[6:7], v[84:85] op_sel_hi:[1,0]
	v_pk_mul_f32 v[4:5], v[4:5], v[84:85] op_sel_hi:[1,0]
.LBB0_850:
	v_sub_f32_e32 v68, v68, v2
	v_sub_f32_e32 v69, v69, v2
	v_sub_f32_e32 v36, v36, v2
	v_sub_f32_e32 v37, v37, v2
	v_exp_f32_e32 v68, v68
	v_exp_f32_e32 v69, v69
	v_exp_f32_e32 v84, v36
	v_exp_f32_e32 v85, v37
	v_sub_f32_e32 v36, v70, v2
	v_sub_f32_e32 v37, v71, v2
	v_sub_f32_e32 v38, v38, v2
	v_sub_f32_e32 v39, v39, v2
	v_exp_f32_e32 v70, v36
	v_exp_f32_e32 v71, v37
	v_exp_f32_e32 v86, v38
	v_exp_f32_e32 v87, v39
	v_sub_f32_e32 v72, v72, v2
	v_sub_f32_e32 v73, v73, v2
	v_sub_f32_e32 v40, v40, v2
	v_sub_f32_e32 v41, v41, v2
	v_exp_f32_e32 v72, v72
	v_exp_f32_e32 v73, v73
	v_exp_f32_e32 v40, v40
	v_exp_f32_e32 v41, v41
	v_sub_f32_e32 v74, v74, v2
	v_sub_f32_e32 v75, v75, v2
	v_add_f32_e32 v36, v84, v68
	v_add_f32_e32 v37, v85, v69
	v_exp_f32_e32 v74, v74
	v_exp_f32_e32 v75, v75
	v_pk_add_f32 v[36:37], v[36:37], 0 op_sel_hi:[1,0]
	v_add_f32_e32 v38, v86, v70
	v_add_f32_e32 v39, v87, v71
	v_sub_f32_e32 v42, v42, v2
	v_sub_f32_e32 v43, v43, v2
	v_add_f32_e32 v36, v38, v36
	v_add_f32_e32 v37, v39, v37
	v_add_f32_e32 v38, v40, v72
	v_add_f32_e32 v39, v41, v73
	v_exp_f32_e32 v42, v42
	v_add_f32_e32 v100, v38, v36
	v_add_f32_e32 v101, v39, v37
	v_sub_f32_e32 v36, v76, v2
	v_sub_f32_e32 v37, v77, v2
	v_cvt_pk_bf16_f32 v38, v72, v73
	v_exp_f32_e32 v76, v36
	v_exp_f32_e32 v77, v37
	v_cvt_pk_bf16_f32 v36, v68, v69
	v_cvt_pk_bf16_f32 v37, v70, v71
	v_cvt_pk_bf16_f32 v39, v74, v75
	v_sub_f32_e32 v68, v78, v2
	v_sub_f32_e32 v69, v79, v2
	v_sub_f32_e32 v70, v80, v2
	v_sub_f32_e32 v71, v81, v2
	s_waitcnt lgkmcnt(7)
	v_mfma_f32_32x32x16_bf16 v[20:35], v[104:107], v[36:39], v[20:35]
	v_exp_f32_e32 v68, v68
	v_exp_f32_e32 v69, v69
	v_exp_f32_e32 v70, v70
	v_exp_f32_e32 v71, v71
	v_exp_f32_e32 v43, v43
	v_sub_f32_e32 v44, v44, v2
	v_sub_f32_e32 v45, v45, v2
	v_sub_f32_e32 v46, v46, v2
	v_sub_f32_e32 v47, v47, v2
	s_waitcnt lgkmcnt(5)
	v_mfma_f32_32x32x16_bf16 v[4:19], v[96:99], v[36:39], v[4:19]
	v_add_f32_e64 v36, v82, -v2
	v_add_f32_e64 v37, v83, -v2
	v_cvt_pk_bf16_f32 v38, v70, v71
	v_exp_f32_e32 v72, v36
	v_exp_f32_e32 v73, v37
	v_cvt_pk_bf16_f32 v36, v76, v77
	v_cvt_pk_bf16_f32 v37, v68, v69
	v_exp_f32_e32 v44, v44
	v_cvt_pk_bf16_f32 v39, v72, v73
	v_exp_f32_e32 v45, v45
	v_exp_f32_e32 v46, v46
	v_mfma_f32_32x32x16_bf16 v[20:35], v[92:95], v[36:39], v[20:35]
	v_exp_f32_e32 v47, v47
	v_add_f32_e32 v102, v42, v74
	v_add_f32_e32 v103, v43, v75
	v_add_f32_e32 v76, v44, v76
	v_add_f32_e32 v77, v45, v77
	v_add_f32_e32 v74, v102, v100
	v_add_f32_e32 v75, v103, v101
	v_add_f32_e32 v68, v46, v68
	v_add_f32_e32 v69, v47, v69
	v_add_f32_e32 v74, v76, v74
	v_add_f32_e32 v75, v77, v75
	v_lshlrev_b32_e32 v1, 2, v155
	s_waitcnt lgkmcnt(2)
	v_mfma_f32_32x32x16_bf16 v[4:19], v[88:91], v[36:39], v[4:19]
	v_add_f32_e64 v36, v48, -v2
	v_add_f32_e64 v37, v49, -v2
	v_cvt_pk_bf16_f32 v38, v40, v41
	v_exp_f32_e32 v48, v36
	v_exp_f32_e32 v49, v37
	v_sub_f32_e32 v40, v50, v2
	v_sub_f32_e32 v41, v51, v2
	v_cvt_pk_bf16_f32 v39, v42, v43
	v_exp_f32_e32 v40, v40
	v_exp_f32_e32 v41, v41
	v_add_f32_e32 v42, v68, v74
	v_add_f32_e32 v43, v69, v75
	v_add_f32_e32 v50, v48, v70
	v_add_f32_e32 v51, v49, v71
	v_cvt_pk_bf16_f32 v36, v84, v85
	v_cvt_pk_bf16_f32 v37, v86, v87
	v_add_f32_e32 v42, v50, v42
	v_add_f32_e32 v43, v51, v43
	v_add_f32_e32 v50, v40, v72
	v_add_f32_e32 v51, v41, v73
	v_mfma_f32_32x32x16_bf16 v[20:35], v[64:67], v[36:39], v[20:35]
	v_xor_b32_e32 v1, 0x80, v1
	s_lshl_b32 s7, s90, 1
	v_mfma_f32_32x32x16_bf16 v[4:19], v[60:63], v[36:39], v[4:19]
	v_add_f32_e64 v36, v50, v42
	v_add_f32_e64 v37, v51, v43
	v_cvt_pk_bf16_f32 v38, v48, v49
	v_add_f32_e32 v0, v36, v37
	v_add_f32_e32 v0, v112, v0
	ds_bpermute_b32 v1, v1, v0
	v_cvt_pk_bf16_f32 v36, v44, v45
	v_cvt_pk_bf16_f32 v37, v46, v47
	v_cvt_pk_bf16_f32 v39, v40, v41
	s_waitcnt lgkmcnt(0)
	v_add_f32_e32 v0, v0, v1
	v_div_scale_f32 v1, s[4:5], v0, v0, 1.0
	v_rcp_f32_e32 v2, v1
	v_mfma_f32_32x32x16_bf16 v[20:35], v[56:59], v[36:39], v[20:35]
	s_mov_b64 s[4:5], 0xd000400
	v_mfma_f32_32x32x16_bf16 v[4:19], v[52:55], v[36:39], v[4:19]
	v_fma_f32 v36, -v1, v2, 1.0
	v_fmac_f32_e32 v2, v36, v2
	v_div_scale_f32 v36, vcc, 1.0, v0, 1.0
	v_mul_f32_e32 v37, v36, v2
	v_fma_f32 v38, -v1, v37, v36
	v_fmac_f32_e32 v37, v38, v2
	v_fma_f32 v1, -v1, v37, v36
	v_lshlrev_b64 v[38:39], 12, v[132:133]
	v_div_fmas_f32 v1, v1, v2, v37
	v_lshl_add_u64 v[38:39], s[10:11], 0, v[38:39]
	v_div_fixup_f32 v36, v1, v0, 1.0
	v_lshl_add_u64 v[38:39], v[38:39], 0, s[20:21]
	v_lshlrev_b32_e32 v2, 1, v137
	v_lshl_add_u64 v[38:39], v[38:39], 0, v[2:3]
	v_pk_mul_f32 v[20:21], v[20:21], v[36:37] op_sel_hi:[1,0]
	v_pk_mul_f32 v[22:23], v[22:23], v[36:37] op_sel_hi:[1,0]
	v_pk_mul_f32 v[6:7], v[6:7], v[36:37] op_sel_hi:[1,0]
	v_lshl_add_u64 v[40:41], v[38:39], 0, s[4:5]
	v_pk_mul_f32 v[42:43], v[4:5], v[36:37] op_sel_hi:[1,0]
	v_cvt_pk_bf16_f32 v4, v20, v21
	v_cvt_pk_bf16_f32 v5, v22, v23
	v_cvt_pk_bf16_f32 v21, v6, v7
	v_pk_mul_f32 v[6:7], v[24:25], v[36:37] op_sel_hi:[1,0]
	v_pk_mul_f32 v[22:23], v[26:27], v[36:37] op_sel_hi:[1,0]
	v_pk_mul_f32 v[8:9], v[8:9], v[36:37] op_sel_hi:[1,0]
	s_mov_b32 s4, 0xd000000
	v_cvt_pk_bf16_f32 v6, v6, v7
	v_cvt_pk_bf16_f32 v7, v22, v23
	v_cvt_pk_bf16_f32 v22, v8, v9
	v_add_co_u32_e32 v8, vcc, s4, v38
	s_and_b32 s4, s36, 0xffffffe0
	v_pk_mul_f32 v[10:11], v[10:11], v[36:37] op_sel_hi:[1,0]
	v_permlane32_swap_b32_e32 v4, v6
	v_permlane32_swap_b32_e32 v5, v7
	v_addc_co_u32_e32 v9, vcc, 0, v39, vcc
	s_add_i32 s6, s7, s4
	s_add_i32 s7, s7, s75
	v_readlane_b32 s4, v254, 58
	v_cvt_pk_bf16_f32 v23, v10, v11
	global_store_dwordx4 v[8:9], v[4:7], off offset:1024
	v_pk_mul_f32 v[8:9], v[12:13], v[36:37] op_sel_hi:[1,0]
	v_pk_mul_f32 v[10:11], v[14:15], v[36:37] op_sel_hi:[1,0]
	v_pk_mul_f32 v[4:5], v[28:29], v[36:37] op_sel_hi:[1,0]
	v_pk_mul_f32 v[6:7], v[30:31], v[36:37] op_sel_hi:[1,0]
	s_sub_i32 s8, s6, 32
	s_add_i32 s9, s7, 0x50
	v_readlane_b32 s5, v254, 59
	v_cvt_pk_bf16_f32 v4, v4, v5
	v_cvt_pk_bf16_f32 v5, v6, v7
	v_cvt_pk_bf16_f32 v8, v8, v9
	v_cvt_pk_bf16_f32 v9, v10, v11
	v_pk_mul_f32 v[6:7], v[32:33], v[36:37] op_sel_hi:[1,0]
	v_pk_mul_f32 v[10:11], v[34:35], v[36:37] op_sel_hi:[1,0]
	v_pk_mul_f32 v[12:13], v[16:17], v[36:37] op_sel_hi:[1,0]
	v_pk_mul_f32 v[14:15], v[18:19], v[36:37] op_sel_hi:[1,0]
	s_and_b64 s[4:5], s[4:5], exec
	v_cvt_pk_bf16_f32 v20, v42, v43
	v_cvt_pk_bf16_f32 v6, v6, v7
	v_cvt_pk_bf16_f32 v7, v10, v11
	v_cvt_pk_bf16_f32 v10, v12, v13
	v_cvt_pk_bf16_f32 v11, v14, v15
	s_cselect_b32 s38, s8, s9
	v_permlane32_swap_b32_e32 v20, v22
	v_permlane32_swap_b32_e32 v21, v23
	v_permlane32_swap_b32_e32 v4, v6
	v_permlane32_swap_b32_e32 v5, v7
	v_permlane32_swap_b32_e32 v8, v10
	v_permlane32_swap_b32_e32 v9, v11
	s_cmpk_gt_i32 s38, 0x7f
	s_mov_b64 s[4:5], -1
	global_store_dwordx4 v[40:41], v[20:23], off offset:64
	global_store_dwordx4 v[40:41], v[4:7], off offset:32
	global_store_dwordx4 v[40:41], v[8:11], off offset:96
	s_cbranch_scc0 .LBB0_870
	s_mov_b64 s[4:5], s[0:1]
	v_mov_b32_e32 v128, v202
	s_add_i32 s8, s38, 0xffffff80
	s_lshl_b32 s5, s8, 5
	v_readfirstlane_b32 s4, v128
	s_ashr_i32 s4, s4, 1
	v_lshlrev_b32_e32 v1, 4, v128
	s_and_b32 s20, s5, 0x7fffff00
	s_andn2_b32 s4, s4, 31
	v_and_b32_e32 v2, 0x70, v1
	v_add_u32_e32 v1, 0x200, v128
	v_and_b32_e32 v52, 31, v128
	s_add_i32 s4, s4, s20
	v_ashrrev_i32_e32 v42, 3, v1
	v_or_b32_e32 v124, s4, v52
	s_lshl_b64 s[4:5], s[20:21], 10
	v_min_i32_e32 v1, 0xff, v42
	s_add_u32 s9, s17, s4
	v_ashrrev_i32_e32 v4, 31, v1
	s_addc_u32 s5, s74, s5
	s_lshl_b32 s4, s8, 6
	v_add_u32_sdwa v4, v1, v4 dst_sel:DWORD dst_unused:UNUSED_PAD src0_sel:DWORD src1_sel:BYTE_3
	s_and_b32 s8, s4, 0x1c0
	v_and_b32_e32 v4, 0xffffff00, v4
	s_lshl_b32 s20, s8, 1
	v_sub_u32_e32 v4, v1, v4
	v_add_u32_e32 v1, 0x400, v128
	s_add_u32 s8, s9, s20
	v_ashrrev_i32_e32 v40, 3, v1
	s_addc_u32 s9, s5, 0
	v_min_i32_e32 v1, 0xff, v40
	s_mov_b32 s5, s21
	v_ashrrev_i32_e32 v6, 31, v1
	s_lshl_b64 s[4:5], s[4:5], 9
	v_ashrrev_i32_e32 v16, 4, v128
	v_add_u32_sdwa v6, v1, v6 dst_sel:DWORD dst_unused:UNUSED_PAD src0_sel:DWORD src1_sel:BYTE_3
	s_add_u32 s4, s10, s4
	v_ashrrev_i32_e32 v17, 31, v16
	v_lshlrev_b32_e32 v0, 3, v128
	v_and_b32_e32 v6, 0xffffff00, v6
	s_addc_u32 s5, s11, s5
	v_lshlrev_b64 v[14:15], 9, v[16:17]
	v_sub_u32_e32 v6, v1, v6
	v_add_u32_e32 v1, 0x600, v128
	v_lshl_add_u64 v[14:15], s[4:5], 0, v[14:15]
	v_and_b32_e32 v20, 0x78, v0
	v_mov_b32_e32 v21, v3
	v_ashrrev_i32_e32 v41, 3, v1
	v_lshl_add_u64 v[32:33], v[14:15], 0, v[20:21]
	s_mov_b64 s[4:5], 0x7c00000
	v_min_i32_e32 v1, 0xff, v41
	v_lshl_add_u64 v[30:31], v[32:33], 0, s[4:5]
	s_mov_b32 s4, 0x7c00000
	v_ashrrev_i32_e32 v12, 31, v1
	v_add_co_u32_e32 v24, vcc, s4, v32
	s_mov_b64 s[4:5], 0x7c04000
	v_add_u32_sdwa v12, v1, v12 dst_sel:DWORD dst_unused:UNUSED_PAD src0_sel:DWORD src1_sel:BYTE_3
	v_addc_co_u32_e32 v25, vcc, 0, v33, vcc
	v_lshl_add_u64 v[36:37], v[32:33], 0, s[4:5]
	s_mov_b32 s4, 0x7c04000
	v_and_b32_e32 v12, 0xffffff00, v12
	v_add_co_u32_e32 v32, vcc, s4, v32
	v_ashrrev_i32_e32 v125, 31, v124
	v_readlane_b32 s4, v255, 0
	v_sub_u32_e32 v12, v1, v12
	v_lshlrev_b64 v[38:39], 10, v[124:125]
	v_readlane_b32 s5, v255, 1
	v_bfe_u32 v53, v128, 5, 1
	v_ashrrev_i32_e32 v5, 31, v4
	v_ashrrev_i32_e32 v7, 31, v6
	v_ashrrev_i32_e32 v13, 31, v12
	v_lshl_add_u64 v[38:39], s[4:5], 0, v[38:39]
	v_lshl_add_u64 v[18:19], s[8:9], 0, v[2:3]
	v_lshlrev_b64 v[4:5], 10, v[4:5]
	v_lshlrev_b64 v[6:7], 10, v[6:7]
	v_lshlrev_b64 v[12:13], 10, v[12:13]
	v_lshl_add_u64 v[44:45], v[38:39], 0, s[20:21]
	v_lshlrev_b32_e32 v38, 4, v53
	v_mov_b32_e32 v39, v3
	v_lshl_add_u64 v[4:5], v[18:19], 0, v[4:5]
	v_lshl_add_u64 v[6:7], v[18:19], 0, v[6:7]
	v_lshl_add_u64 v[12:13], v[18:19], 0, v[12:13]
	v_addc_co_u32_e32 v33, vcc, 0, v33, vcc
	v_lshl_add_u64 v[44:45], v[44:45], 0, v[38:39]
	s_barrier
	global_load_dwordx4 v[8:11], v[4:5], off
	s_nop 0
	global_load_dwordx4 v[4:7], v[6:7], off
	s_nop 0
	global_load_dwordx4 v[12:15], v[12:13], off
	s_nop 0
	global_load_dwordx2 v[22:23], v[30:31], off offset:128
	s_nop 0
	global_load_dwordx2 v[24:25], v[24:25], off
	s_nop 0
	global_load_dwordx2 v[26:27], v[30:31], off offset:256
	global_load_dwordx2 v[28:29], v[36:37], off offset:128
	s_nop 0
	global_load_dwordx2 v[30:31], v[30:31], off offset:384
	s_nop 0
	global_load_dwordx2 v[32:33], v[32:33], off
	s_nop 0
	global_load_dwordx2 v[34:35], v[36:37], off offset:256
	s_nop 0
	global_load_dwordx2 v[36:37], v[36:37], off offset:384
	s_nop 0
	global_load_dwordx4 v[96:99], v[44:45], off
	global_load_dwordx4 v[92:95], v[44:45], off offset:32
	global_load_dwordx4 v[88:91], v[44:45], off offset:64
	global_load_dwordx4 v[84:87], v[44:45], off offset:96
	v_ashrrev_i32_e32 v17, 3, v128
	s_movk_i32 s4, 0x100
	v_add_u32_e32 v2, 0, v2
	v_cmp_gt_i32_e32 vcc, s4, v17
	s_and_saveexec_b64 s[4:5], vcc
	s_cbranch_execz .LBB0_853
	v_ashrrev_i32_e32 v0, 31, v17
	v_add_u32_sdwa v0, v17, v0 dst_sel:DWORD dst_unused:UNUSED_PAD src0_sel:DWORD src1_sel:BYTE_3
	v_and_b32_e32 v0, 0xffffff00, v0
	v_sub_u32_e32 v44, v17, v0
	v_ashrrev_i32_e32 v45, 31, v44
	v_lshlrev_b64 v[44:45], 10, v[44:45]
	v_lshl_add_u64 v[18:19], v[18:19], 0, v[44:45]
	global_load_dwordx4 v[44:47], v[18:19], off
	s_movk_i32 s8, 0x90
	v_mad_u64_u32 v[18:19], s[8:9], v17, s8, v[2:3]
	s_waitcnt vmcnt(0)
	ds_write_b128 v18, v[44:47]

.LBB0_862:
	v_mov_b32_e32 v127, v126
	v_sub_f32_e32 v20, v20, v126
	v_sub_f32_e32 v21, v21, v127
	v_sub_f32_e32 v36, v36, v126
	v_sub_f32_e32 v37, v37, v127
	v_exp_f32_e32 v20, v20
	v_exp_f32_e32 v21, v21
	v_exp_f32_e32 v100, v36
	v_exp_f32_e32 v101, v37
	v_sub_f32_e32 v22, v22, v126
	v_sub_f32_e32 v23, v23, v127
	v_sub_f32_e32 v36, v38, v126
	v_sub_f32_e32 v37, v39, v127
	v_exp_f32_e32 v22, v22
	v_exp_f32_e32 v23, v23
	v_exp_f32_e32 v102, v36
	v_exp_f32_e32 v103, v37
	v_sub_f32_e32 v24, v24, v126
	v_sub_f32_e32 v25, v25, v127
	v_sub_f32_e32 v40, v40, v126
	v_sub_f32_e32 v41, v41, v127
	v_exp_f32_e32 v24, v24
	v_exp_f32_e32 v25, v25
	v_exp_f32_e32 v40, v40
	v_exp_f32_e32 v41, v41
	v_sub_f32_e32 v26, v26, v126
	v_sub_f32_e32 v27, v27, v127
	v_sub_f32_e32 v42, v42, v126
	v_sub_f32_e32 v43, v43, v127
	v_exp_f32_e32 v26, v26
	v_exp_f32_e32 v27, v27
	v_exp_f32_e32 v42, v42
	v_exp_f32_e32 v43, v43
	v_sub_f32_e32 v28, v28, v126
	v_sub_f32_e32 v29, v29, v127
	v_sub_f32_e32 v44, v44, v126
	v_sub_f32_e32 v45, v45, v127
	v_add_f32_e32 v36, v100, v20
	v_add_f32_e32 v37, v101, v21
	v_exp_f32_e32 v104, v28
	v_exp_f32_e32 v105, v29
	v_exp_f32_e32 v44, v44
	v_exp_f32_e32 v45, v45
	v_pk_add_f32 v[36:37], v[36:37], 0 op_sel_hi:[1,0]
	v_add_f32_e32 v38, v102, v22
	v_add_f32_e32 v39, v103, v23
	v_sub_f32_e32 v28, v30, v126
	v_sub_f32_e32 v29, v31, v127
	v_add_f32_e32 v36, v38, v36
	v_add_f32_e32 v37, v39, v37
	v_add_f32_e32 v38, v40, v24
	v_add_f32_e32 v39, v41, v25
	v_sub_f32_e32 v30, v46, v126
	v_sub_f32_e32 v31, v47, v127
	v_add_f32_e32 v36, v38, v36
	v_add_f32_e32 v37, v39, v37
	v_add_f32_e32 v38, v42, v26
	v_add_f32_e32 v39, v43, v27
	v_exp_f32_e32 v46, v28
	v_exp_f32_e32 v47, v29
	v_exp_f32_e32 v106, v30
	v_exp_f32_e32 v107, v31
	v_add_f32_e32 v28, v38, v36
	v_add_f32_e32 v29, v39, v37
	v_add_f32_e32 v30, v44, v104
	v_add_f32_e32 v31, v45, v105
	v_mov_b32_e32 v5, v4
	v_add_f32_e32 v108, v30, v28
	v_add_f32_e32 v109, v31, v29
	v_sub_f32_e32 v28, v32, v126
	v_sub_f32_e32 v29, v33, v127
	v_sub_f32_e32 v30, v48, v126
	v_sub_f32_e32 v31, v49, v127
	v_exp_f32_e32 v48, v28
	v_exp_f32_e32 v49, v29
	v_exp_f32_e32 v112, v30
	v_exp_f32_e32 v113, v31
	v_sub_f32_e32 v28, v34, v126
	v_sub_f32_e32 v29, v35, v127
	v_sub_f32_e32 v30, v50, v126
	v_sub_f32_e32 v31, v51, v127
	v_exp_f32_e32 v50, v28
	v_exp_f32_e32 v51, v29
	v_exp_f32_e32 v114, v30
	v_exp_f32_e32 v115, v31
	v_mov_b32_e32 v6, v4
	v_mov_b32_e32 v7, v4
	v_mov_b32_e32 v8, v4
	v_mov_b32_e32 v9, v4
	v_mov_b32_e32 v10, v4
	v_mov_b32_e32 v11, v4
	v_mov_b32_e32 v12, v4
	v_mov_b32_e32 v13, v4
	v_mov_b32_e32 v14, v4
	v_mov_b32_e32 v15, v4
	v_mov_b32_e32 v16, v4
	v_mov_b32_e32 v17, v4
	v_mov_b32_e32 v18, v4
	v_mov_b32_e32 v19, v4
	v_add_f32_e32 v110, v106, v46
	v_add_f32_e32 v111, v107, v47
	v_cvt_pk_bf16_f32 v36, v20, v21
	v_cvt_pk_bf16_f32 v37, v22, v23
	v_cvt_pk_bf16_f32 v38, v24, v25
	v_cvt_pk_bf16_f32 v39, v26, v27
	s_waitcnt lgkmcnt(7)
	s_nop 0
	v_mfma_f32_32x32x16_bf16 v[20:35], v[80:83], v[36:39], v[4:19]
	v_add_f32_e64 v80, v110, v108
	v_add_f32_e64 v81, v111, v109
	v_add_f32_e64 v82, v112, v48
	v_add_f32_e64 v83, v113, v49
	v_add_f32_e64 v80, v82, v80
	v_add_f32_e64 v81, v83, v81
	v_add_f32_e32 v82, v114, v50
	v_add_f32_e32 v83, v115, v51
	s_nop 0
	v_add_f32_e32 v80, v82, v80
	v_add_f32_e32 v81, v83, v81
	s_nop 0
	v_add_f32_e32 v0, v80, v81
	v_add_f32_e32 v117, v4, v0
	s_waitcnt lgkmcnt(5)
	v_mfma_f32_32x32x16_bf16 v[4:19], v[76:79], v[36:39], v[4:19]
	v_cvt_pk_bf16_f32 v36, v104, v105
	v_cvt_pk_bf16_f32 v37, v46, v47
	v_cvt_pk_bf16_f32 v38, v48, v49
	v_cvt_pk_bf16_f32 v39, v50, v51
	s_nop 1
	v_mfma_f32_32x32x16_bf16 v[20:35], v[68:71], v[36:39], v[20:35]
	s_waitcnt lgkmcnt(2)
	v_mfma_f32_32x32x16_bf16 v[4:19], v[72:75], v[36:39], v[4:19]
	v_cvt_pk_bf16_f32 v36, v100, v101
	v_cvt_pk_bf16_f32 v37, v102, v103
	v_cvt_pk_bf16_f32 v38, v40, v41
	v_cvt_pk_bf16_f32 v39, v42, v43
	s_nop 1
	v_mfma_f32_32x32x16_bf16 v[20:35], v[64:67], v[36:39], v[20:35]
	v_mfma_f32_32x32x16_bf16 v[4:19], v[60:63], v[36:39], v[4:19]
	v_cvt_pk_bf16_f32 v36, v44, v45
	v_cvt_pk_bf16_f32 v37, v106, v107
	v_cvt_pk_bf16_f32 v38, v112, v113
	v_cvt_pk_bf16_f32 v39, v114, v115
	s_waitcnt lgkmcnt(1)
	s_nop 0
	v_mfma_f32_32x32x16_bf16 v[20:35], v[56:59], v[36:39], v[20:35]
	s_waitcnt lgkmcnt(0)
	v_mfma_f32_32x32x16_bf16 v[4:19], v[52:55], v[36:39], v[4:19]
	ds_read_b128 v[36:39], v130 offset:9216
	ds_read_b128 v[40:43], v130 offset:9248
	s_waitcnt lgkmcnt(1)
	v_mfma_f32_32x32x16_bf16 v[60:75], v[36:39], v[96:99], 0
	ds_read_b128 v[36:39], v130 offset:13824
	ds_read_b128 v[76:79], v130 offset:13856
	s_waitcnt lgkmcnt(1)
	v_mfma_f32_32x32x16_bf16 v[44:59], v[36:39], v[96:99], 0
	v_mfma_f32_32x32x16_bf16 v[60:75], v[40:43], v[92:95], v[60:75]
	ds_read_b128 v[36:39], v130 offset:9280
	ds_read_b128 v[40:43], v130 offset:9312
	s_waitcnt lgkmcnt(2)
	v_mfma_f32_32x32x16_bf16 v[44:59], v[76:79], v[92:95], v[44:59]
	s_waitcnt lgkmcnt(1)
	v_mfma_f32_32x32x16_bf16 v[60:75], v[36:39], v[88:91], v[60:75]
	ds_read_b128 v[36:39], v130 offset:13888
	ds_read_b128 v[118:121], v130 offset:13920
	ds_read2_b64 v[112:115], v131 offset0:16 offset1:18
	s_waitcnt lgkmcnt(2)
	v_mfma_f32_32x32x16_bf16 v[44:59], v[36:39], v[88:91], v[44:59]
	v_mfma_f32_32x32x16_bf16 v[60:75], v[40:43], v[84:87], v[60:75]
	ds_read2_b64 v[104:107], v131 offset0:20 offset1:22
	ds_read2_b64 v[108:111], v132 offset0:48 offset1:50
	ds_read2_b64 v[40:43], v131 offset0:24 offset1:26
	ds_read2_b64 v[36:39], v132 offset0:56 offset1:58
	ds_read2_b64 v[100:103], v132 offset0:52 offset1:54
	ds_read2_b64 v[80:83], v131 offset0:28 offset1:30
	ds_read2_b64 v[76:79], v132 offset0:60 offset1:62
	s_waitcnt lgkmcnt(8)
	v_mfma_f32_32x32x16_bf16 v[44:59], v[118:121], v[84:87], v[44:59]
	s_nop 11
	v_maximum3_f32 v0, v61, v45, v45
	v_maximum3_f32 v0, v60, v44, v0
	v_maximum3_f32 v1, v62, v46, v46
	v_maximum3_f32 v2, v63, v47, v47
	v_maximum3_f32 v0, v0, v1, v2
	v_maximum3_f32 v1, v64, v48, v48
	v_maximum3_f32 v2, v65, v49, v49
	v_maximum3_f32 v0, v0, v1, v2
	v_maximum3_f32 v1, v66, v50, v50
	v_maximum3_f32 v2, v67, v51, v51
	v_maximum3_f32 v0, v0, v1, v2
	v_maximum3_f32 v1, v68, v52, v52
	v_maximum3_f32 v2, v69, v53, v53
	v_maximum3_f32 v0, v0, v1, v2
	v_maximum3_f32 v1, v70, v54, v54
	v_maximum3_f32 v2, v71, v55, v55
	v_maximum3_f32 v0, v0, v1, v2
	v_maximum3_f32 v1, v72, v56, v56
	v_maximum3_f32 v2, v73, v57, v57
	v_maximum3_f32 v0, v0, v1, v2
	v_maximum3_f32 v1, v74, v58, v58
	v_maximum3_f32 v2, v75, v59, v59
	v_maximum3_f32 v0, v0, v1, v2
	v_mov_b32_e32 v1, v0
	s_nop 1
	v_permlane32_swap_b32_e32 v0, v1
	s_nop 0
	v_maximum3_f32 v2, v0, v1, v1
	v_cmp_gt_f32_e32 vcc, v2, v126
	s_cbranch_vccz .LBB0_864
	v_maximum3_f32 v2, v126, v2, v2
	v_sub_f32_e32 v0, v126, v2
	v_exp_f32_e32 v116, v0
	v_mov_b32_e32 v126, v2
	v_mul_f32_e32 v117, v117, v116
	v_pk_mul_f32 v[34:35], v[34:35], v[116:117] op_sel_hi:[1,0]
	v_pk_mul_f32 v[32:33], v[32:33], v[116:117] op_sel_hi:[1,0]
	v_pk_mul_f32 v[30:31], v[30:31], v[116:117] op_sel_hi:[1,0]
	v_pk_mul_f32 v[28:29], v[28:29], v[116:117] op_sel_hi:[1,0]
	v_pk_mul_f32 v[26:27], v[26:27], v[116:117] op_sel_hi:[1,0]
	v_pk_mul_f32 v[24:25], v[24:25], v[116:117] op_sel_hi:[1,0]
	v_pk_mul_f32 v[22:23], v[22:23], v[116:117] op_sel_hi:[1,0]
	v_pk_mul_f32 v[20:21], v[20:21], v[116:117] op_sel_hi:[1,0]
	v_pk_mul_f32 v[18:19], v[18:19], v[116:117] op_sel_hi:[1,0]
	v_pk_mul_f32 v[16:17], v[16:17], v[116:117] op_sel_hi:[1,0]
	v_pk_mul_f32 v[14:15], v[14:15], v[116:117] op_sel_hi:[1,0]
	v_pk_mul_f32 v[12:13], v[12:13], v[116:117] op_sel_hi:[1,0]
	v_pk_mul_f32 v[10:11], v[10:11], v[116:117] op_sel_hi:[1,0]
	v_pk_mul_f32 v[8:9], v[8:9], v[116:117] op_sel_hi:[1,0]
	v_pk_mul_f32 v[6:7], v[6:7], v[116:117] op_sel_hi:[1,0]
	v_pk_mul_f32 v[4:5], v[4:5], v[116:117] op_sel_hi:[1,0]
	v_mov_b32_e32 v116, v2
	s_branch .LBB0_865

.LBB0_865:
	v_sub_f32_e32 v60, v60, v116
	v_sub_f32_e32 v61, v61, v116
	v_sub_f32_e32 v118, v44, v116
	v_sub_f32_e32 v119, v45, v116
	v_exp_f32_e32 v44, v60
	v_exp_f32_e32 v45, v61
	v_sub_f32_e32 v60, v62, v116
	v_sub_f32_e32 v61, v63, v116
	v_sub_f32_e32 v46, v46, v116
	v_sub_f32_e32 v47, v47, v116
	v_exp_f32_e32 v120, v60
	v_exp_f32_e32 v121, v61
	v_sub_f32_e32 v60, v64, v116
	v_sub_f32_e32 v61, v65, v116
	v_sub_f32_e32 v64, v68, v116
	v_sub_f32_e32 v65, v69, v116
	v_exp_f32_e32 v122, v60
	v_exp_f32_e32 v123, v61
	v_sub_f32_e32 v60, v66, v116
	v_sub_f32_e32 v61, v67, v116
	v_exp_f32_e32 v136, v64
	v_exp_f32_e32 v134, v60
	v_exp_f32_e32 v135, v61
	v_cvt_pk_bf16_f32 v60, v44, v45
	v_cvt_pk_bf16_f32 v61, v120, v121
	v_cvt_pk_bf16_f32 v62, v122, v123
	v_cvt_pk_bf16_f32 v63, v134, v135
	v_exp_f32_e32 v137, v65
	v_sub_f32_e32 v64, v70, v116
	v_sub_f32_e32 v65, v71, v116
	s_waitcnt lgkmcnt(5)
	v_mfma_f32_32x32x16_bf16 v[4:19], v[108:111], v[60:63], v[4:19]
	v_exp_f32_e32 v118, v118
	v_exp_f32_e32 v119, v119
	v_sub_f32_e32 v52, v52, v116
	v_sub_f32_e32 v53, v53, v116
	v_sub_f32_e32 v54, v54, v116
	v_sub_f32_e32 v55, v55, v116
	v_sub_f32_e32 v56, v56, v116
	v_sub_f32_e32 v57, v57, v116
	v_mfma_f32_32x32x16_bf16 v[20:35], v[112:115], v[60:63], v[20:35]
	v_exp_f32_e32 v112, v64
	v_exp_f32_e32 v113, v65
	v_sub_f32_e32 v64, v72, v116
	v_sub_f32_e32 v65, v73, v116
	v_sub_f32_e32 v60, v74, v116
	v_sub_f32_e32 v61, v75, v116
	v_exp_f32_e32 v114, v64
	v_exp_f32_e32 v115, v65
	v_exp_f32_e32 v108, v60
	v_exp_f32_e32 v109, v61
	v_cvt_pk_bf16_f32 v60, v136, v137
	v_cvt_pk_bf16_f32 v61, v112, v113
	v_cvt_pk_bf16_f32 v62, v114, v115
	v_cvt_pk_bf16_f32 v63, v108, v109
	s_waitcnt lgkmcnt(2)
	s_nop 0
	v_mfma_f32_32x32x16_bf16 v[4:19], v[100:103], v[60:63], v[4:19]
	v_mfma_f32_32x32x16_bf16 v[20:35], v[104:107], v[60:63], v[20:35]
	v_exp_f32_e32 v104, v46
	v_exp_f32_e32 v105, v47
	v_sub_f32_e32 v46, v48, v116
	v_sub_f32_e32 v47, v49, v116
	v_add_f32_e32 v120, v104, v120
	v_add_f32_e32 v121, v105, v121
	v_exp_f32_e32 v110, v46
	v_exp_f32_e32 v111, v47
	v_sub_f32_e32 v46, v50, v116
	v_sub_f32_e32 v47, v51, v116
	v_cvt_pk_bf16_f32 v48, v110, v111
	v_exp_f32_e32 v138, v46
	v_exp_f32_e32 v139, v47
	v_cvt_pk_bf16_f32 v46, v118, v119
	v_cvt_pk_bf16_f32 v47, v104, v105
	v_add_f32_e32 v110, v110, v122
	v_add_f32_e32 v111, v111, v123
	v_cvt_pk_bf16_f32 v49, v138, v139
	s_nop 1
	v_mfma_f32_32x32x16_bf16 v[4:19], v[36:39], v[46:49], v[4:19]
	ds_read_b128 v[36:39], v130 offset:18432
	ds_read_b128 v[100:103], v130 offset:18464
	ds_read_b128 v[104:107], v130 offset:23072
	s_waitcnt lgkmcnt(2)
	v_mfma_f32_32x32x16_bf16 v[60:75], v[36:39], v[96:99], 0
	ds_read_b128 v[36:39], v130 offset:23040
	v_mfma_f32_32x32x16_bf16 v[20:35], v[40:43], v[46:49], v[20:35]
	v_add_f32_e64 v40, v118, v44
	v_add_f32_e64 v41, v119, v45
	v_add_f32_e64 v118, v40, 0
	v_add_f32_e64 v119, v41, 0
	v_add_f32_e64 v118, v120, v118
	v_add_f32_e64 v119, v121, v119
	v_add_f32_e32 v110, v110, v118
	v_add_f32_e32 v111, v111, v119
	v_exp_f32_e32 v118, v52
	v_exp_f32_e32 v119, v53
	v_add_f32_e32 v52, v138, v134
	v_add_f32_e32 v53, v139, v135
	s_waitcnt lgkmcnt(2)
	v_mfma_f32_32x32x16_bf16 v[60:75], v[100:103], v[92:95], v[60:75]
	v_add_f32_e64 v52, v52, v110
	v_add_f32_e64 v53, v53, v111
	v_add_f32_e64 v100, v118, v136
	v_add_f32_e64 v101, v119, v137
	v_exp_f32_e32 v110, v54
	v_exp_f32_e32 v111, v55
	v_add_f32_e32 v120, v100, v52
	v_add_f32_e32 v121, v101, v53
	ds_read_b128 v[52:55], v130 offset:18496
	v_cvt_pk_bf16_f32 v138, v118, v119
	s_waitcnt lgkmcnt(1)
	v_mfma_f32_32x32x16_bf16 v[36:51], v[36:39], v[96:99], 0
	v_cvt_pk_bf16_f32 v139, v110, v111
	v_mfma_f32_32x32x16_bf16 v[36:51], v[104:107], v[92:95], v[36:51]
	v_add_f32_e64 v104, v110, v112
	v_add_f32_e64 v105, v111, v113
	v_exp_f32_e32 v106, v56
	v_exp_f32_e32 v107, v57
	v_sub_f32_e32 v112, v58, v116
	v_sub_f32_e32 v113, v59, v116
	ds_read_b128 v[56:59], v130 offset:23104
	ds_read_b128 v[100:103], v130 offset:18528
	ds_read_b128 v[134:137], v130 offset:23136
	v_cvt_pk_bf16_f32 v140, v106, v107
	s_waitcnt lgkmcnt(3)
	v_mfma_f32_32x32x16_bf16 v[60:75], v[52:55], v[88:91], v[60:75]
	v_exp_f32_e32 v52, v112
	v_exp_f32_e32 v53, v113
	v_add_f32_e32 v54, v104, v120
	v_add_f32_e32 v55, v105, v121
	v_add_f32_e32 v104, v106, v114
	v_add_f32_e32 v105, v107, v115
	v_cvt_pk_bf16_f32 v141, v52, v53
	v_add_f32_e32 v54, v104, v54
	v_add_f32_e32 v55, v105, v55
	s_waitcnt lgkmcnt(2)
	v_mfma_f32_32x32x16_bf16 v[36:51], v[56:59], v[88:91], v[36:51]
	v_add_f32_e64 v104, v52, v108
	v_add_f32_e64 v105, v53, v109
	v_add_f32_e64 v54, v104, v54
	v_add_f32_e64 v55, v105, v55
	v_add_f32_e32 v0, v54, v55
	v_add_f32_e32 v127, v117, v0
	ds_read2_b64 v[120:123], v131 offset0:32 offset1:34
	ds_read2_b64 v[112:115], v131 offset0:36 offset1:38
	ds_read2_b64 v[116:119], v132 offset0:64 offset1:66
	ds_read2_b64 v[56:59], v131 offset0:40 offset1:42
	ds_read2_b64 v[52:55], v132 offset0:72 offset1:74
	ds_read2_b64 v[108:111], v132 offset0:68 offset1:70
	ds_read2_b64 v[104:107], v131 offset0:44 offset1:46
	s_waitcnt lgkmcnt(8)
	v_mfma_f32_32x32x16_bf16 v[60:75], v[100:103], v[84:87], v[60:75]
	ds_read2_b64 v[100:103], v132 offset0:76 offset1:78
	s_waitcnt lgkmcnt(8)
	v_mfma_f32_32x32x16_bf16 v[36:51], v[134:137], v[84:87], v[36:51]
	v_mfma_f32_32x32x16_bf16 v[20:35], v[80:83], v[138:141], v[20:35]
	s_nop 10
	v_maximum3_f32 v0, v61, v37, v37
	v_maximum3_f32 v0, v60, v36, v0
	v_maximum3_f32 v1, v62, v38, v38
	v_maximum3_f32 v133, v63, v39, v39
	v_maximum3_f32 v0, v0, v1, v133
	v_maximum3_f32 v1, v64, v40, v40
	v_maximum3_f32 v80, v65, v41, v41
	v_maximum3_f32 v0, v0, v1, v80
	v_maximum3_f32 v1, v66, v42, v42
	v_maximum3_f32 v80, v67, v43, v43
	v_maximum3_f32 v0, v0, v1, v80
	v_maximum3_f32 v1, v68, v44, v44
	v_maximum3_f32 v80, v69, v45, v45
	v_mfma_f32_32x32x16_bf16 v[4:19], v[76:79], v[138:141], v[4:19]
	v_maximum3_f32 v0, v0, v1, v80
	v_maximum3_f32 v1, v70, v46, v46
	v_maximum3_f32 v76, v71, v47, v47
	v_maximum3_f32 v0, v0, v1, v76
	v_maximum3_f32 v1, v72, v48, v48
	v_maximum3_f32 v76, v73, v49, v49
	v_maximum3_f32 v0, v0, v1, v76
	v_maximum3_f32 v1, v74, v50, v50
	v_maximum3_f32 v76, v75, v51, v51
	v_maximum3_f32 v0, v0, v1, v76
	v_mov_b32_e32 v1, v0
	s_nop 1
	v_permlane32_swap_b32_e32 v0, v1
	s_nop 0
	v_maximum3_f32 v76, v0, v1, v1
	v_cmp_gt_f32_e32 vcc, v76, v126
	s_cbranch_vccz .LBB0_867
	v_maximum3_f32 v2, v126, v76, v76
	v_sub_f32_e32 v0, v126, v2
	v_exp_f32_e32 v76, v0
	v_mov_b32_e32 v126, v2
	v_mul_f32_e32 v127, v127, v76
	v_pk_mul_f32 v[34:35], v[34:35], v[76:77] op_sel_hi:[1,0]
	v_pk_mul_f32 v[32:33], v[32:33], v[76:77] op_sel_hi:[1,0]
	v_pk_mul_f32 v[30:31], v[30:31], v[76:77] op_sel_hi:[1,0]
	v_pk_mul_f32 v[28:29], v[28:29], v[76:77] op_sel_hi:[1,0]
	v_pk_mul_f32 v[26:27], v[26:27], v[76:77] op_sel_hi:[1,0]
	v_pk_mul_f32 v[24:25], v[24:25], v[76:77] op_sel_hi:[1,0]
	v_pk_mul_f32 v[22:23], v[22:23], v[76:77] op_sel_hi:[1,0]
	v_pk_mul_f32 v[20:21], v[20:21], v[76:77] op_sel_hi:[1,0]
	v_pk_mul_f32 v[18:19], v[18:19], v[76:77] op_sel_hi:[1,0]
	v_pk_mul_f32 v[16:17], v[16:17], v[76:77] op_sel_hi:[1,0]
	v_pk_mul_f32 v[14:15], v[14:15], v[76:77] op_sel_hi:[1,0]
	v_pk_mul_f32 v[12:13], v[12:13], v[76:77] op_sel_hi:[1,0]
	v_pk_mul_f32 v[10:11], v[10:11], v[76:77] op_sel_hi:[1,0]
	v_pk_mul_f32 v[8:9], v[8:9], v[76:77] op_sel_hi:[1,0]
	v_pk_mul_f32 v[6:7], v[6:7], v[76:77] op_sel_hi:[1,0]
	v_pk_mul_f32 v[4:5], v[4:5], v[76:77] op_sel_hi:[1,0]
.LBB0_867:
	v_sub_f32_e32 v62, v62, v2
	v_sub_f32_e32 v63, v63, v2
	v_sub_f32_e32 v60, v60, v2
	v_sub_f32_e32 v61, v61, v2
	v_exp_f32_e32 v134, v62
	v_exp_f32_e32 v135, v63
	v_sub_f32_e32 v62, v64, v2
	v_sub_f32_e32 v63, v65, v2
	v_sub_f32_e32 v76, v36, v2
	v_sub_f32_e32 v77, v37, v2
	v_exp_f32_e32 v136, v62
	v_exp_f32_e32 v137, v63
	v_sub_f32_e32 v62, v66, v2
	v_sub_f32_e32 v63, v67, v2
	v_exp_f32_e32 v36, v60
	v_exp_f32_e32 v37, v61
	v_exp_f32_e32 v138, v62
	v_exp_f32_e32 v139, v63
	v_cvt_pk_bf16_f32 v63, v134, v135
	v_cvt_pk_bf16_f32 v62, v36, v37
	v_cvt_pk_bf16_f32 v64, v136, v137
	v_cvt_pk_bf16_f32 v65, v138, v139
	v_sub_f32_e32 v66, v68, v2
	v_sub_f32_e32 v67, v69, v2
	v_sub_f32_e32 v38, v38, v2
	v_sub_f32_e32 v39, v39, v2
	s_waitcnt lgkmcnt(7)
	v_mfma_f32_32x32x16_bf16 v[20:35], v[120:123], v[62:65], v[20:35]
	v_exp_f32_e32 v140, v66
	v_exp_f32_e32 v141, v67
	v_sub_f32_e32 v66, v70, v2
	v_sub_f32_e32 v67, v71, v2
	v_exp_f32_e32 v60, v76
	v_exp_f32_e32 v120, v66
	v_exp_f32_e32 v121, v67
	v_sub_f32_e32 v66, v72, v2
	v_sub_f32_e32 v67, v73, v2
	s_waitcnt lgkmcnt(5)
	v_mfma_f32_32x32x16_bf16 v[4:19], v[116:119], v[62:65], v[4:19]
	v_add_f32_e64 v62, v74, -v2
	v_add_f32_e64 v63, v75, -v2
	v_exp_f32_e32 v122, v66
	v_exp_f32_e32 v123, v67
	v_exp_f32_e32 v116, v62
	v_exp_f32_e32 v117, v63
	v_cvt_pk_bf16_f32 v62, v140, v141
	v_cvt_pk_bf16_f32 v63, v120, v121
	v_cvt_pk_bf16_f32 v64, v122, v123
	v_cvt_pk_bf16_f32 v65, v116, v117
	v_exp_f32_e32 v66, v38
	v_exp_f32_e32 v67, v39
	v_mfma_f32_32x32x16_bf16 v[20:35], v[112:115], v[62:65], v[20:35]
	v_add_f32_e64 v38, v40, -v2
	v_add_f32_e64 v39, v41, -v2
	v_exp_f32_e32 v61, v77
	v_exp_f32_e32 v118, v38
	v_exp_f32_e32 v119, v39
	v_sub_f32_e32 v38, v42, v2
	v_sub_f32_e32 v39, v43, v2
	v_add_f32_e32 v36, v60, v36
	v_add_f32_e32 v37, v61, v37
	v_exp_f32_e32 v42, v38
	s_waitcnt lgkmcnt(2)
	v_mfma_f32_32x32x16_bf16 v[4:19], v[108:111], v[62:65], v[4:19]
	v_exp_f32_e32 v43, v39
	v_cvt_pk_bf16_f32 v38, v60, v61
	v_cvt_pk_bf16_f32 v39, v66, v67
	v_cvt_pk_bf16_f32 v40, v118, v119
	v_cvt_pk_bf16_f32 v41, v42, v43
	v_pk_add_f32 v[36:37], v[36:37], 0 op_sel_hi:[1,0]
	v_add_f32_e32 v134, v66, v134
	v_add_f32_e32 v135, v67, v135
	v_mfma_f32_32x32x16_bf16 v[20:35], v[56:59], v[38:41], v[20:35]
	v_add_f32_e64 v36, v134, v36
	v_add_f32_e64 v37, v135, v37
	v_add_f32_e64 v50, v50, -v2
	v_add_f32_e64 v51, v51, -v2
	v_exp_f32_e32 v50, v50
	v_exp_f32_e32 v51, v51
	v_mfma_f32_32x32x16_bf16 v[4:19], v[52:55], v[38:41], v[4:19]
	ds_read_b128 v[38:41], v130 offset:27648
	ds_read_b128 v[108:111], v130 offset:27680
	ds_read_b128 v[112:115], v130 offset:32288
	s_waitcnt lgkmcnt(2)
	v_mfma_f32_32x32x16_bf16 v[68:83], v[38:41], v[96:99], 0
	ds_read_b128 v[38:41], v130 offset:32256
	s_waitcnt lgkmcnt(0)
	v_mfma_f32_32x32x16_bf16 v[52:67], v[38:41], v[96:99], 0
	v_add_f32_e64 v38, v118, v136
	v_add_f32_e64 v39, v119, v137
	v_add_f32_e64 v40, v46, -v2
	v_add_f32_e64 v41, v47, -v2
	v_add_f32_e64 v36, v38, v36
	v_add_f32_e64 v37, v39, v37
	v_sub_f32_e32 v38, v44, v2
	v_sub_f32_e32 v39, v45, v2
	v_exp_f32_e32 v98, v40
	v_exp_f32_e32 v96, v38
	v_exp_f32_e32 v97, v39
	v_add_f32_e32 v38, v42, v138
	v_add_f32_e32 v39, v43, v139
	v_mfma_f32_32x32x16_bf16 v[68:83], v[108:111], v[92:95], v[68:83]
	v_add_f32_e64 v36, v38, v36
	v_add_f32_e64 v37, v39, v37
	v_add_f32_e64 v38, v96, v140
	v_add_f32_e64 v39, v97, v141
	v_exp_f32_e32 v99, v41
	v_add_f32_e32 v108, v38, v36
	v_add_f32_e32 v109, v39, v37
	ds_read_b128 v[36:39], v130 offset:27712
	v_sub_f32_e32 v40, v48, v2
	v_sub_f32_e32 v41, v49, v2
	v_mfma_f32_32x32x16_bf16 v[52:67], v[112:115], v[92:95], v[52:67]
	v_exp_f32_e32 v48, v40
	v_exp_f32_e32 v49, v41
	ds_read_b128 v[40:43], v130 offset:32320
	ds_read_b128 v[44:47], v130 offset:27744
	v_add_f32_e32 v92, v98, v120
	v_add_f32_e32 v93, v99, v121
	v_add_f32_e32 v94, v50, v116
	v_add_f32_e32 v95, v51, v117
	v_cvt_pk_bf16_f32 v114, v96, v97
	v_cvt_pk_bf16_f32 v115, v98, v99
	s_waitcnt lgkmcnt(2)
	v_mfma_f32_32x32x16_bf16 v[68:83], v[36:39], v[88:91], v[68:83]
	v_add_f32_e64 v36, v92, v108
	v_add_f32_e64 v37, v93, v109
	v_add_f32_e64 v38, v48, v122
	v_add_f32_e64 v39, v49, v123
	v_cvt_pk_bf16_f32 v116, v48, v49
	v_add_f32_e32 v92, v38, v36
	v_add_f32_e32 v93, v39, v37
	ds_read_b128 v[36:39], v130 offset:32352
	v_cvt_pk_bf16_f32 v117, v50, v51
	s_waitcnt lgkmcnt(2)
	v_mfma_f32_32x32x16_bf16 v[52:67], v[40:43], v[88:91], v[52:67]
	v_add_f32_e64 v40, v94, v92
	v_add_f32_e64 v41, v95, v93
	v_add_f32_e32 v0, v40, v41
	v_add_f32_e32 v112, v127, v0
	s_waitcnt lgkmcnt(1)
	v_mfma_f32_32x32x16_bf16 v[68:83], v[44:47], v[84:87], v[68:83]
	ds_read2_b64 v[108:111], v131 offset0:48 offset1:50
	ds_read2_b64 v[92:95], v131 offset0:52 offset1:54
	ds_read2_b64 v[96:99], v132 offset0:80 offset1:82
	ds_read2_b64 v[48:51], v131 offset0:56 offset1:58
	ds_read2_b64 v[44:47], v132 offset0:88 offset1:90
	ds_read2_b64 v[88:91], v132 offset0:84 offset1:86
	ds_read2_b64 v[40:43], v131 offset0:60 offset1:62
	s_waitcnt lgkmcnt(7)
	v_mfma_f32_32x32x16_bf16 v[52:67], v[36:39], v[84:87], v[52:67]
	ds_read2_b64 v[36:39], v132 offset0:92 offset1:94
	v_mfma_f32_32x32x16_bf16 v[20:35], v[104:107], v[114:117], v[20:35]
	s_nop 9
	v_maximum3_f32 v0, v69, v53, v53
	v_maximum3_f32 v0, v68, v52, v0
	v_maximum3_f32 v1, v70, v54, v54
	v_maximum3_f32 v84, v71, v55, v55
	v_maximum3_f32 v0, v0, v1, v84
	v_maximum3_f32 v1, v72, v56, v56
	v_maximum3_f32 v84, v73, v57, v57
	v_maximum3_f32 v0, v0, v1, v84
	v_maximum3_f32 v1, v74, v58, v58
	v_maximum3_f32 v84, v75, v59, v59
	v_maximum3_f32 v0, v0, v1, v84
	v_maximum3_f32 v1, v76, v60, v60
	v_maximum3_f32 v84, v77, v61, v61
	v_maximum3_f32 v0, v0, v1, v84
	v_maximum3_f32 v1, v78, v62, v62
	v_maximum3_f32 v84, v79, v63, v63
	v_mfma_f32_32x32x16_bf16 v[4:19], v[100:103], v[114:117], v[4:19]
	v_maximum3_f32 v0, v0, v1, v84
	v_maximum3_f32 v1, v80, v64, v64
	v_maximum3_f32 v84, v81, v65, v65
	v_maximum3_f32 v0, v0, v1, v84
	v_maximum3_f32 v1, v82, v66, v66
	v_maximum3_f32 v84, v83, v67, v67
	v_maximum3_f32 v0, v0, v1, v84
	v_mov_b32_e32 v1, v0
	s_nop 1
	v_permlane32_swap_b32_e32 v0, v1
	s_nop 0
	v_maximum3_f32 v84, v0, v1, v1
	v_cmp_gt_f32_e32 vcc, v84, v126
	s_cbranch_vccz .LBB0_869
	v_maximum3_f32 v2, v126, v84, v84
	v_sub_f32_e32 v0, v126, v2
	v_exp_f32_e32 v84, v0
	s_nop 0
	v_mul_f32_e32 v112, v112, v84
	v_pk_mul_f32 v[34:35], v[34:35], v[84:85] op_sel_hi:[1,0]
	v_pk_mul_f32 v[32:33], v[32:33], v[84:85] op_sel_hi:[1,0]
	v_pk_mul_f32 v[30:31], v[30:31], v[84:85] op_sel_hi:[1,0]
	v_pk_mul_f32 v[28:29], v[28:29], v[84:85] op_sel_hi:[1,0]
	v_pk_mul_f32 v[26:27], v[26:27], v[84:85] op_sel_hi:[1,0]
	v_pk_mul_f32 v[24:25], v[24:25], v[84:85] op_sel_hi:[1,0]
	v_pk_mul_f32 v[22:23], v[22:23], v[84:85] op_sel_hi:[1,0]
	v_pk_mul_f32 v[20:21], v[20:21], v[84:85] op_sel_hi:[1,0]
	v_pk_mul_f32 v[18:19], v[18:19], v[84:85] op_sel_hi:[1,0]
	v_pk_mul_f32 v[16:17], v[16:17], v[84:85] op_sel_hi:[1,0]
	v_pk_mul_f32 v[14:15], v[14:15], v[84:85] op_sel_hi:[1,0]
	v_pk_mul_f32 v[12:13], v[12:13], v[84:85] op_sel_hi:[1,0]
	v_pk_mul_f32 v[10:11], v[10:11], v[84:85] op_sel_hi:[1,0]
	v_pk_mul_f32 v[8:9], v[8:9], v[84:85] op_sel_hi:[1,0]
	v_pk_mul_f32 v[6:7], v[6:7], v[84:85] op_sel_hi:[1,0]
	v_pk_mul_f32 v[4:5], v[4:5], v[84:85] op_sel_hi:[1,0]
.LBB0_869:
	v_sub_f32_e32 v68, v68, v2
	v_sub_f32_e32 v69, v69, v2
	v_sub_f32_e32 v52, v52, v2
	v_sub_f32_e32 v53, v53, v2
	v_exp_f32_e32 v68, v68
	v_exp_f32_e32 v69, v69
	v_exp_f32_e32 v84, v52
	v_exp_f32_e32 v85, v53
	v_sub_f32_e32 v52, v70, v2
	v_sub_f32_e32 v53, v71, v2
	v_sub_f32_e32 v54, v54, v2
	v_sub_f32_e32 v55, v55, v2
	v_exp_f32_e32 v70, v52
	v_exp_f32_e32 v71, v53
	v_exp_f32_e32 v86, v54
	v_exp_f32_e32 v87, v55
	v_sub_f32_e32 v72, v72, v2
	v_sub_f32_e32 v73, v73, v2
	v_sub_f32_e32 v56, v56, v2
	v_sub_f32_e32 v57, v57, v2
	v_exp_f32_e32 v72, v72
	v_exp_f32_e32 v73, v73
	v_exp_f32_e32 v56, v56
	v_exp_f32_e32 v57, v57
	v_sub_f32_e32 v74, v74, v2
	v_sub_f32_e32 v75, v75, v2
	v_add_f32_e32 v52, v84, v68
	v_add_f32_e32 v53, v85, v69
	v_exp_f32_e32 v74, v74
	v_exp_f32_e32 v75, v75
	v_pk_add_f32 v[52:53], v[52:53], 0 op_sel_hi:[1,0]
	v_add_f32_e32 v54, v86, v70
	v_add_f32_e32 v55, v87, v71
	v_sub_f32_e32 v58, v58, v2
	v_sub_f32_e32 v59, v59, v2
	v_add_f32_e32 v52, v54, v52
	v_add_f32_e32 v53, v55, v53
	v_add_f32_e32 v54, v56, v72
	v_add_f32_e32 v55, v57, v73
	v_exp_f32_e32 v58, v58
	v_add_f32_e32 v100, v54, v52
	v_add_f32_e32 v101, v55, v53
	v_sub_f32_e32 v52, v76, v2
	v_sub_f32_e32 v53, v77, v2
	v_cvt_pk_bf16_f32 v54, v72, v73
	v_exp_f32_e32 v76, v52
	v_exp_f32_e32 v77, v53
	v_cvt_pk_bf16_f32 v52, v68, v69
	v_cvt_pk_bf16_f32 v53, v70, v71
	v_cvt_pk_bf16_f32 v55, v74, v75
	v_sub_f32_e32 v68, v78, v2
	v_sub_f32_e32 v69, v79, v2
	v_sub_f32_e32 v70, v80, v2
	v_sub_f32_e32 v71, v81, v2
	s_waitcnt lgkmcnt(7)
	v_mfma_f32_32x32x16_bf16 v[20:35], v[108:111], v[52:55], v[20:35]
	v_exp_f32_e32 v68, v68
	v_exp_f32_e32 v69, v69
	v_exp_f32_e32 v70, v70
	v_exp_f32_e32 v71, v71
	v_exp_f32_e32 v59, v59
	v_sub_f32_e32 v60, v60, v2
	v_sub_f32_e32 v61, v61, v2
	v_sub_f32_e32 v62, v62, v2
	v_sub_f32_e32 v63, v63, v2
	s_waitcnt lgkmcnt(5)
	v_mfma_f32_32x32x16_bf16 v[4:19], v[96:99], v[52:55], v[4:19]
	v_add_f32_e64 v52, v82, -v2
	v_add_f32_e64 v53, v83, -v2
	v_cvt_pk_bf16_f32 v54, v70, v71
	v_exp_f32_e32 v72, v52
	v_exp_f32_e32 v73, v53
	v_cvt_pk_bf16_f32 v52, v76, v77
	v_cvt_pk_bf16_f32 v53, v68, v69
	v_exp_f32_e32 v60, v60
	v_cvt_pk_bf16_f32 v55, v72, v73
	v_exp_f32_e32 v61, v61
	v_exp_f32_e32 v62, v62
	v_mfma_f32_32x32x16_bf16 v[20:35], v[92:95], v[52:55], v[20:35]
	v_exp_f32_e32 v63, v63
	v_add_f32_e32 v102, v58, v74
	v_add_f32_e32 v103, v59, v75
	v_add_f32_e32 v76, v60, v76
	v_add_f32_e32 v77, v61, v77
	v_add_f32_e32 v74, v102, v100
	v_add_f32_e32 v75, v103, v101
	v_add_f32_e32 v68, v62, v68
	v_add_f32_e32 v69, v63, v69
	v_add_f32_e32 v74, v76, v74
	v_add_f32_e32 v75, v77, v75
	v_and_b32_e32 v0, 63, v128
	s_waitcnt lgkmcnt(2)
	v_mfma_f32_32x32x16_bf16 v[4:19], v[88:91], v[52:55], v[4:19]
	v_add_f32_e64 v52, v64, -v2
	v_add_f32_e64 v53, v65, -v2
	v_cvt_pk_bf16_f32 v54, v56, v57
	v_exp_f32_e32 v64, v52
	v_exp_f32_e32 v65, v53
	v_cvt_pk_bf16_f32 v52, v84, v85
	v_cvt_pk_bf16_f32 v53, v86, v87
	v_cvt_pk_bf16_f32 v55, v58, v59
	v_add_f32_e32 v56, v64, v70
	v_add_f32_e32 v57, v65, v71
	v_lshlrev_b32_e32 v0, 2, v0
	v_mfma_f32_32x32x16_bf16 v[20:35], v[48:51], v[52:55], v[20:35]
	v_add_f32_e64 v48, v66, -v2
	v_add_f32_e64 v49, v67, -v2
	v_add_f32_e64 v50, v68, v74
	v_add_f32_e64 v51, v69, v75
	v_exp_f32_e32 v48, v48
	v_exp_f32_e32 v49, v49
	v_add_f32_e32 v50, v56, v50
	v_add_f32_e32 v51, v57, v51
	v_xor_b32_e32 v0, 0x80, v0
	v_add_f32_e32 v56, v48, v72
	v_add_f32_e32 v57, v49, v73
	v_mfma_f32_32x32x16_bf16 v[4:19], v[44:47], v[52:55], v[4:19]
	v_add_f32_e64 v44, v56, v50
	v_add_f32_e64 v45, v57, v51
	v_cvt_pk_bf16_f32 v46, v64, v65
	v_add_f32_e32 v1, v44, v45
	v_add_f32_e32 v1, v112, v1
	ds_bpermute_b32 v0, v0, v1
	v_cvt_pk_bf16_f32 v44, v60, v61
	v_cvt_pk_bf16_f32 v45, v62, v63
	v_cvt_pk_bf16_f32 v47, v48, v49
	s_waitcnt lgkmcnt(0)
	v_add_f32_e32 v0, v1, v0
	v_div_scale_f32 v1, s[4:5], v0, v0, 1.0
	v_rcp_f32_e32 v2, v1
	v_mfma_f32_32x32x16_bf16 v[20:35], v[40:43], v[44:47], v[20:35]
	s_mov_b64 s[4:5], 0xd000400
	v_mfma_f32_32x32x16_bf16 v[4:19], v[36:39], v[44:47], v[4:19]
	v_fma_f32 v36, -v1, v2, 1.0
	v_fmac_f32_e32 v2, v36, v2
	v_div_scale_f32 v36, vcc, 1.0, v0, 1.0
	v_mul_f32_e32 v37, v36, v2
	v_fma_f32 v38, -v1, v37, v36
	v_fmac_f32_e32 v37, v38, v2
	v_fma_f32 v1, -v1, v37, v36
	v_lshlrev_b64 v[38:39], 12, v[124:125]
	v_div_fmas_f32 v1, v1, v2, v37
	v_lshl_add_u64 v[38:39], s[10:11], 0, v[38:39]
	v_div_fixup_f32 v36, v1, v0, 1.0
	v_lshl_add_u64 v[38:39], v[38:39], 0, s[20:21]
	v_lshlrev_b32_e32 v2, 1, v129
	v_lshl_add_u64 v[38:39], v[38:39], 0, v[2:3]
	v_pk_mul_f32 v[20:21], v[20:21], v[36:37] op_sel_hi:[1,0]
	v_pk_mul_f32 v[22:23], v[22:23], v[36:37] op_sel_hi:[1,0]
	v_pk_mul_f32 v[6:7], v[6:7], v[36:37] op_sel_hi:[1,0]
	v_lshl_add_u64 v[40:41], v[38:39], 0, s[4:5]
	v_pk_mul_f32 v[42:43], v[4:5], v[36:37] op_sel_hi:[1,0]
	v_cvt_pk_bf16_f32 v4, v20, v21
	v_cvt_pk_bf16_f32 v5, v22, v23
	v_cvt_pk_bf16_f32 v21, v6, v7
	v_pk_mul_f32 v[6:7], v[24:25], v[36:37] op_sel_hi:[1,0]
	v_pk_mul_f32 v[22:23], v[26:27], v[36:37] op_sel_hi:[1,0]
	v_pk_mul_f32 v[8:9], v[8:9], v[36:37] op_sel_hi:[1,0]
	s_mov_b32 s4, 0xd000000
	v_cvt_pk_bf16_f32 v6, v6, v7
	v_cvt_pk_bf16_f32 v7, v22, v23
	v_cvt_pk_bf16_f32 v22, v8, v9
	v_add_co_u32_e32 v8, vcc, s4, v38
	v_pk_mul_f32 v[10:11], v[10:11], v[36:37] op_sel_hi:[1,0]
	v_permlane32_swap_b32_e32 v4, v6
	v_permlane32_swap_b32_e32 v5, v7
	v_addc_co_u32_e32 v9, vcc, 0, v39, vcc
	v_cvt_pk_bf16_f32 v23, v10, v11
	global_store_dwordx4 v[8:9], v[4:7], off offset:1024
	v_pk_mul_f32 v[8:9], v[12:13], v[36:37] op_sel_hi:[1,0]
	v_pk_mul_f32 v[10:11], v[14:15], v[36:37] op_sel_hi:[1,0]
	v_pk_mul_f32 v[4:5], v[28:29], v[36:37] op_sel_hi:[1,0]
	v_pk_mul_f32 v[6:7], v[30:31], v[36:37] op_sel_hi:[1,0]
	v_cvt_pk_bf16_f32 v4, v4, v5
	v_cvt_pk_bf16_f32 v5, v6, v7
	v_cvt_pk_bf16_f32 v8, v8, v9
	v_cvt_pk_bf16_f32 v9, v10, v11
	v_pk_mul_f32 v[6:7], v[32:33], v[36:37] op_sel_hi:[1,0]
	v_pk_mul_f32 v[10:11], v[34:35], v[36:37] op_sel_hi:[1,0]
	v_pk_mul_f32 v[12:13], v[16:17], v[36:37] op_sel_hi:[1,0]
	v_pk_mul_f32 v[14:15], v[18:19], v[36:37] op_sel_hi:[1,0]
	v_cvt_pk_bf16_f32 v20, v42, v43
	v_cvt_pk_bf16_f32 v6, v6, v7
	v_cvt_pk_bf16_f32 v7, v10, v11
	v_cvt_pk_bf16_f32 v10, v12, v13
	v_cvt_pk_bf16_f32 v11, v14, v15
	v_permlane32_swap_b32_e32 v20, v22
	v_permlane32_swap_b32_e32 v21, v23
	v_permlane32_swap_b32_e32 v4, v6
	v_permlane32_swap_b32_e32 v5, v7
	v_permlane32_swap_b32_e32 v8, v10
	v_permlane32_swap_b32_e32 v9, v11
	s_mov_b64 s[4:5], 0
	global_store_dwordx4 v[40:41], v[20:23], off offset:64
	global_store_dwordx4 v[40:41], v[4:7], off offset:32
	global_store_dwordx4 v[40:41], v[8:11], off offset:96

.LBB0_882:
	v_sub_f32_e32 v20, v48, v2
	v_sub_f32_e32 v21, v49, v2
	v_mov_b32_e32 v5, v4
	v_exp_f32_e32 v112, v20
	v_exp_f32_e32 v113, v21
	v_sub_f32_e32 v20, v50, v2
	v_sub_f32_e32 v21, v51, v2
	v_mov_b32_e32 v6, v4
	v_exp_f32_e32 v116, v20
	v_exp_f32_e32 v117, v21
	v_sub_f32_e32 v20, v52, v2
	v_sub_f32_e32 v21, v53, v2
	v_mov_b32_e32 v7, v4
	v_exp_f32_e32 v118, v20
	v_exp_f32_e32 v119, v21
	v_sub_f32_e32 v20, v54, v2
	v_sub_f32_e32 v21, v55, v2
	v_mov_b32_e32 v8, v4
	v_exp_f32_e32 v120, v20
	v_exp_f32_e32 v121, v21
	v_mov_b32_e32 v9, v4
	v_mov_b32_e32 v10, v4
	v_mov_b32_e32 v11, v4
	v_mov_b32_e32 v12, v4
	v_mov_b32_e32 v13, v4
	v_mov_b32_e32 v14, v4
	v_mov_b32_e32 v15, v4
	v_mov_b32_e32 v16, v4
	v_mov_b32_e32 v17, v4
	v_mov_b32_e32 v18, v4
	v_mov_b32_e32 v19, v4
	v_sub_f32_e32 v22, v32, v2
	v_sub_f32_e32 v23, v33, v2
	v_cvt_pk_bf16_f32 v48, v112, v113
	v_cvt_pk_bf16_f32 v49, v116, v117
	v_cvt_pk_bf16_f32 v50, v118, v119
	v_cvt_pk_bf16_f32 v51, v120, v121
	v_exp_f32_e32 v114, v22
	v_exp_f32_e32 v115, v23
	v_sub_f32_e32 v132, v34, v2
	v_sub_f32_e32 v133, v35, v2
	v_sub_f32_e32 v52, v56, v2
	v_sub_f32_e32 v53, v57, v2
	s_waitcnt lgkmcnt(7)
	v_mfma_f32_32x32x16_bf16 v[20:35], v[108:111], v[48:51], v[4:19]
	v_exp_f32_e32 v134, v52
	v_exp_f32_e32 v135, v53
	v_sub_f32_e32 v52, v58, v2
	v_sub_f32_e32 v53, v59, v2
	v_sub_f32_e32 v36, v36, v2
	v_sub_f32_e32 v37, v37, v2
	v_exp_f32_e32 v108, v52
	v_exp_f32_e32 v109, v53
	v_sub_f32_e32 v52, v60, v2
	v_sub_f32_e32 v53, v61, v2
	s_waitcnt lgkmcnt(5)
	v_mfma_f32_32x32x16_bf16 v[4:19], v[104:107], v[48:51], v[4:19]
	v_add_f32_e64 v48, v62, -v2
	v_add_f32_e64 v49, v63, -v2
	v_exp_f32_e32 v110, v52
	v_exp_f32_e32 v111, v53
	v_exp_f32_e32 v104, v48
	v_exp_f32_e32 v105, v49
	v_cvt_pk_bf16_f32 v48, v134, v135
	v_cvt_pk_bf16_f32 v49, v108, v109
	v_cvt_pk_bf16_f32 v50, v110, v111
	v_cvt_pk_bf16_f32 v51, v104, v105
	v_sub_f32_e32 v40, v40, v2
	v_sub_f32_e32 v41, v41, v2
	s_nop 0
	v_mfma_f32_32x32x16_bf16 v[20:35], v[100:103], v[48:51], v[20:35]
	v_exp_f32_e32 v102, v36
	v_exp_f32_e32 v103, v37
	v_sub_f32_e32 v36, v38, v2
	v_sub_f32_e32 v37, v39, v2
	v_exp_f32_e32 v100, v132
	v_exp_f32_e32 v101, v133
	v_exp_f32_e32 v106, v36
	v_exp_f32_e32 v107, v37
	s_waitcnt lgkmcnt(2)
	v_mfma_f32_32x32x16_bf16 v[4:19], v[80:83], v[48:51], v[4:19]
	v_cvt_pk_bf16_f32 v36, v114, v115
	v_cvt_pk_bf16_f32 v37, v100, v101
	v_cvt_pk_bf16_f32 v38, v102, v103
	v_cvt_pk_bf16_f32 v39, v106, v107
	v_exp_f32_e32 v80, v40
	v_exp_f32_e32 v81, v41
	v_sub_f32_e32 v40, v42, v2
	v_sub_f32_e32 v41, v43, v2
	v_mfma_f32_32x32x16_bf16 v[20:35], v[76:79], v[36:39], v[20:35]
	v_exp_f32_e32 v82, v40
	v_exp_f32_e32 v83, v41
	v_sub_f32_e32 v40, v44, v2
	v_sub_f32_e32 v41, v45, v2
	v_add_f32_e32 v76, v114, v112
	v_add_f32_e32 v77, v115, v113
	v_exp_f32_e32 v132, v40
	v_exp_f32_e32 v133, v41
	v_mfma_f32_32x32x16_bf16 v[4:19], v[72:75], v[36:39], v[4:19]
	v_add_f32_e64 v36, v46, -v2
	v_add_f32_e64 v37, v47, -v2
	v_cvt_pk_bf16_f32 v38, v132, v133
	v_exp_f32_e32 v136, v36
	v_exp_f32_e32 v137, v37
	v_cvt_pk_bf16_f32 v36, v80, v81
	v_cvt_pk_bf16_f32 v37, v82, v83
	ds_read_b128 v[72:75], v128 offset:9280
	v_cvt_pk_bf16_f32 v39, v136, v137
	s_waitcnt lgkmcnt(2)
	s_nop 0
	v_mfma_f32_32x32x16_bf16 v[20:35], v[68:71], v[36:39], v[20:35]
	ds_read_b128 v[68:71], v128 offset:9248
	s_waitcnt lgkmcnt(2)
	v_mfma_f32_32x32x16_bf16 v[4:19], v[64:67], v[36:39], v[4:19]
	ds_read_b128 v[36:39], v128 offset:9216
	s_waitcnt lgkmcnt(0)
	v_mfma_f32_32x32x16_bf16 v[52:67], v[36:39], v[96:99], 0
	ds_read_b128 v[36:39], v128 offset:13824
	v_mfma_f32_32x32x16_bf16 v[52:67], v[68:71], v[92:95], v[52:67]
	ds_read_b128 v[68:71], v128 offset:13856
	s_waitcnt lgkmcnt(1)
	v_mfma_f32_32x32x16_bf16 v[36:51], v[36:39], v[96:99], 0
	s_waitcnt lgkmcnt(0)
	v_mfma_f32_32x32x16_bf16 v[36:51], v[68:71], v[92:95], v[36:51]
	v_add_f32_e64 v68, v76, 0
	v_add_f32_e64 v69, v77, 0
	v_add_f32_e64 v70, v100, v116
	v_add_f32_e64 v71, v101, v117
	v_add_f32_e64 v68, v70, v68
	v_add_f32_e64 v69, v71, v69
	v_add_f32_e32 v70, v102, v118
	v_add_f32_e32 v71, v103, v119
	s_nop 0
	v_add_f32_e32 v100, v70, v68
	v_add_f32_e32 v101, v71, v69
	ds_read_b128 v[68:71], v128 offset:13888
	ds_read_b128 v[76:79], v128 offset:9312
	v_mfma_f32_32x32x16_bf16 v[52:67], v[72:75], v[88:91], v[52:67]
	v_add_f32_e64 v72, v106, v120
	v_add_f32_e64 v73, v107, v121
	ds_read_b128 v[118:121], v128 offset:13920
	v_add_f32_e64 v72, v72, v100
	v_add_f32_e64 v73, v73, v101
	v_add_f32_e32 v74, v80, v134
	v_add_f32_e32 v75, v81, v135
	s_nop 0
	v_add_f32_e32 v72, v74, v72
	v_add_f32_e32 v73, v75, v73
	v_add_f32_e32 v74, v82, v108
	v_add_f32_e32 v75, v83, v109
	s_waitcnt lgkmcnt(2)
	v_mfma_f32_32x32x16_bf16 v[36:51], v[68:71], v[88:91], v[36:51]
	v_add_f32_e64 v72, v74, v72
	v_add_f32_e64 v73, v75, v73
	v_add_f32_e64 v68, v132, v110
	v_add_f32_e64 v69, v133, v111
	v_add_f32_e64 v70, v136, v104
	v_add_f32_e64 v71, v137, v105
	v_add_f32_e32 v68, v68, v72
	v_add_f32_e32 v69, v69, v73
	ds_read2_b64 v[108:111], v129 offset0:16 offset1:18
	v_add_f32_e32 v68, v70, v68
	v_add_f32_e32 v69, v71, v69
	s_waitcnt lgkmcnt(2)
	v_mfma_f32_32x32x16_bf16 v[52:67], v[76:79], v[84:87], v[52:67]
	v_add_f32_e32 v0, v68, v69
	v_add_f32_e32 v116, v122, v0
	ds_read2_b64 v[80:83], v129 offset0:20 offset1:22
	ds_read2_b64 v[100:103], v130 offset0:48 offset1:50
	ds_read2_b64 v[72:75], v129 offset0:24 offset1:26
	ds_read2_b64 v[68:71], v130 offset0:56 offset1:58
	ds_read2_b64 v[76:79], v130 offset0:52 offset1:54
	ds_read2_b64 v[112:115], v129 offset0:28 offset1:30
	ds_read2_b64 v[104:107], v130 offset0:60 offset1:62
	s_waitcnt lgkmcnt(8)
	v_mfma_f32_32x32x16_bf16 v[36:51], v[118:121], v[84:87], v[36:51]
	s_nop 11
	v_maximum3_f32 v0, v53, v37, v37
	v_maximum3_f32 v0, v52, v36, v0
	v_maximum3_f32 v1, v54, v38, v38
	v_maximum3_f32 v117, v55, v39, v39
	v_maximum3_f32 v0, v0, v1, v117
	v_maximum3_f32 v1, v56, v40, v40
	v_maximum3_f32 v117, v57, v41, v41
	v_maximum3_f32 v0, v0, v1, v117
	v_maximum3_f32 v1, v58, v42, v42
	v_maximum3_f32 v117, v59, v43, v43
	v_maximum3_f32 v0, v0, v1, v117
	v_maximum3_f32 v1, v60, v44, v44
	v_maximum3_f32 v117, v61, v45, v45
	v_maximum3_f32 v0, v0, v1, v117
	v_maximum3_f32 v1, v62, v46, v46
	v_maximum3_f32 v117, v63, v47, v47
	v_maximum3_f32 v0, v0, v1, v117
	v_maximum3_f32 v1, v64, v48, v48
	v_maximum3_f32 v117, v65, v49, v49
	v_maximum3_f32 v0, v0, v1, v117
	v_maximum3_f32 v1, v66, v50, v50
	v_maximum3_f32 v117, v67, v51, v51
	v_maximum3_f32 v0, v0, v1, v117
	v_mov_b32_e32 v1, v0
	s_nop 1
	v_permlane32_swap_b32_e32 v0, v1
	s_nop 0
	v_maximum3_f32 v117, v0, v1, v1
	v_cmp_gt_f32_e32 vcc, v117, v2
	s_cbranch_vccz .LBB0_884
	v_maximum3_f32 v0, v2, v117, v117
	v_sub_f32_e32 v1, v2, v0
	v_exp_f32_e32 v2, v1
	s_nop 0
	v_mul_f32_e32 v116, v116, v2
	v_pk_mul_f32 v[34:35], v[34:35], v[2:3] op_sel_hi:[1,0]
	v_pk_mul_f32 v[32:33], v[32:33], v[2:3] op_sel_hi:[1,0]
	v_pk_mul_f32 v[30:31], v[30:31], v[2:3] op_sel_hi:[1,0]
	v_pk_mul_f32 v[28:29], v[28:29], v[2:3] op_sel_hi:[1,0]
	v_pk_mul_f32 v[26:27], v[26:27], v[2:3] op_sel_hi:[1,0]
	v_pk_mul_f32 v[24:25], v[24:25], v[2:3] op_sel_hi:[1,0]
	v_pk_mul_f32 v[22:23], v[22:23], v[2:3] op_sel_hi:[1,0]
	v_pk_mul_f32 v[20:21], v[20:21], v[2:3] op_sel_hi:[1,0]
	v_pk_mul_f32 v[18:19], v[18:19], v[2:3] op_sel_hi:[1,0]
	v_pk_mul_f32 v[16:17], v[16:17], v[2:3] op_sel_hi:[1,0]
	v_pk_mul_f32 v[14:15], v[14:15], v[2:3] op_sel_hi:[1,0]
	v_pk_mul_f32 v[12:13], v[12:13], v[2:3] op_sel_hi:[1,0]
	v_pk_mul_f32 v[10:11], v[10:11], v[2:3] op_sel_hi:[1,0]
	v_pk_mul_f32 v[8:9], v[8:9], v[2:3] op_sel_hi:[1,0]
	v_pk_mul_f32 v[6:7], v[6:7], v[2:3] op_sel_hi:[1,0]
	v_pk_mul_f32 v[4:5], v[4:5], v[2:3] op_sel_hi:[1,0]
	v_mov_b32_e32 v2, v0
.LBB0_884:
	v_sub_f32_e32 v54, v54, v2
	v_sub_f32_e32 v55, v55, v2
	v_sub_f32_e32 v52, v52, v2
	v_sub_f32_e32 v53, v53, v2
	v_exp_f32_e32 v120, v54
	v_exp_f32_e32 v121, v55
	v_sub_f32_e32 v54, v56, v2
	v_sub_f32_e32 v55, v57, v2
	v_sub_f32_e32 v118, v36, v2
	v_sub_f32_e32 v119, v37, v2
	v_exp_f32_e32 v122, v54
	v_exp_f32_e32 v123, v55
	v_sub_f32_e32 v54, v58, v2
	v_sub_f32_e32 v55, v59, v2
	v_exp_f32_e32 v36, v52
	v_exp_f32_e32 v37, v53
	v_exp_f32_e32 v132, v54
	v_exp_f32_e32 v133, v55
	v_cvt_pk_bf16_f32 v55, v120, v121
	v_cvt_pk_bf16_f32 v54, v36, v37
	v_cvt_pk_bf16_f32 v56, v122, v123
	v_cvt_pk_bf16_f32 v57, v132, v133
	v_sub_f32_e32 v58, v60, v2
	v_sub_f32_e32 v59, v61, v2
	v_sub_f32_e32 v38, v38, v2
	v_sub_f32_e32 v39, v39, v2
	s_waitcnt lgkmcnt(7)
	v_mfma_f32_32x32x16_bf16 v[20:35], v[108:111], v[54:57], v[20:35]
	v_exp_f32_e32 v134, v58
	v_exp_f32_e32 v135, v59
	v_sub_f32_e32 v58, v62, v2
	v_sub_f32_e32 v59, v63, v2
	v_exp_f32_e32 v52, v118
	v_exp_f32_e32 v136, v58
	v_exp_f32_e32 v137, v59
	v_sub_f32_e32 v58, v64, v2
	v_sub_f32_e32 v59, v65, v2
	s_waitcnt lgkmcnt(5)
	v_mfma_f32_32x32x16_bf16 v[4:19], v[100:103], v[54:57], v[4:19]
	v_add_f32_e64 v54, v66, -v2
	v_add_f32_e64 v55, v67, -v2
	v_exp_f32_e32 v138, v58
	v_exp_f32_e32 v139, v59
	v_exp_f32_e32 v140, v54
	v_exp_f32_e32 v141, v55
	v_cvt_pk_bf16_f32 v54, v134, v135
	v_cvt_pk_bf16_f32 v55, v136, v137
	v_cvt_pk_bf16_f32 v56, v138, v139
	v_cvt_pk_bf16_f32 v57, v140, v141
	v_exp_f32_e32 v58, v38
	v_exp_f32_e32 v59, v39
	v_mfma_f32_32x32x16_bf16 v[20:35], v[80:83], v[54:57], v[20:35]
	v_add_f32_e64 v38, v40, -v2
	v_add_f32_e64 v39, v41, -v2
	v_exp_f32_e32 v53, v119
	v_exp_f32_e32 v118, v38
	v_exp_f32_e32 v119, v39
	v_sub_f32_e32 v38, v42, v2
	v_sub_f32_e32 v39, v43, v2
	v_add_f32_e32 v36, v52, v36
	v_add_f32_e32 v37, v53, v37
	v_exp_f32_e32 v42, v38
	s_waitcnt lgkmcnt(2)
	v_mfma_f32_32x32x16_bf16 v[4:19], v[76:79], v[54:57], v[4:19]
	v_exp_f32_e32 v43, v39
	v_cvt_pk_bf16_f32 v38, v52, v53
	v_cvt_pk_bf16_f32 v39, v58, v59
	v_cvt_pk_bf16_f32 v40, v118, v119
	v_cvt_pk_bf16_f32 v41, v42, v43
	v_pk_add_f32 v[36:37], v[36:37], 0 op_sel_hi:[1,0]
	v_add_f32_e32 v120, v58, v120
	v_add_f32_e32 v121, v59, v121
	v_mfma_f32_32x32x16_bf16 v[20:35], v[72:75], v[38:41], v[20:35]
	v_add_f32_e64 v36, v120, v36
	v_add_f32_e64 v37, v121, v37
	v_add_f32_e64 v50, v50, -v2
	v_add_f32_e64 v51, v51, -v2
	v_mfma_f32_32x32x16_bf16 v[4:19], v[68:71], v[38:41], v[4:19]
	ds_read_b128 v[38:41], v128 offset:18432
	ds_read_b128 v[100:103], v128 offset:18464
	ds_read_b128 v[108:111], v128 offset:23072
	s_waitcnt lgkmcnt(2)
	v_mfma_f32_32x32x16_bf16 v[68:83], v[38:41], v[96:99], 0
	ds_read_b128 v[38:41], v128 offset:23040
	s_waitcnt lgkmcnt(0)
	v_mfma_f32_32x32x16_bf16 v[52:67], v[38:41], v[96:99], 0
	v_add_f32_e64 v38, v118, v122
	v_add_f32_e64 v39, v119, v123
	v_add_f32_e64 v40, v46, -v2
	v_add_f32_e64 v41, v47, -v2
	v_add_f32_e64 v36, v38, v36
	v_add_f32_e64 v37, v39, v37
	v_sub_f32_e32 v38, v44, v2
	v_sub_f32_e32 v39, v45, v2
	v_exp_f32_e32 v120, v40
	v_exp_f32_e32 v118, v38
	v_exp_f32_e32 v119, v39
	v_add_f32_e32 v38, v42, v132
	v_add_f32_e32 v39, v43, v133
	v_mfma_f32_32x32x16_bf16 v[68:83], v[100:103], v[92:95], v[68:83]
	v_add_f32_e64 v36, v38, v36
	v_add_f32_e64 v37, v39, v37
	v_add_f32_e64 v38, v118, v134
	v_add_f32_e64 v39, v119, v135
	v_exp_f32_e32 v121, v41
	v_add_f32_e32 v100, v38, v36
	v_add_f32_e32 v101, v39, v37
	ds_read_b128 v[36:39], v128 offset:18496
	v_sub_f32_e32 v40, v48, v2
	v_sub_f32_e32 v41, v49, v2
	v_add_f32_e32 v102, v120, v136
	v_add_f32_e32 v103, v121, v137
	v_mfma_f32_32x32x16_bf16 v[52:67], v[108:111], v[92:95], v[52:67]
	v_exp_f32_e32 v48, v40
	v_exp_f32_e32 v49, v41
	ds_read_b128 v[40:43], v128 offset:23104
	ds_read_b128 v[44:47], v128 offset:18528
	v_cvt_pk_bf16_f32 v132, v118, v119
	v_cvt_pk_bf16_f32 v133, v120, v121
	v_cvt_pk_bf16_f32 v134, v48, v49
	s_waitcnt lgkmcnt(2)
	v_mfma_f32_32x32x16_bf16 v[68:83], v[36:39], v[88:91], v[68:83]
	v_add_f32_e64 v38, v102, v100
	v_add_f32_e64 v39, v103, v101
	ds_read_b128 v[100:103], v128 offset:23136
	v_exp_f32_e32 v36, v50
	v_exp_f32_e32 v37, v51
	v_add_f32_e32 v50, v48, v138
	v_add_f32_e32 v51, v49, v139
	v_cvt_pk_bf16_f32 v135, v36, v37
	s_waitcnt lgkmcnt(2)
	v_mfma_f32_32x32x16_bf16 v[52:67], v[40:43], v[88:91], v[52:67]
	v_add_f32_e64 v38, v50, v38
	v_add_f32_e64 v39, v51, v39
	v_add_f32_e64 v50, v36, v140
	v_add_f32_e64 v51, v37, v141
	v_add_f32_e64 v38, v50, v38
	v_add_f32_e64 v39, v51, v39
	v_add_f32_e32 v0, v38, v39
	v_add_f32_e32 v131, v116, v0
	s_waitcnt lgkmcnt(1)
	v_mfma_f32_32x32x16_bf16 v[68:83], v[44:47], v[84:87], v[68:83]
	ds_read2_b64 v[120:123], v129 offset0:32 offset1:34
	ds_read2_b64 v[48:51], v129 offset0:36 offset1:38
	ds_read2_b64 v[116:119], v130 offset0:64 offset1:66
	ds_read2_b64 v[40:43], v129 offset0:40 offset1:42
	ds_read2_b64 v[36:39], v130 offset0:72 offset1:74
	ds_read2_b64 v[44:47], v130 offset0:68 offset1:70
	ds_read2_b64 v[108:111], v129 offset0:44 offset1:46
	s_waitcnt lgkmcnt(7)
	v_mfma_f32_32x32x16_bf16 v[52:67], v[100:103], v[84:87], v[52:67]
	ds_read2_b64 v[100:103], v130 offset0:76 offset1:78
	v_mfma_f32_32x32x16_bf16 v[20:35], v[112:115], v[132:135], v[20:35]
	s_nop 9
	v_maximum3_f32 v0, v69, v53, v53
	v_maximum3_f32 v0, v68, v52, v0
	v_maximum3_f32 v1, v70, v54, v54
	v_maximum3_f32 v136, v71, v55, v55
	v_maximum3_f32 v0, v0, v1, v136
	v_maximum3_f32 v1, v72, v56, v56
	v_maximum3_f32 v112, v73, v57, v57
	v_maximum3_f32 v0, v0, v1, v112
	v_maximum3_f32 v1, v74, v58, v58
	v_maximum3_f32 v112, v75, v59, v59
	v_maximum3_f32 v0, v0, v1, v112
	v_maximum3_f32 v1, v76, v60, v60
	v_maximum3_f32 v112, v77, v61, v61
	v_mfma_f32_32x32x16_bf16 v[4:19], v[104:107], v[132:135], v[4:19]
	v_maximum3_f32 v0, v0, v1, v112
	v_maximum3_f32 v1, v78, v62, v62
	v_maximum3_f32 v104, v79, v63, v63
	v_maximum3_f32 v0, v0, v1, v104
	v_maximum3_f32 v1, v80, v64, v64
	v_maximum3_f32 v104, v81, v65, v65
	v_maximum3_f32 v0, v0, v1, v104
	v_maximum3_f32 v1, v82, v66, v66
	v_maximum3_f32 v104, v83, v67, v67
	v_maximum3_f32 v0, v0, v1, v104
	v_mov_b32_e32 v1, v0
	s_nop 1
	v_permlane32_swap_b32_e32 v0, v1
	s_nop 0
	v_maximum3_f32 v104, v0, v1, v1
	v_cmp_gt_f32_e32 vcc, v104, v2
	s_cbranch_vccz .LBB0_886
	v_maximum3_f32 v0, v2, v104, v104
	v_sub_f32_e32 v1, v2, v0
	v_exp_f32_e32 v2, v1
	s_nop 0
	v_mul_f32_e32 v131, v131, v2
	v_pk_mul_f32 v[34:35], v[34:35], v[2:3] op_sel_hi:[1,0]
	v_pk_mul_f32 v[32:33], v[32:33], v[2:3] op_sel_hi:[1,0]
	v_pk_mul_f32 v[30:31], v[30:31], v[2:3] op_sel_hi:[1,0]
	v_pk_mul_f32 v[28:29], v[28:29], v[2:3] op_sel_hi:[1,0]
	v_pk_mul_f32 v[26:27], v[26:27], v[2:3] op_sel_hi:[1,0]
	v_pk_mul_f32 v[24:25], v[24:25], v[2:3] op_sel_hi:[1,0]
	v_pk_mul_f32 v[22:23], v[22:23], v[2:3] op_sel_hi:[1,0]
	v_pk_mul_f32 v[20:21], v[20:21], v[2:3] op_sel_hi:[1,0]
	v_pk_mul_f32 v[18:19], v[18:19], v[2:3] op_sel_hi:[1,0]
	v_pk_mul_f32 v[16:17], v[16:17], v[2:3] op_sel_hi:[1,0]
	v_pk_mul_f32 v[14:15], v[14:15], v[2:3] op_sel_hi:[1,0]
	v_pk_mul_f32 v[12:13], v[12:13], v[2:3] op_sel_hi:[1,0]
	v_pk_mul_f32 v[10:11], v[10:11], v[2:3] op_sel_hi:[1,0]
	v_pk_mul_f32 v[8:9], v[8:9], v[2:3] op_sel_hi:[1,0]
	v_pk_mul_f32 v[6:7], v[6:7], v[2:3] op_sel_hi:[1,0]
	v_pk_mul_f32 v[4:5], v[4:5], v[2:3] op_sel_hi:[1,0]
	v_mov_b32_e32 v2, v0
.LBB0_886:
	v_sub_f32_e32 v68, v68, v2
	v_sub_f32_e32 v69, v69, v2
	v_sub_f32_e32 v104, v52, v2
	v_sub_f32_e32 v105, v53, v2
	v_exp_f32_e32 v52, v68
	v_exp_f32_e32 v53, v69
	v_sub_f32_e32 v68, v70, v2
	v_sub_f32_e32 v69, v71, v2
	v_exp_f32_e32 v104, v104
	v_exp_f32_e32 v106, v68
	v_exp_f32_e32 v107, v69
	v_sub_f32_e32 v68, v72, v2
	v_sub_f32_e32 v69, v73, v2
	v_sub_f32_e32 v72, v76, v2
	v_sub_f32_e32 v73, v77, v2
	v_exp_f32_e32 v112, v68
	v_exp_f32_e32 v113, v69
	v_sub_f32_e32 v68, v74, v2
	v_sub_f32_e32 v69, v75, v2
	v_exp_f32_e32 v132, v72
	v_exp_f32_e32 v114, v68
	v_exp_f32_e32 v115, v69
	v_cvt_pk_bf16_f32 v68, v52, v53
	v_cvt_pk_bf16_f32 v69, v106, v107
	v_cvt_pk_bf16_f32 v70, v112, v113
	v_cvt_pk_bf16_f32 v71, v114, v115
	v_exp_f32_e32 v133, v73
	v_sub_f32_e32 v72, v78, v2
	v_sub_f32_e32 v73, v79, v2
	s_waitcnt lgkmcnt(5)
	v_mfma_f32_32x32x16_bf16 v[4:19], v[116:119], v[68:71], v[4:19]
	v_exp_f32_e32 v105, v105
	v_sub_f32_e32 v60, v60, v2
	v_sub_f32_e32 v61, v61, v2
	v_sub_f32_e32 v66, v66, v2
	v_sub_f32_e32 v67, v67, v2
	s_nop 0
	v_exp_f32_e32 v66, v66
	v_exp_f32_e32 v67, v67
	v_mfma_f32_32x32x16_bf16 v[20:35], v[120:123], v[68:71], v[20:35]
	v_exp_f32_e32 v120, v72
	v_exp_f32_e32 v121, v73
	v_sub_f32_e32 v72, v80, v2
	v_sub_f32_e32 v73, v81, v2
	v_sub_f32_e32 v68, v82, v2
	v_sub_f32_e32 v69, v83, v2
	v_exp_f32_e32 v122, v72
	v_exp_f32_e32 v123, v73
	v_exp_f32_e32 v116, v68
	v_exp_f32_e32 v117, v69
	v_cvt_pk_bf16_f32 v68, v132, v133
	v_cvt_pk_bf16_f32 v69, v120, v121
	v_cvt_pk_bf16_f32 v70, v122, v123
	v_cvt_pk_bf16_f32 v71, v116, v117
	s_waitcnt lgkmcnt(2)
	s_nop 0
	v_mfma_f32_32x32x16_bf16 v[4:19], v[44:47], v[68:71], v[4:19]
	v_add_f32_e64 v44, v58, -v2
	v_add_f32_e64 v45, v59, -v2
	v_exp_f32_e32 v58, v44
	v_exp_f32_e32 v59, v45
	v_cvt_pk_bf16_f32 v44, v104, v105
	v_cvt_pk_bf16_f32 v47, v58, v59
	v_mfma_f32_32x32x16_bf16 v[20:35], v[48:51], v[68:71], v[20:35]
	v_add_f32_e64 v48, v54, -v2
	v_add_f32_e64 v49, v55, -v2
	v_add_f32_e64 v50, v56, -v2
	v_add_f32_e64 v51, v57, -v2
	v_exp_f32_e32 v48, v48
	v_exp_f32_e32 v49, v49
	v_exp_f32_e32 v118, v50
	v_exp_f32_e32 v119, v51
	v_add_f32_e32 v58, v58, v114
	v_add_f32_e32 v59, v59, v115
	v_cvt_pk_bf16_f32 v45, v48, v49
	v_add_f32_e32 v134, v48, v106
	v_add_f32_e32 v135, v49, v107
	v_cvt_pk_bf16_f32 v46, v118, v119
	s_nop 1
	v_mfma_f32_32x32x16_bf16 v[4:19], v[36:39], v[44:47], v[4:19]
	ds_read_b128 v[36:39], v128 offset:27648
	ds_read_b128 v[54:57], v128 offset:27680
	s_waitcnt lgkmcnt(1)
	v_mfma_f32_32x32x16_bf16 v[68:83], v[36:39], v[96:99], 0
	ds_read_b128 v[36:39], v128 offset:32256
	v_mfma_f32_32x32x16_bf16 v[20:35], v[40:43], v[44:47], v[20:35]
	v_add_f32_e64 v40, v104, v52
	v_add_f32_e64 v41, v105, v53
	ds_read_b128 v[104:107], v128 offset:32288
	v_add_f32_e64 v52, v40, 0
	v_add_f32_e64 v53, v41, 0
	v_add_f32_e32 v52, v134, v52
	v_add_f32_e32 v53, v135, v53
	s_waitcnt lgkmcnt(1)
	v_mfma_f32_32x32x16_bf16 v[36:51], v[36:39], v[96:99], 0
	v_add_f32_e64 v96, v118, v112
	v_add_f32_e64 v97, v119, v113
	v_add_f32_e64 v52, v96, v52
	v_add_f32_e64 v53, v97, v53
	v_exp_f32_e32 v96, v60
	v_exp_f32_e32 v97, v61
	v_add_f32_e32 v52, v58, v52
	v_add_f32_e32 v53, v59, v53
	v_cvt_pk_bf16_f32 v114, v96, v97
	v_mfma_f32_32x32x16_bf16 v[68:83], v[54:57], v[92:95], v[68:83]
	v_add_f32_e64 v54, v96, v132
	v_add_f32_e64 v55, v97, v133
	v_add_f32_e64 v56, v62, -v2
	v_add_f32_e64 v57, v63, -v2
	v_add_f32_e64 v112, v54, v52
	v_add_f32_e64 v113, v55, v53
	ds_read_b128 v[52:55], v128 offset:27712
	v_exp_f32_e32 v98, v56
	v_exp_f32_e32 v99, v57
	v_sub_f32_e32 v56, v64, v2
	v_sub_f32_e32 v57, v65, v2
	s_waitcnt lgkmcnt(1)
	v_mfma_f32_32x32x16_bf16 v[36:51], v[104:107], v[92:95], v[36:51]
	v_exp_f32_e32 v64, v56
	v_exp_f32_e32 v65, v57
	ds_read_b128 v[56:59], v128 offset:32320
	ds_read_b128 v[60:63], v128 offset:27744
	v_add_f32_e32 v92, v98, v120
	v_add_f32_e32 v93, v99, v121
	v_add_f32_e32 v94, v66, v116
	v_add_f32_e32 v95, v67, v117
	v_cvt_pk_bf16_f32 v115, v98, v99
	v_cvt_pk_bf16_f32 v116, v64, v65
	s_waitcnt lgkmcnt(2)
	v_mfma_f32_32x32x16_bf16 v[68:83], v[52:55], v[88:91], v[68:83]
	v_add_f32_e64 v52, v92, v112
	v_add_f32_e64 v53, v93, v113
	v_add_f32_e64 v54, v64, v122
	v_add_f32_e64 v55, v65, v123
	v_cvt_pk_bf16_f32 v117, v66, v67
	v_add_f32_e32 v92, v54, v52
	v_add_f32_e32 v93, v55, v53
	ds_read_b128 v[52:55], v128 offset:32352
	s_waitcnt lgkmcnt(2)
	v_mfma_f32_32x32x16_bf16 v[36:51], v[56:59], v[88:91], v[36:51]
	v_add_f32_e64 v56, v94, v92
	v_add_f32_e64 v57, v95, v93
	v_add_f32_e32 v0, v56, v57
	v_add_f32_e32 v112, v131, v0
	s_waitcnt lgkmcnt(1)
	v_mfma_f32_32x32x16_bf16 v[68:83], v[60:63], v[84:87], v[68:83]
	ds_read2_b64 v[104:107], v129 offset0:48 offset1:50
	ds_read2_b64 v[92:95], v129 offset0:52 offset1:54
	ds_read2_b64 v[96:99], v130 offset0:80 offset1:82
	ds_read2_b64 v[64:67], v129 offset0:56 offset1:58
	ds_read2_b64 v[60:63], v130 offset0:88 offset1:90
	ds_read2_b64 v[88:91], v130 offset0:84 offset1:86
	ds_read2_b64 v[56:59], v129 offset0:60 offset1:62
	s_waitcnt lgkmcnt(7)
	v_mfma_f32_32x32x16_bf16 v[36:51], v[52:55], v[84:87], v[36:51]
	ds_read2_b64 v[52:55], v130 offset0:92 offset1:94
	v_mfma_f32_32x32x16_bf16 v[20:35], v[108:111], v[114:117], v[20:35]
	s_nop 9
	v_maximum3_f32 v0, v69, v37, v37
	v_maximum3_f32 v0, v68, v36, v0
	v_maximum3_f32 v1, v70, v38, v38
	v_maximum3_f32 v84, v71, v39, v39
	v_maximum3_f32 v0, v0, v1, v84
	v_maximum3_f32 v1, v72, v40, v40
	v_maximum3_f32 v84, v73, v41, v41
	v_maximum3_f32 v0, v0, v1, v84
	v_maximum3_f32 v1, v74, v42, v42
	v_maximum3_f32 v84, v75, v43, v43
	v_maximum3_f32 v0, v0, v1, v84
	v_maximum3_f32 v1, v76, v44, v44
	v_maximum3_f32 v84, v77, v45, v45
	v_maximum3_f32 v0, v0, v1, v84
	v_maximum3_f32 v1, v78, v46, v46
	v_maximum3_f32 v84, v79, v47, v47
	v_mfma_f32_32x32x16_bf16 v[4:19], v[100:103], v[114:117], v[4:19]
	v_maximum3_f32 v0, v0, v1, v84
	v_maximum3_f32 v1, v80, v48, v48
	v_maximum3_f32 v84, v81, v49, v49
	v_maximum3_f32 v0, v0, v1, v84
	v_maximum3_f32 v1, v82, v50, v50
	v_maximum3_f32 v84, v83, v51, v51
	v_maximum3_f32 v0, v0, v1, v84
	v_mov_b32_e32 v1, v0
	s_nop 1
	v_permlane32_swap_b32_e32 v0, v1
	s_nop 0
	v_maximum3_f32 v84, v0, v1, v1
	v_cmp_gt_f32_e32 vcc, v84, v2
	s_cbranch_vccz .LBB0_888
	v_maximum3_f32 v0, v2, v84, v84
	v_sub_f32_e32 v1, v2, v0
	v_exp_f32_e32 v2, v1
	s_nop 0
	v_mul_f32_e32 v112, v112, v2
	v_pk_mul_f32 v[34:35], v[34:35], v[2:3] op_sel_hi:[1,0]
	v_pk_mul_f32 v[32:33], v[32:33], v[2:3] op_sel_hi:[1,0]
	v_pk_mul_f32 v[30:31], v[30:31], v[2:3] op_sel_hi:[1,0]
	v_pk_mul_f32 v[28:29], v[28:29], v[2:3] op_sel_hi:[1,0]
	v_pk_mul_f32 v[26:27], v[26:27], v[2:3] op_sel_hi:[1,0]
	v_pk_mul_f32 v[24:25], v[24:25], v[2:3] op_sel_hi:[1,0]
	v_pk_mul_f32 v[22:23], v[22:23], v[2:3] op_sel_hi:[1,0]
	v_pk_mul_f32 v[20:21], v[20:21], v[2:3] op_sel_hi:[1,0]
	v_pk_mul_f32 v[18:19], v[18:19], v[2:3] op_sel_hi:[1,0]
	v_pk_mul_f32 v[16:17], v[16:17], v[2:3] op_sel_hi:[1,0]
	v_pk_mul_f32 v[14:15], v[14:15], v[2:3] op_sel_hi:[1,0]
	v_pk_mul_f32 v[12:13], v[12:13], v[2:3] op_sel_hi:[1,0]
	v_pk_mul_f32 v[10:11], v[10:11], v[2:3] op_sel_hi:[1,0]
	v_pk_mul_f32 v[8:9], v[8:9], v[2:3] op_sel_hi:[1,0]
	v_pk_mul_f32 v[6:7], v[6:7], v[2:3] op_sel_hi:[1,0]
	v_pk_mul_f32 v[4:5], v[4:5], v[2:3] op_sel_hi:[1,0]
	v_mov_b32_e32 v2, v0
.LBB0_888:
	v_sub_f32_e32 v68, v68, v2
	v_sub_f32_e32 v69, v69, v2
	v_sub_f32_e32 v36, v36, v2
	v_sub_f32_e32 v37, v37, v2
	v_exp_f32_e32 v68, v68
	v_exp_f32_e32 v69, v69
	v_exp_f32_e32 v84, v36
	v_exp_f32_e32 v85, v37
	v_sub_f32_e32 v36, v70, v2
	v_sub_f32_e32 v37, v71, v2
	v_sub_f32_e32 v38, v38, v2
	v_sub_f32_e32 v39, v39, v2
	v_exp_f32_e32 v70, v36
	v_exp_f32_e32 v71, v37
	v_exp_f32_e32 v86, v38
	v_exp_f32_e32 v87, v39
	v_sub_f32_e32 v72, v72, v2
	v_sub_f32_e32 v73, v73, v2
	v_sub_f32_e32 v40, v40, v2
	v_sub_f32_e32 v41, v41, v2
	v_exp_f32_e32 v72, v72
	v_exp_f32_e32 v73, v73
	v_exp_f32_e32 v40, v40
	v_exp_f32_e32 v41, v41
	v_sub_f32_e32 v74, v74, v2
	v_sub_f32_e32 v75, v75, v2
	v_add_f32_e32 v36, v84, v68
	v_add_f32_e32 v37, v85, v69
	v_exp_f32_e32 v74, v74
	v_exp_f32_e32 v75, v75
	v_pk_add_f32 v[36:37], v[36:37], 0 op_sel_hi:[1,0]
	v_add_f32_e32 v38, v86, v70
	v_add_f32_e32 v39, v87, v71
	v_sub_f32_e32 v42, v42, v2
	v_sub_f32_e32 v43, v43, v2
	v_add_f32_e32 v36, v38, v36
	v_add_f32_e32 v37, v39, v37
	v_add_f32_e32 v38, v40, v72
	v_add_f32_e32 v39, v41, v73
	v_exp_f32_e32 v42, v42
	v_add_f32_e32 v100, v38, v36
	v_add_f32_e32 v101, v39, v37
	v_sub_f32_e32 v36, v76, v2
	v_sub_f32_e32 v37, v77, v2
	v_cvt_pk_bf16_f32 v38, v72, v73
	v_exp_f32_e32 v76, v36
	v_exp_f32_e32 v77, v37
	v_cvt_pk_bf16_f32 v36, v68, v69
	v_cvt_pk_bf16_f32 v37, v70, v71
	v_cvt_pk_bf16_f32 v39, v74, v75
	v_sub_f32_e32 v68, v78, v2
	v_sub_f32_e32 v69, v79, v2
	v_sub_f32_e32 v70, v80, v2
	v_sub_f32_e32 v71, v81, v2
	s_waitcnt lgkmcnt(7)
	v_mfma_f32_32x32x16_bf16 v[20:35], v[104:107], v[36:39], v[20:35]
	v_exp_f32_e32 v68, v68
	v_exp_f32_e32 v69, v69
	v_exp_f32_e32 v70, v70
	v_exp_f32_e32 v71, v71
	v_exp_f32_e32 v43, v43
	v_sub_f32_e32 v44, v44, v2
	v_sub_f32_e32 v45, v45, v2
	v_sub_f32_e32 v46, v46, v2
	v_sub_f32_e32 v47, v47, v2
	s_waitcnt lgkmcnt(5)
	v_mfma_f32_32x32x16_bf16 v[4:19], v[96:99], v[36:39], v[4:19]
	v_add_f32_e64 v36, v82, -v2
	v_add_f32_e64 v37, v83, -v2
	v_cvt_pk_bf16_f32 v38, v70, v71
	v_exp_f32_e32 v72, v36
	v_exp_f32_e32 v73, v37
	v_cvt_pk_bf16_f32 v36, v76, v77
	v_cvt_pk_bf16_f32 v37, v68, v69
	v_exp_f32_e32 v44, v44
	v_cvt_pk_bf16_f32 v39, v72, v73
	v_exp_f32_e32 v45, v45
	v_exp_f32_e32 v46, v46
	v_mfma_f32_32x32x16_bf16 v[20:35], v[92:95], v[36:39], v[20:35]
	v_exp_f32_e32 v47, v47
	v_add_f32_e32 v102, v42, v74
	v_add_f32_e32 v103, v43, v75
	v_add_f32_e32 v76, v44, v76
	v_add_f32_e32 v77, v45, v77
	v_add_f32_e32 v74, v102, v100
	v_add_f32_e32 v75, v103, v101
	v_add_f32_e32 v68, v46, v68
	v_add_f32_e32 v69, v47, v69
	v_add_f32_e32 v74, v76, v74
	v_add_f32_e32 v75, v77, v75
	v_lshlrev_b32_e32 v1, 2, v127
	s_waitcnt lgkmcnt(2)
	v_mfma_f32_32x32x16_bf16 v[4:19], v[88:91], v[36:39], v[4:19]
	v_add_f32_e64 v36, v48, -v2
	v_add_f32_e64 v37, v49, -v2
	v_cvt_pk_bf16_f32 v38, v40, v41
	v_exp_f32_e32 v48, v36
	v_exp_f32_e32 v49, v37
	v_sub_f32_e32 v40, v50, v2
	v_sub_f32_e32 v41, v51, v2
	v_cvt_pk_bf16_f32 v39, v42, v43
	v_exp_f32_e32 v40, v40
	v_exp_f32_e32 v41, v41
	v_add_f32_e32 v42, v68, v74
	v_add_f32_e32 v43, v69, v75
	v_add_f32_e32 v50, v48, v70
	v_add_f32_e32 v51, v49, v71
	v_cvt_pk_bf16_f32 v36, v84, v85
	v_cvt_pk_bf16_f32 v37, v86, v87
	v_add_f32_e32 v42, v50, v42
	v_add_f32_e32 v43, v51, v43
	v_add_f32_e32 v50, v40, v72
	v_add_f32_e32 v51, v41, v73
	v_mfma_f32_32x32x16_bf16 v[20:35], v[64:67], v[36:39], v[20:35]
	v_xor_b32_e32 v1, 0x80, v1
	v_mfma_f32_32x32x16_bf16 v[4:19], v[60:63], v[36:39], v[4:19]
	v_add_f32_e64 v36, v50, v42
	v_add_f32_e64 v37, v51, v43
	v_cvt_pk_bf16_f32 v38, v48, v49
	v_add_f32_e32 v0, v36, v37
	v_add_f32_e32 v0, v112, v0
	ds_bpermute_b32 v1, v1, v0
	v_cvt_pk_bf16_f32 v36, v44, v45
	v_cvt_pk_bf16_f32 v37, v46, v47
	v_cvt_pk_bf16_f32 v39, v40, v41
	s_waitcnt lgkmcnt(0)
	v_add_f32_e32 v0, v0, v1
	v_div_scale_f32 v1, s[4:5], v0, v0, 1.0
	v_rcp_f32_e32 v2, v1
	v_mfma_f32_32x32x16_bf16 v[20:35], v[56:59], v[36:39], v[20:35]
	s_lshl_b32 s4, s8, 6
	s_lshl_b32 s20, s4, 1
	v_mfma_f32_32x32x16_bf16 v[4:19], v[52:55], v[36:39], v[4:19]
	v_fma_f32 v36, -v1, v2, 1.0
	v_fmac_f32_e32 v2, v36, v2
	v_div_scale_f32 v36, vcc, 1.0, v0, 1.0
	v_mul_f32_e32 v37, v36, v2
	v_fma_f32 v38, -v1, v37, v36
	v_fmac_f32_e32 v37, v38, v2
	v_fma_f32 v1, -v1, v37, v36
	v_div_fmas_f32 v1, v1, v2, v37
	v_div_fixup_f32 v36, v1, v0, 1.0
	v_lshlrev_b64 v[38:39], 12, v[124:125]
	v_pk_mul_f32 v[20:21], v[20:21], v[36:37] op_sel_hi:[1,0]
	v_pk_mul_f32 v[22:23], v[22:23], v[36:37] op_sel_hi:[1,0]
	v_pk_mul_f32 v[6:7], v[6:7], v[36:37] op_sel_hi:[1,0]
	v_lshl_add_u64 v[38:39], s[70:71], 0, v[38:39]
	v_pk_mul_f32 v[40:41], v[4:5], v[36:37] op_sel_hi:[1,0]
	v_cvt_pk_bf16_f32 v4, v20, v21
	v_cvt_pk_bf16_f32 v5, v22, v23
	v_cvt_pk_bf16_f32 v21, v6, v7
	v_pk_mul_f32 v[6:7], v[24:25], v[36:37] op_sel_hi:[1,0]
	v_pk_mul_f32 v[22:23], v[26:27], v[36:37] op_sel_hi:[1,0]
	v_lshl_add_u64 v[38:39], v[38:39], 0, s[20:21]
	v_lshlrev_b32_e32 v2, 1, v126
	v_cvt_pk_bf16_f32 v6, v6, v7
	v_cvt_pk_bf16_f32 v7, v22, v23
	v_lshl_add_u64 v[38:39], v[38:39], 0, v[2:3]
	v_pk_mul_f32 v[8:9], v[8:9], v[36:37] op_sel_hi:[1,0]
	v_pk_mul_f32 v[10:11], v[10:11], v[36:37] op_sel_hi:[1,0]
	v_permlane32_swap_b32_e32 v4, v6
	v_permlane32_swap_b32_e32 v5, v7
	v_cvt_pk_bf16_f32 v22, v8, v9
	v_cvt_pk_bf16_f32 v23, v10, v11
	global_store_dwordx4 v[38:39], v[4:7], off
	v_pk_mul_f32 v[8:9], v[12:13], v[36:37] op_sel_hi:[1,0]
	v_pk_mul_f32 v[10:11], v[14:15], v[36:37] op_sel_hi:[1,0]
	v_pk_mul_f32 v[4:5], v[28:29], v[36:37] op_sel_hi:[1,0]
	v_pk_mul_f32 v[6:7], v[30:31], v[36:37] op_sel_hi:[1,0]
	v_cvt_pk_bf16_f32 v4, v4, v5
	v_cvt_pk_bf16_f32 v5, v6, v7
	v_cvt_pk_bf16_f32 v8, v8, v9
	v_cvt_pk_bf16_f32 v9, v10, v11
	v_pk_mul_f32 v[6:7], v[32:33], v[36:37] op_sel_hi:[1,0]
	v_pk_mul_f32 v[10:11], v[34:35], v[36:37] op_sel_hi:[1,0]
	v_pk_mul_f32 v[12:13], v[16:17], v[36:37] op_sel_hi:[1,0]
	v_pk_mul_f32 v[14:15], v[18:19], v[36:37] op_sel_hi:[1,0]
	v_cvt_pk_bf16_f32 v20, v40, v41
	v_cvt_pk_bf16_f32 v6, v6, v7
	v_cvt_pk_bf16_f32 v7, v10, v11
	v_cvt_pk_bf16_f32 v10, v12, v13
	v_cvt_pk_bf16_f32 v11, v14, v15
	v_permlane32_swap_b32_e32 v20, v22
	v_permlane32_swap_b32_e32 v21, v23
	v_permlane32_swap_b32_e32 v4, v6
	v_permlane32_swap_b32_e32 v5, v7
	v_permlane32_swap_b32_e32 v8, v10
	v_permlane32_swap_b32_e32 v9, v11
	global_store_dwordx4 v[38:39], v[20:23], off offset:64
	global_store_dwordx4 v[38:39], v[4:7], off offset:32
	global_store_dwordx4 v[38:39], v[8:11], off offset:96

.LBB0_908:
	v_sub_f32_e32 v68, v68, v2
	v_sub_f32_e32 v69, v69, v2
	v_sub_f32_e32 v52, v52, v2
	v_sub_f32_e32 v53, v53, v2
	v_exp_f32_e32 v68, v68
	v_exp_f32_e32 v69, v69
	v_exp_f32_e32 v84, v52
	v_exp_f32_e32 v85, v53
	v_sub_f32_e32 v52, v70, v2
	v_sub_f32_e32 v53, v71, v2
	v_sub_f32_e32 v54, v54, v2
	v_sub_f32_e32 v55, v55, v2
	v_exp_f32_e32 v70, v52
	v_exp_f32_e32 v71, v53
	v_exp_f32_e32 v86, v54
	v_exp_f32_e32 v87, v55
	v_sub_f32_e32 v72, v72, v2
	v_sub_f32_e32 v73, v73, v2
	v_sub_f32_e32 v56, v56, v2
	v_sub_f32_e32 v57, v57, v2
	v_exp_f32_e32 v72, v72
	v_exp_f32_e32 v73, v73
	v_exp_f32_e32 v56, v56
	v_exp_f32_e32 v57, v57
	v_sub_f32_e32 v74, v74, v2
	v_sub_f32_e32 v75, v75, v2
	v_add_f32_e32 v52, v84, v68
	v_add_f32_e32 v53, v85, v69
	v_exp_f32_e32 v74, v74
	v_exp_f32_e32 v75, v75
	v_pk_add_f32 v[52:53], v[52:53], 0 op_sel_hi:[1,0]
	v_add_f32_e32 v54, v86, v70
	v_add_f32_e32 v55, v87, v71
	v_sub_f32_e32 v58, v58, v2
	v_sub_f32_e32 v59, v59, v2
	v_add_f32_e32 v52, v54, v52
	v_add_f32_e32 v53, v55, v53
	v_add_f32_e32 v54, v56, v72
	v_add_f32_e32 v55, v57, v73
	v_exp_f32_e32 v58, v58
	v_add_f32_e32 v100, v54, v52
	v_add_f32_e32 v101, v55, v53
	v_sub_f32_e32 v52, v76, v2
	v_sub_f32_e32 v53, v77, v2
	v_cvt_pk_bf16_f32 v54, v72, v73
	v_exp_f32_e32 v76, v52
	v_exp_f32_e32 v77, v53
	v_cvt_pk_bf16_f32 v52, v68, v69
	v_cvt_pk_bf16_f32 v53, v70, v71
	v_cvt_pk_bf16_f32 v55, v74, v75
	v_sub_f32_e32 v68, v78, v2
	v_sub_f32_e32 v69, v79, v2
	v_sub_f32_e32 v70, v80, v2
	v_sub_f32_e32 v71, v81, v2
	s_waitcnt lgkmcnt(7)
	v_mfma_f32_32x32x16_bf16 v[20:35], v[108:111], v[52:55], v[20:35]
	v_exp_f32_e32 v68, v68
	v_exp_f32_e32 v69, v69
	v_exp_f32_e32 v70, v70
	v_exp_f32_e32 v71, v71
	v_exp_f32_e32 v59, v59
	v_sub_f32_e32 v60, v60, v2
	v_sub_f32_e32 v61, v61, v2
	v_sub_f32_e32 v62, v62, v2
	v_sub_f32_e32 v63, v63, v2
	s_waitcnt lgkmcnt(5)
	v_mfma_f32_32x32x16_bf16 v[4:19], v[96:99], v[52:55], v[4:19]
	v_add_f32_e64 v52, v82, -v2
	v_add_f32_e64 v53, v83, -v2
	v_cvt_pk_bf16_f32 v54, v70, v71
	v_exp_f32_e32 v72, v52
	v_exp_f32_e32 v73, v53
	v_cvt_pk_bf16_f32 v52, v76, v77
	v_cvt_pk_bf16_f32 v53, v68, v69
	v_exp_f32_e32 v60, v60
	v_cvt_pk_bf16_f32 v55, v72, v73
	v_exp_f32_e32 v61, v61
	v_exp_f32_e32 v62, v62
	v_mfma_f32_32x32x16_bf16 v[20:35], v[92:95], v[52:55], v[20:35]
	v_exp_f32_e32 v63, v63
	v_add_f32_e32 v102, v58, v74
	v_add_f32_e32 v103, v59, v75
	v_add_f32_e32 v76, v60, v76
	v_add_f32_e32 v77, v61, v77
	v_add_f32_e32 v74, v102, v100
	v_add_f32_e32 v75, v103, v101
	v_add_f32_e32 v68, v62, v68
	v_add_f32_e32 v69, v63, v69
	v_add_f32_e32 v74, v76, v74
	v_add_f32_e32 v75, v77, v75
	v_and_b32_e32 v0, 63, v128
	s_waitcnt lgkmcnt(2)
	v_mfma_f32_32x32x16_bf16 v[4:19], v[88:91], v[52:55], v[4:19]
	v_add_f32_e64 v52, v64, -v2
	v_add_f32_e64 v53, v65, -v2
	v_cvt_pk_bf16_f32 v54, v56, v57
	v_exp_f32_e32 v64, v52
	v_exp_f32_e32 v65, v53
	v_cvt_pk_bf16_f32 v52, v84, v85
	v_cvt_pk_bf16_f32 v53, v86, v87
	v_cvt_pk_bf16_f32 v55, v58, v59
	v_add_f32_e32 v56, v64, v70
	v_add_f32_e32 v57, v65, v71
	v_lshlrev_b32_e32 v0, 2, v0
	v_mfma_f32_32x32x16_bf16 v[20:35], v[48:51], v[52:55], v[20:35]
	v_add_f32_e64 v48, v66, -v2
	v_add_f32_e64 v49, v67, -v2
	v_add_f32_e64 v50, v68, v74
	v_add_f32_e64 v51, v69, v75
	v_exp_f32_e32 v48, v48
	v_exp_f32_e32 v49, v49
	v_add_f32_e32 v50, v56, v50
	v_add_f32_e32 v51, v57, v51
	v_xor_b32_e32 v0, 0x80, v0
	v_add_f32_e32 v56, v48, v72
	v_add_f32_e32 v57, v49, v73
	v_mfma_f32_32x32x16_bf16 v[4:19], v[44:47], v[52:55], v[4:19]
	v_add_f32_e64 v44, v56, v50
	v_add_f32_e64 v45, v57, v51
	v_cvt_pk_bf16_f32 v46, v64, v65
	v_add_f32_e32 v1, v44, v45
	v_add_f32_e32 v1, v112, v1
	ds_bpermute_b32 v0, v0, v1
	v_cvt_pk_bf16_f32 v44, v60, v61
	v_cvt_pk_bf16_f32 v45, v62, v63
	v_cvt_pk_bf16_f32 v47, v48, v49
	s_waitcnt lgkmcnt(0)
	v_add_f32_e32 v0, v1, v0
	v_div_scale_f32 v1, s[4:5], v0, v0, 1.0
	v_rcp_f32_e32 v2, v1
	v_mfma_f32_32x32x16_bf16 v[20:35], v[40:43], v[44:47], v[20:35]
	s_mov_b64 s[4:5], 0xd000400
	v_mfma_f32_32x32x16_bf16 v[4:19], v[36:39], v[44:47], v[4:19]
	v_fma_f32 v36, -v1, v2, 1.0
	v_fmac_f32_e32 v2, v36, v2
	v_div_scale_f32 v36, vcc, 1.0, v0, 1.0
	v_mul_f32_e32 v37, v36, v2
	v_fma_f32 v38, -v1, v37, v36
	v_fmac_f32_e32 v37, v38, v2
	v_fma_f32 v1, -v1, v37, v36
	v_lshlrev_b64 v[38:39], 12, v[124:125]
	v_div_fmas_f32 v1, v1, v2, v37
	v_lshl_add_u64 v[38:39], s[10:11], 0, v[38:39]
	v_div_fixup_f32 v36, v1, v0, 1.0
	v_lshl_add_u64 v[38:39], v[38:39], 0, s[20:21]
	v_lshlrev_b32_e32 v2, 1, v129
	v_lshl_add_u64 v[38:39], v[38:39], 0, v[2:3]
	v_pk_mul_f32 v[20:21], v[20:21], v[36:37] op_sel_hi:[1,0]
	v_pk_mul_f32 v[22:23], v[22:23], v[36:37] op_sel_hi:[1,0]
	v_pk_mul_f32 v[6:7], v[6:7], v[36:37] op_sel_hi:[1,0]
	v_lshl_add_u64 v[40:41], v[38:39], 0, s[4:5]
	v_pk_mul_f32 v[42:43], v[4:5], v[36:37] op_sel_hi:[1,0]
	v_cvt_pk_bf16_f32 v4, v20, v21
	v_cvt_pk_bf16_f32 v5, v22, v23
	v_cvt_pk_bf16_f32 v21, v6, v7
	v_pk_mul_f32 v[6:7], v[24:25], v[36:37] op_sel_hi:[1,0]
	v_pk_mul_f32 v[22:23], v[26:27], v[36:37] op_sel_hi:[1,0]
	v_pk_mul_f32 v[8:9], v[8:9], v[36:37] op_sel_hi:[1,0]
	s_mov_b32 s4, 0xd000000
	v_cvt_pk_bf16_f32 v6, v6, v7
	v_cvt_pk_bf16_f32 v7, v22, v23
	v_cvt_pk_bf16_f32 v22, v8, v9
	v_add_co_u32_e32 v8, vcc, s4, v38
	v_pk_mul_f32 v[10:11], v[10:11], v[36:37] op_sel_hi:[1,0]
	v_permlane32_swap_b32_e32 v4, v6
	v_permlane32_swap_b32_e32 v5, v7
	v_addc_co_u32_e32 v9, vcc, 0, v39, vcc
	v_cvt_pk_bf16_f32 v23, v10, v11
	global_store_dwordx4 v[8:9], v[4:7], off offset:1024
	v_pk_mul_f32 v[8:9], v[12:13], v[36:37] op_sel_hi:[1,0]
	v_pk_mul_f32 v[10:11], v[14:15], v[36:37] op_sel_hi:[1,0]
	v_pk_mul_f32 v[4:5], v[28:29], v[36:37] op_sel_hi:[1,0]
	v_pk_mul_f32 v[6:7], v[30:31], v[36:37] op_sel_hi:[1,0]
	v_cvt_pk_bf16_f32 v4, v4, v5
	v_cvt_pk_bf16_f32 v5, v6, v7
	v_cvt_pk_bf16_f32 v8, v8, v9
	v_cvt_pk_bf16_f32 v9, v10, v11
	v_pk_mul_f32 v[6:7], v[32:33], v[36:37] op_sel_hi:[1,0]
	v_pk_mul_f32 v[10:11], v[34:35], v[36:37] op_sel_hi:[1,0]
	v_pk_mul_f32 v[12:13], v[16:17], v[36:37] op_sel_hi:[1,0]
	v_pk_mul_f32 v[14:15], v[18:19], v[36:37] op_sel_hi:[1,0]
	v_cvt_pk_bf16_f32 v20, v42, v43
	v_cvt_pk_bf16_f32 v6, v6, v7
	v_cvt_pk_bf16_f32 v7, v10, v11
	v_cvt_pk_bf16_f32 v10, v12, v13
	v_cvt_pk_bf16_f32 v11, v14, v15
	v_permlane32_swap_b32_e32 v20, v22
	v_permlane32_swap_b32_e32 v21, v23
	v_permlane32_swap_b32_e32 v4, v6
	v_permlane32_swap_b32_e32 v5, v7
	v_permlane32_swap_b32_e32 v8, v10
	v_permlane32_swap_b32_e32 v9, v11
	global_store_dwordx4 v[40:41], v[20:23], off offset:64
	global_store_dwordx4 v[40:41], v[4:7], off offset:32
	global_store_dwordx4 v[40:41], v[8:11], off offset:96
	s_mov_b64 s[4:5], 0

.LBB0_967:
	v_add_f32_e32 v82, v106, v104
	v_add_f32_e32 v83, v107, v105
	v_add_f32_e32 v90, v110, v108
	v_add_f32_e32 v91, v111, v109
	v_pk_add_f32 v[82:83], v[82:83], 0 op_sel_hi:[1,0]
	v_sub_f32_e32 v92, v186, v76
	v_sub_f32_e32 v93, v187, v76
	v_add_f32_e32 v82, v90, v82
	v_add_f32_e32 v83, v91, v83
	v_add_f32_e32 v90, v114, v112
	v_add_f32_e32 v91, v115, v113
	v_sub_f32_e32 v94, v184, v76
	v_sub_f32_e32 v95, v185, v76
	v_add_f32_e32 v82, v90, v82
	v_add_f32_e32 v83, v91, v83
	v_add_f32_e32 v90, v172, v162
	v_add_f32_e32 v91, v173, v163
	v_exp_f32_e32 v112, v92
	v_add_f32_e32 v82, v90, v82
	v_add_f32_e32 v83, v91, v83
	v_add_f32_e32 v90, v174, v164
	v_add_f32_e32 v91, v175, v165
	v_exp_f32_e32 v113, v93
	v_add_f32_e32 v82, v90, v82
	v_add_f32_e32 v83, v91, v83
	v_add_f32_e32 v90, v176, v166
	v_add_f32_e32 v91, v177, v167
	v_exp_f32_e32 v114, v94
	v_add_f32_e32 v82, v90, v82
	v_add_f32_e32 v83, v91, v83
	v_add_f32_e32 v90, v178, v168
	v_add_f32_e32 v91, v179, v169
	v_exp_f32_e32 v115, v95
	v_add_f32_e32 v82, v90, v82
	v_add_f32_e32 v83, v91, v83
	v_add_f32_e32 v90, v180, v170
	v_add_f32_e32 v91, v181, v171
	v_sub_f32_e32 v88, v88, v76
	v_sub_f32_e32 v89, v89, v76
	v_add_f32_e32 v82, v90, v82
	v_add_f32_e32 v83, v91, v83
	v_sub_f32_e32 v90, v192, v76
	v_sub_f32_e32 v91, v193, v76
	v_add_f32_e32 v0, v82, v83
	v_sub_f32_e32 v82, v194, v76
	v_sub_f32_e32 v83, v195, v76
	v_exp_f32_e32 v108, v90
	v_exp_f32_e32 v98, v82
	v_exp_f32_e32 v99, v83
	v_exp_f32_e32 v109, v91
	v_sub_f32_e32 v82, v190, v76
	v_sub_f32_e32 v83, v191, v76
	v_sub_f32_e32 v90, v188, v76
	v_sub_f32_e32 v91, v189, v76
	v_exp_f32_e32 v106, v82
	v_exp_f32_e32 v107, v83
	v_exp_f32_e32 v110, v90
	v_exp_f32_e32 v111, v91
	v_add_f32_e32 v82, v108, v98
	v_add_f32_e32 v83, v109, v99
	v_sub_f32_e32 v92, v182, v76
	v_sub_f32_e32 v93, v183, v76
	v_pk_add_f32 v[82:83], v[82:83], 0 op_sel_hi:[1,0]
	v_add_f32_e32 v90, v110, v106
	v_add_f32_e32 v91, v111, v107
	v_exp_f32_e32 v164, v88
	v_exp_f32_e32 v165, v89
	v_add_f32_e32 v82, v90, v82
	v_add_f32_e32 v83, v91, v83
	v_add_f32_e32 v88, v114, v112
	v_add_f32_e32 v89, v115, v113
	v_exp_f32_e32 v162, v92
	v_exp_f32_e32 v163, v93
	v_add_f32_e32 v166, v88, v82
	v_add_f32_e32 v167, v89, v83
	v_sub_f32_e32 v82, v86, v76
	v_sub_f32_e32 v83, v87, v76
	v_cvt_pk_bf16_f32 v104, v98, v99
	v_exp_f32_e32 v170, v82
	v_exp_f32_e32 v171, v83
	v_sub_f32_e32 v82, v84, v76
	v_sub_f32_e32 v83, v85, v76
	v_cvt_pk_bf16_f32 v105, v106, v107
	v_exp_f32_e32 v172, v82
	v_exp_f32_e32 v173, v83
	ds_read_b64 v[84:85], v244
	ds_read_b64 v[82:83], v237
	ds_read_b64 v[86:87], v239
	ds_read_b64 v[90:91], v240
	ds_read_b64 v[94:95], v238
	ds_read_b64 v[88:89], v241
	ds_read_b64 v[92:93], v242
	ds_read_b64 v[96:97], v243
	v_cvt_pk_bf16_f32 v106, v112, v113
	v_cvt_pk_bf16_f32 v107, v162, v163
	v_sub_f32_e32 v78, v78, v76
	v_sub_f32_e32 v79, v79, v76
	v_sub_f32_e32 v72, v72, v76
	v_sub_f32_e32 v73, v73, v76
	s_waitcnt lgkmcnt(6)
	v_mfma_f32_32x32x16_bf16 v[20:35], v[82:85], v[104:107], v[20:35]
	v_add_f32_e64 v82, v80, -v76
	v_add_f32_e64 v83, v81, -v76
	v_exp_f32_e32 v98, v78
	v_exp_f32_e32 v99, v79
	v_exp_f32_e32 v112, v82
	ds_read_b64 v[78:79], v235
	ds_read_b64 v[80:81], v236
	v_exp_f32_e32 v113, v83
	ds_read_b64 v[82:83], v233
	ds_read_b64 v[84:85], v234
	s_waitcnt lgkmcnt(6)
	v_mfma_f32_32x32x16_bf16 v[4:19], v[86:89], v[104:107], v[4:19]
	v_cvt_pk_bf16_f32 v86, v170, v171
	v_cvt_pk_bf16_f32 v87, v172, v173
	v_cvt_pk_bf16_f32 v88, v98, v99
	v_cvt_pk_bf16_f32 v89, v112, v113
	v_add_f32_e64 v168, v164, v162
	v_add_f32_e64 v169, v165, v163
	v_sub_f32_e32 v68, v68, v76
	v_sub_f32_e32 v69, v69, v76
	s_add_i32 s8, s8, 64
	s_waitcnt lgkmcnt(2)
	v_mfma_f32_32x32x16_bf16 v[20:35], v[78:81], v[86:89], v[20:35]
	v_exp_f32_e32 v80, v72
	v_exp_f32_e32 v81, v73
	v_sub_f32_e32 v72, v74, v76
	v_sub_f32_e32 v73, v75, v76
	v_add_f32_e32 v78, v168, v166
	v_add_f32_e32 v79, v169, v167
	v_exp_f32_e32 v104, v72
	v_exp_f32_e32 v105, v73
	v_add_f32_e32 v72, v80, v170
	v_add_f32_e32 v73, v81, v171
	s_waitcnt lgkmcnt(0)
	v_mfma_f32_32x32x16_bf16 v[4:19], v[82:85], v[86:89], v[4:19]
	v_add_f32_e64 v82, v72, v78
	v_add_f32_e64 v83, v73, v79
	v_cvt_pk_bf16_f32 v72, v108, v109
	v_cvt_pk_bf16_f32 v73, v110, v111
	v_cvt_pk_bf16_f32 v74, v114, v115
	v_cvt_pk_bf16_f32 v75, v164, v165
	v_sub_f32_e32 v77, v71, v76
	v_sub_f32_e32 v76, v70, v76
	v_exp_f32_e32 v86, v68
	v_mfma_f32_32x32x16_bf16 v[20:35], v[90:93], v[72:75], v[20:35]
	v_exp_f32_e32 v87, v69
	v_exp_f32_e32 v88, v76
	ds_read_b64 v[68:69], v231
	ds_read_b64 v[70:71], v232
	v_exp_f32_e32 v89, v77
	v_cvt_pk_bf16_f32 v76, v80, v81
	v_cvt_pk_bf16_f32 v77, v104, v105
	v_cvt_pk_bf16_f32 v78, v86, v87
	v_mfma_f32_32x32x16_bf16 v[4:19], v[94:97], v[72:75], v[4:19]
	ds_read_b64 v[72:73], v245
	ds_read_b64 v[74:75], v246
	v_cvt_pk_bf16_f32 v79, v88, v89
	v_add_f32_e64 v84, v104, v172
	v_add_f32_e64 v85, v105, v173
	v_readlane_b32 s64, v254, 62
	v_add_f32_e32 v102, v102, v0
	s_add_i32 s6, s20, s8
	s_mov_b32 s78, 0x3b800000
	s_waitcnt lgkmcnt(2)
	v_mfma_f32_32x32x16_bf16 v[20:35], v[68:71], v[76:79], v[20:35]
	v_add_f32_e64 v68, v84, v82
	v_add_f32_e64 v69, v85, v83
	v_add_f32_e64 v70, v86, v98
	v_add_f32_e64 v71, v87, v99
	s_mov_b32 s88, s9
	v_add_f32_e32 v68, v70, v68
	v_add_f32_e32 v69, v71, v69
	v_add_f32_e32 v70, v88, v112
	v_add_f32_e32 v71, v89, v113
	v_readlane_b32 s65, v254, 63
	v_add_f32_e32 v68, v70, v68
	v_add_f32_e32 v69, v71, v69
	s_waitcnt lgkmcnt(0)
	v_mfma_f32_32x32x16_bf16 v[4:19], v[72:75], v[76:79], v[4:19]
	v_add_f32_e32 v0, v68, v69
	v_add_f32_e32 v152, v152, v0
	v_add_u32_e32 v153, 0x80, v153
	v_add_u32_e32 v222, 0x2400, v222
	v_add_u32_e32 v229, 0x80, v229
	s_cmp_lt_u32 s6, s17
	v_add_u32_e32 v230, 0x80, v230
	s_cbranch_scc0 .LBB0_974

.LBB0_971:
	v_add_u32_e32 v79, 0, v230
	v_sub_f32_e32 v92, v106, v78
	v_sub_f32_e32 v93, v107, v78
	v_sub_f32_e32 v84, v84, v78
	v_sub_f32_e32 v85, v85, v78
	v_add_u32_e32 v0, 0, v229
	v_sub_f32_e32 v90, v104, v78
	v_sub_f32_e32 v91, v105, v78
	v_exp_f32_e32 v106, v92
	v_exp_f32_e32 v107, v93
	v_sub_f32_e32 v92, v110, v78
	v_sub_f32_e32 v93, v111, v78
	v_exp_f32_e32 v162, v84
	v_exp_f32_e32 v163, v85
	v_sub_f32_e32 v84, v86, v78
	v_sub_f32_e32 v85, v87, v78
	v_add_u32_e32 v1, 0, v153
	v_add_u32_e32 v244, 0x10e10, v0
	v_exp_f32_e32 v104, v90
	v_exp_f32_e32 v105, v91
	v_sub_f32_e32 v90, v108, v78
	v_sub_f32_e32 v91, v109, v78
	v_exp_f32_e32 v110, v92
	v_exp_f32_e32 v111, v93
	v_sub_f32_e32 v92, v112, v78
	v_sub_f32_e32 v93, v113, v78
	v_exp_f32_e32 v164, v84
	v_exp_f32_e32 v165, v85
	v_sub_f32_e32 v84, v88, v78
	v_sub_f32_e32 v85, v89, v78
	v_add_u32_e32 v237, 0x10e00, v0
	v_add_u32_e32 v239, 0x10f00, v1
	v_add_u32_e32 v240, 0x10e40, v79
	v_add_u32_e32 v238, 0x10f40, v1
	v_add_u32_e32 v241, 0x10f10, v1
	v_exp_f32_e32 v108, v90
	v_exp_f32_e32 v109, v91
	v_exp_f32_e32 v112, v92
	v_exp_f32_e32 v113, v93
	v_exp_f32_e32 v166, v84
	v_exp_f32_e32 v167, v85
	ds_read_b64 v[86:87], v244
	ds_read_b64 v[84:85], v237
	ds_read_b64 v[92:93], v239
	ds_read_b64 v[96:97], v240
	ds_read_b64 v[184:185], v238
	ds_read_b64 v[94:95], v241
	v_cvt_pk_bf16_f32 v172, v104, v105
	v_cvt_pk_bf16_f32 v173, v108, v109
	v_cvt_pk_bf16_f32 v174, v112, v113
	v_cvt_pk_bf16_f32 v175, v162, v163
	v_add_u32_e32 v235, 0x10e20, v0
	v_add_u32_e32 v233, 0x10f20, v1
	s_waitcnt lgkmcnt(4)
	v_mfma_f32_32x32x16_bf16 v[52:67], v[84:87], v[172:175], v[52:67]
	v_add_f32_e64 v80, v80, -v78
	v_add_f32_e64 v81, v81, -v78
	v_add_f32_e64 v84, v82, -v78
	v_add_f32_e64 v85, v83, -v78
	v_add_u32_e32 v236, 0x10e30, v0
	v_add_u32_e32 v234, 0x10f30, v1
	v_exp_f32_e32 v168, v80
	v_exp_f32_e32 v169, v81
	v_exp_f32_e32 v170, v84
	s_waitcnt lgkmcnt(0)
	v_mfma_f32_32x32x16_bf16 v[36:51], v[92:95], v[172:175], v[36:51]
	ds_read_b64 v[80:81], v235
	ds_read_b64 v[82:83], v236
	v_exp_f32_e32 v171, v85
	ds_read_b64 v[84:85], v233
	ds_read_b64 v[86:87], v234
	v_cvt_pk_bf16_f32 v92, v164, v165
	v_cvt_pk_bf16_f32 v93, v166, v167
	v_cvt_pk_bf16_f32 v94, v168, v169
	v_cvt_pk_bf16_f32 v95, v170, v171
	v_add_u32_e32 v242, 0x10e50, v79
	v_sub_f32_e32 v90, v114, v78
	v_sub_f32_e32 v91, v115, v78
	s_waitcnt lgkmcnt(2)
	v_mfma_f32_32x32x16_bf16 v[52:67], v[80:83], v[92:95], v[52:67]
	v_add_f32_e64 v68, v68, -v78
	v_add_f32_e64 v69, v69, -v78
	v_add_u32_e32 v243, 0x10f50, v1
	v_exp_f32_e32 v114, v90
	ds_read_b64 v[98:99], v242
	ds_read_b64 v[186:187], v243
	v_exp_f32_e32 v115, v91
	v_exp_f32_e32 v172, v68
	v_exp_f32_e32 v173, v69
	s_waitcnt lgkmcnt(2)
	v_mfma_f32_32x32x16_bf16 v[36:51], v[84:87], v[92:95], v[36:51]
	v_add_f32_e64 v68, v70, -v78
	v_add_f32_e64 v69, v71, -v78
	v_add_f32_e64 v72, v72, -v78
	v_add_f32_e64 v73, v73, -v78
	v_exp_f32_e32 v174, v68
	v_exp_f32_e32 v175, v69
	v_cvt_pk_bf16_f32 v68, v106, v107
	v_cvt_pk_bf16_f32 v69, v110, v111
	v_cvt_pk_bf16_f32 v70, v114, v115
	v_cvt_pk_bf16_f32 v71, v172, v173
	v_add_u32_e32 v231, 0x10e60, v79
	v_exp_f32_e32 v176, v72
	s_waitcnt lgkmcnt(1)
	v_mfma_f32_32x32x16_bf16 v[52:67], v[96:99], v[68:71], v[52:67]
	v_exp_f32_e32 v177, v73
	v_sub_f32_e32 v72, v74, v78
	v_sub_f32_e32 v73, v75, v78
	v_add_u32_e32 v232, 0x10e70, v79
	v_exp_f32_e32 v178, v72
	v_exp_f32_e32 v179, v73
	ds_read_b64 v[72:73], v231
	ds_read_b64 v[74:75], v232
	ds_read_b128 v[188:191], v182 offset:32
	s_waitcnt lgkmcnt(3)
	v_mfma_f32_32x32x16_bf16 v[36:51], v[184:187], v[68:71], v[36:51]
	v_add_f32_e64 v68, v76, -v78
	v_add_f32_e64 v69, v77, -v78
	v_cvt_pk_bf16_f32 v184, v174, v175
	v_exp_f32_e32 v180, v68
	v_exp_f32_e32 v181, v69
	ds_read_b128 v[68:71], v182
	v_cvt_pk_bf16_f32 v185, v176, v177
	v_cvt_pk_bf16_f32 v186, v178, v179
	v_cvt_pk_bf16_f32 v187, v180, v181
	ds_read_b128 v[84:87], v182 offset:4608
	v_add_u32_e32 v245, 0x10f60, v1
	s_waitcnt lgkmcnt(3)
	v_mfma_f32_32x32x16_bf16 v[52:67], v[72:75], v[184:187], v[52:67]
	ds_read_b64 v[248:249], v245
	v_add_u32_e32 v246, 0x10f70, v1
	ds_read_b64 v[250:251], v246
	s_waitcnt lgkmcnt(3)
	v_mfma_f32_32x32x16_bf16 v[68:83], v[68:71], v[128:131], 0
	v_mfma_f32_32x32x16_bf16 v[68:83], v[188:191], v[124:127], v[68:83]
	ds_read_b128 v[188:191], v182 offset:4640
	s_waitcnt lgkmcnt(3)
	v_mfma_f32_32x32x16_bf16 v[84:99], v[84:87], v[128:131], 0
	s_waitcnt lgkmcnt(0)
	v_mfma_f32_32x32x16_bf16 v[84:99], v[188:191], v[124:127], v[84:99]
	ds_read_b128 v[188:191], v182 offset:64
	s_waitcnt lgkmcnt(0)
	v_mfma_f32_32x32x16_bf16 v[68:83], v[188:191], v[120:123], v[68:83]
	ds_read_b128 v[188:191], v182 offset:4672
	s_waitcnt lgkmcnt(0)
	v_mfma_f32_32x32x16_bf16 v[84:99], v[188:191], v[120:123], v[84:99]
	ds_read_b128 v[188:191], v182 offset:96
	s_waitcnt lgkmcnt(0)
	v_mfma_f32_32x32x16_bf16 v[68:83], v[188:191], v[116:119], v[68:83]
	ds_read_b128 v[188:191], v182 offset:4704
	s_waitcnt lgkmcnt(0)
	v_mfma_f32_32x32x16_bf16 v[84:99], v[188:191], v[116:119], v[84:99]
	s_nop 8
	v_cndmask_b32_e64 v195, v69, v210, s[42:43]
	v_cndmask_b32_e64 v194, v68, v210, s[38:39]
	v_cndmask_b32_e64 v190, v70, v210, s[46:47]
	v_cndmask_b32_e64 v191, v71, v210, s[50:51]
	v_cndmask_b32_e64 v182, v74, v210, s[62:63]
	v_cndmask_b32_e64 v183, v75, v210, s[66:67]
	v_cndmask_b32_e64 v193, v85, v210, s[44:45]
	v_cndmask_b32_e64 v192, v84, v210, s[40:41]
	v_cndmask_b32_e64 v188, v86, v210, s[48:49]
	v_cndmask_b32_e64 v189, v87, v210, s[52:53]
	v_maximum3_f32 v0, v195, v193, v193
	v_mfma_f32_32x32x16_bf16 v[36:51], v[248:251], v[184:187], v[36:51]
	v_cndmask_b32_e64 v186, v72, v210, s[54:55]
	v_cndmask_b32_e64 v184, v88, v210, s[56:57]
	v_cndmask_b32_e64 v187, v73, v210, s[58:59]
	v_cndmask_b32_e64 v185, v89, v210, s[60:61]
	v_cndmask_b32_e64 v86, v76, v210, s[70:71]
	v_maximum3_f32 v0, v194, v192, v0
	v_maximum3_f32 v1, v190, v188, v188
	v_maximum3_f32 v76, v191, v189, v189
	v_cndmask_b32_e64 v88, v90, v210, s[64:65]
	v_cndmask_b32_e64 v89, v91, v210, s[68:69]
	v_maximum3_f32 v0, v0, v1, v76
	v_maximum3_f32 v1, v186, v184, v184
	v_maximum3_f32 v76, v187, v185, v185
	v_cndmask_b32_e64 v72, v92, v210, s[72:73]
	v_cndmask_b32_e64 v87, v77, v210, s[74:75]
	v_cndmask_b32_e64 v73, v93, v210, s[76:77]
	v_maximum3_f32 v0, v0, v1, v76
	v_maximum3_f32 v1, v182, v88, v88
	v_maximum3_f32 v76, v183, v89, v89
	v_cndmask_b32_e64 v84, v78, v210, s[78:79]
	v_cndmask_b32_e64 v74, v94, v210, s[80:81]
	v_cndmask_b32_e64 v85, v79, v210, s[82:83]
	v_cndmask_b32_e64 v75, v95, v210, s[84:85]
	v_maximum3_f32 v0, v0, v1, v76
	v_maximum3_f32 v1, v86, v72, v72
	v_maximum3_f32 v76, v87, v73, v73
	v_cndmask_b32_e64 v78, v80, v210, s[86:87]
	v_cndmask_b32_e64 v68, v96, v210, s[88:89]
	v_cndmask_b32_e64 v79, v81, v210, s[90:91]
	v_cndmask_b32_e64 v69, v97, v210, s[92:93]
	v_maximum3_f32 v0, v0, v1, v76
	v_maximum3_f32 v1, v84, v74, v74
	v_maximum3_f32 v76, v85, v75, v75
	v_cndmask_b32_e64 v80, v82, v210, s[94:95]
	v_cndmask_b32_e64 v70, v98, v210, s[96:97]
	v_cndmask_b32_e64 v81, v83, v210, s[4:5]
	v_cndmask_b32_e64 v71, v99, v210, s[6:7]
	v_maximum3_f32 v0, v0, v1, v76
	v_maximum3_f32 v1, v78, v68, v68
	v_maximum3_f32 v76, v79, v69, v69
	v_maximum3_f32 v0, v0, v1, v76
	v_maximum3_f32 v1, v80, v70, v70
	v_maximum3_f32 v76, v81, v71, v71
	v_maximum3_f32 v0, v0, v1, v76
	v_mov_b32_e32 v1, v0
	s_nop 1
	v_permlane32_swap_b32_e32 v0, v1
	s_nop 0
	v_maximum3_f32 v76, v0, v1, v1
	v_cmp_gt_f32_e32 vcc, v76, v151
	s_cbranch_vccnz .LBB0_966
	v_mov_b32_e32 v76, v151
	s_branch .LBB0_967

.LBB0_975:
	v_readlane_b32 s4, v255, 0
	s_lshl_b32 s8, s4, 6
	v_lshlrev_b32_e32 v0, 2, v101
	v_add3_u32 v222, 0, v221, v100
	s_cmp_gt_i32 s6, s17
	v_xor_b32_e32 v221, 0x80, v0
	s_cbranch_scc1 .LBB0_977
	v_readlane_b32 s4, v254, 44
	v_sub_u32_e32 v69, v161, v228
	v_add_u32_e32 v69, s6, v69
	v_mov_b32_e32 v0, s4
	v_readlane_b32 s4, v255, 8
	v_readlane_b32 s5, v255, 9
	s_sub_i32 s4, s6, s4
	v_mad_i32_i24 v0, s2, v159, v0
	s_mul_i32 s5, s4, 0x90
	s_lshl_b32 s4, s4, 1
	v_add_u32_e32 v1, s5, v222
	v_add3_u32 v0, v0, v220, s4
	v_readlane_b32 s2, v255, 11
	s_movk_i32 s9, 0xfeff
	s_nop 0
	v_add_u32_e32 v68, s2, v0
	ds_read_b128 v[100:103], v1
	ds_read_b128 v[112:115], v1 offset:32
	ds_read_b128 v[108:111], v1 offset:64
	ds_read_b128 v[104:107], v1 offset:96
	ds_read2_b64 v[96:99], v0 offset1:2
	ds_read2_b64 v[92:95], v0 offset0:4 offset1:6
	ds_read2_b64 v[88:91], v68 offset1:2
	ds_read2_b64 v[84:87], v68 offset0:4 offset1:6
	v_add_u32_e32 v0, 0xffffff7f, v69
	v_cmp_gt_u32_e32 vcc, s9, v0
	v_add_u32_e32 v0, 0xffffff80, v69
	v_cmp_gt_u32_e64 s[4:5], s9, v0
	v_add_u32_e32 v0, 0xffffff81, v69
	v_cmp_gt_u32_e64 s[6:7], s9, v0
	v_add_u32_e32 v0, 0xffffff82, v69
	v_cmp_gt_u32_e64 s[38:39], s9, v0
	v_add_u32_e32 v0, 0xffffff87, v69
	v_cmp_gt_u32_e64 s[40:41], s9, v0
	v_add_u32_e32 v0, 0xffffff88, v69
	v_cmp_gt_u32_e64 s[42:43], s9, v0
	v_add_u32_e32 v0, 0xffffff89, v69
	v_cmp_gt_u32_e64 s[44:45], s9, v0
	v_add_u32_e32 v0, 0xffffff8a, v69
	v_cmp_gt_u32_e64 s[46:47], s9, v0
	v_add_u32_e32 v0, 0xffffff8f, v69
	v_cmp_gt_u32_e64 s[48:49], s9, v0
	v_add_u32_e32 v0, 0xffffff90, v69
	v_cmp_gt_u32_e64 s[50:51], s9, v0
	v_add_u32_e32 v0, 0xffffff91, v69
	v_cmp_gt_u32_e64 s[52:53], s9, v0
	v_add_u32_e32 v0, 0xffffff92, v69
	v_cmp_gt_u32_e64 s[54:55], s9, v0
	v_add_u32_e32 v0, 0xffffff97, v69
	v_cmp_gt_u32_e64 s[56:57], s9, v0
	v_add_u32_e32 v0, 0xffffff98, v69
	v_cmp_gt_u32_e64 s[58:59], s9, v0
	v_add_u32_e32 v0, 0xffffff99, v69
	v_cmp_gt_u32_e64 s[60:61], s9, v0
	v_add_u32_e32 v0, 0xffffff9a, v69
	s_waitcnt lgkmcnt(7)
	v_mfma_f32_32x32x16_bf16 v[68:83], v[100:103], v[144:147], 0
	v_cmp_gt_u32_e64 s[62:63], s9, v0
	s_waitcnt lgkmcnt(6)
	v_mfma_f32_32x32x16_bf16 v[68:83], v[112:115], v[140:143], v[68:83]
	s_waitcnt lgkmcnt(5)
	v_mfma_f32_32x32x16_bf16 v[68:83], v[108:111], v[136:139], v[68:83]
	s_waitcnt lgkmcnt(4)
	v_mfma_f32_32x32x16_bf16 v[68:83], v[104:107], v[132:135], v[68:83]
	s_nop 11
	v_cndmask_b32_e32 v0, v68, v210, vcc
	v_cndmask_b32_e64 v1, v69, v210, s[4:5]
	v_cndmask_b32_e64 v68, v70, v210, s[6:7]
	v_cndmask_b32_e64 v69, v71, v210, s[38:39]
	v_cndmask_b32_e64 v70, v72, v210, s[40:41]
	v_cndmask_b32_e64 v72, v74, v210, s[44:45]
	v_cndmask_b32_e64 v74, v76, v210, s[48:49]
	v_cndmask_b32_e64 v76, v78, v210, s[52:53]
	v_cndmask_b32_e64 v78, v80, v210, s[56:57]
	v_cndmask_b32_e64 v80, v82, v210, s[60:61]
	v_maximum3_f32 v82, v0, v1, v1
	v_cndmask_b32_e64 v71, v73, v210, s[42:43]
	v_maximum3_f32 v82, v82, v68, v69
	v_cndmask_b32_e64 v73, v75, v210, s[46:47]
	v_maximum3_f32 v82, v82, v70, v71
	v_cndmask_b32_e64 v75, v77, v210, s[50:51]
	v_maximum3_f32 v82, v82, v72, v73
	v_cndmask_b32_e64 v77, v79, v210, s[54:55]
	v_maximum3_f32 v82, v82, v74, v75
	v_cndmask_b32_e64 v79, v81, v210, s[58:59]
	v_maximum3_f32 v82, v82, v76, v77
	v_cndmask_b32_e64 v81, v83, v210, s[62:63]
	v_maximum3_f32 v82, v82, v78, v79
	v_maximum3_f32 v82, v82, v80, v81
	ds_bpermute_b32 v83, v221, v82
	s_waitcnt lgkmcnt(0)
	v_maximum3_f32 v162, v150, v82, v83
	v_sub_f32_e32 v0, v0, v162
	v_sub_f32_e32 v82, v150, v162
	v_exp_f32_e32 v150, v0
	v_sub_f32_e32 v0, v1, v162
	v_exp_f32_e32 v164, v0
	v_sub_f32_e32 v0, v68, v162
	v_exp_f32_e32 v166, v0
	v_sub_f32_e32 v0, v69, v162
	v_exp_f32_e32 v168, v0
	v_sub_f32_e32 v0, v70, v162
	v_exp_f32_e32 v170, v0
	v_sub_f32_e32 v0, v71, v162
	v_exp_f32_e32 v172, v0
	v_sub_f32_e32 v0, v72, v162
	v_exp_f32_e32 v174, v0
	v_sub_f32_e32 v0, v73, v162
	v_exp_f32_e32 v176, v0
	v_sub_f32_e32 v0, v74, v162
	v_exp_f32_e32 v194, v82
	v_exp_f32_e32 v178, v0
	v_sub_f32_e32 v0, v75, v162
	v_exp_f32_e32 v180, v0
	v_sub_f32_e32 v0, v76, v162
	v_exp_f32_e32 v182, v0
	v_sub_f32_e32 v0, v77, v162
	v_exp_f32_e32 v184, v0
	v_sub_f32_e32 v0, v78, v162
	v_pk_mul_f32 v[52:53], v[52:53], v[194:195] op_sel_hi:[1,0]
	v_pk_mul_f32 v[54:55], v[54:55], v[194:195] op_sel_hi:[1,0]
	v_pk_mul_f32 v[56:57], v[56:57], v[194:195] op_sel_hi:[1,0]
	v_pk_mul_f32 v[58:59], v[58:59], v[194:195] op_sel_hi:[1,0]
	v_pk_mul_f32 v[60:61], v[60:61], v[194:195] op_sel_hi:[1,0]
	v_pk_mul_f32 v[62:63], v[62:63], v[194:195] op_sel_hi:[1,0]
	v_pk_mul_f32 v[64:65], v[64:65], v[194:195] op_sel_hi:[1,0]
	v_pk_mul_f32 v[66:67], v[66:67], v[194:195] op_sel_hi:[1,0]
	v_pk_mul_f32 v[50:51], v[50:51], v[194:195] op_sel_hi:[1,0]
	v_pk_mul_f32 v[48:49], v[48:49], v[194:195] op_sel_hi:[1,0]
	v_pk_mul_f32 v[46:47], v[46:47], v[194:195] op_sel_hi:[1,0]
	v_pk_mul_f32 v[44:45], v[44:45], v[194:195] op_sel_hi:[1,0]
	v_pk_mul_f32 v[42:43], v[42:43], v[194:195] op_sel_hi:[1,0]
	v_pk_mul_f32 v[40:41], v[40:41], v[194:195] op_sel_hi:[1,0]
	v_pk_mul_f32 v[38:39], v[38:39], v[194:195] op_sel_hi:[1,0]
	v_pk_mul_f32 v[36:37], v[36:37], v[194:195] op_sel_hi:[1,0]
	v_cvt_pk_bf16_f32 v68, v150, v164
	v_cvt_pk_bf16_f32 v69, v166, v168
	v_cvt_pk_bf16_f32 v70, v170, v172
	v_cvt_pk_bf16_f32 v71, v174, v176
	v_exp_f32_e32 v186, v0
	v_sub_f32_e32 v0, v79, v162
	v_mfma_f32_32x32x16_bf16 v[52:67], v[96:99], v[68:71], v[52:67]
	v_exp_f32_e32 v188, v0
	v_sub_f32_e32 v0, v80, v162
	v_exp_f32_e32 v190, v0
	v_sub_f32_e32 v0, v81, v162
	v_exp_f32_e32 v192, v0
	v_cvt_pk_bf16_f32 v72, v178, v180
	v_cvt_pk_bf16_f32 v73, v182, v184
	v_mfma_f32_32x32x16_bf16 v[36:51], v[88:91], v[68:71], v[36:51]
	v_cvt_pk_bf16_f32 v74, v186, v188
	v_cvt_pk_bf16_f32 v75, v190, v192
	s_nop 1
	v_mfma_f32_32x32x16_bf16 v[52:67], v[92:95], v[72:75], v[52:67]
	v_mfma_f32_32x32x16_bf16 v[36:51], v[84:87], v[72:75], v[36:51]
	v_mfma_f32_32x32x16_bf16 v[68:83], v[100:103], v[128:131], 0
	v_mfma_f32_32x32x16_bf16 v[68:83], v[112:115], v[124:127], v[68:83]
	v_mfma_f32_32x32x16_bf16 v[68:83], v[108:111], v[120:123], v[68:83]
	v_mfma_f32_32x32x16_bf16 v[68:83], v[104:107], v[116:119], v[68:83]
	s_nop 11
	v_cndmask_b32_e32 v0, v68, v210, vcc
	v_cndmask_b32_e64 v1, v69, v210, s[4:5]
	v_cndmask_b32_e64 v68, v70, v210, s[6:7]
	v_cndmask_b32_e64 v69, v71, v210, s[38:39]
	v_cndmask_b32_e64 v70, v72, v210, s[40:41]
	v_cndmask_b32_e64 v72, v74, v210, s[44:45]
	v_cndmask_b32_e64 v74, v76, v210, s[48:49]
	v_cndmask_b32_e64 v76, v78, v210, s[52:53]
	v_cndmask_b32_e64 v78, v80, v210, s[56:57]
	v_cndmask_b32_e64 v80, v82, v210, s[60:61]
	v_maximum3_f32 v82, v0, v1, v1
	v_cndmask_b32_e64 v71, v73, v210, s[42:43]
	v_maximum3_f32 v82, v82, v68, v69
	v_cndmask_b32_e64 v73, v75, v210, s[46:47]
	v_maximum3_f32 v82, v82, v70, v71
	v_cndmask_b32_e64 v75, v77, v210, s[50:51]
	v_maximum3_f32 v82, v82, v72, v73
	v_cndmask_b32_e64 v77, v79, v210, s[54:55]
	v_maximum3_f32 v82, v82, v74, v75
	v_cndmask_b32_e64 v79, v81, v210, s[58:59]
	v_maximum3_f32 v82, v82, v76, v77
	v_cndmask_b32_e64 v81, v83, v210, s[62:63]
	v_maximum3_f32 v82, v82, v78, v79
	v_maximum3_f32 v82, v82, v80, v81
	ds_bpermute_b32 v83, v221, v82
	s_waitcnt lgkmcnt(0)
	v_maximum3_f32 v163, v151, v82, v83
	v_sub_f32_e32 v0, v0, v163
	v_sub_f32_e32 v82, v151, v163
	v_exp_f32_e32 v151, v0
	v_sub_f32_e32 v0, v1, v163
	v_exp_f32_e32 v165, v0
	v_sub_f32_e32 v0, v68, v163
	v_exp_f32_e32 v167, v0
	v_sub_f32_e32 v0, v69, v163
	v_exp_f32_e32 v169, v0
	v_sub_f32_e32 v0, v70, v163
	v_exp_f32_e32 v171, v0
	v_sub_f32_e32 v0, v71, v163
	v_pk_add_f32 v[68:69], v[150:151], 0 op_sel_hi:[1,0]
	v_exp_f32_e32 v173, v0
	v_add_f32_e32 v68, v164, v68
	v_add_f32_e32 v69, v165, v69
	v_sub_f32_e32 v0, v72, v163
	v_add_f32_e32 v68, v166, v68
	v_add_f32_e32 v69, v167, v69
	v_exp_f32_e32 v175, v0
	v_sub_f32_e32 v0, v73, v163
	v_add_f32_e32 v68, v168, v68
	v_add_f32_e32 v69, v169, v69
	v_exp_f32_e32 v177, v0
	v_sub_f32_e32 v0, v74, v163
	v_add_f32_e32 v68, v170, v68
	v_add_f32_e32 v69, v171, v69
	v_exp_f32_e32 v179, v0
	v_sub_f32_e32 v0, v75, v163
	v_add_f32_e32 v68, v172, v68
	v_add_f32_e32 v69, v173, v69
	v_exp_f32_e32 v181, v0
	v_sub_f32_e32 v0, v76, v163
	v_exp_f32_e32 v183, v0
	v_sub_f32_e32 v0, v77, v163
	v_add_f32_e32 v68, v174, v68
	v_add_f32_e32 v69, v175, v69
	v_exp_f32_e32 v185, v0
	v_sub_f32_e32 v0, v78, v163
	v_add_f32_e32 v68, v176, v68
	v_add_f32_e32 v69, v177, v69
	v_exp_f32_e32 v187, v0
	v_sub_f32_e32 v0, v79, v163
	v_add_f32_e32 v68, v178, v68
	v_add_f32_e32 v69, v179, v69
	v_exp_f32_e32 v189, v0
	v_sub_f32_e32 v0, v80, v163
	v_add_f32_e32 v68, v180, v68
	v_add_f32_e32 v69, v181, v69
	v_exp_f32_e32 v191, v0
	v_sub_f32_e32 v0, v81, v163
	v_add_f32_e32 v68, v182, v68
	v_add_f32_e32 v69, v183, v69
	v_exp_f32_e32 v193, v0
	v_add_f32_e32 v68, v184, v68
	v_add_f32_e32 v69, v185, v69
	v_exp_f32_e32 v195, v82
	v_add_f32_e32 v68, v186, v68
	v_add_f32_e32 v69, v187, v69
	v_cvt_pk_bf16_f32 v70, v171, v173
	v_add_f32_e32 v68, v188, v68
	v_add_f32_e32 v69, v189, v69
	v_cvt_pk_bf16_f32 v71, v175, v177
	v_add_f32_e32 v68, v190, v68
	v_add_f32_e32 v69, v191, v69
	v_cvt_pk_bf16_f32 v72, v179, v181
	v_add_f32_e32 v68, v192, v68
	v_add_f32_e32 v69, v193, v69
	v_cvt_pk_bf16_f32 v73, v183, v185
	v_pk_fma_f32 v[152:153], v[152:153], v[194:195], v[68:69]
	v_mov_b32_e32 v68, v195
	v_pk_mul_f32 v[20:21], v[20:21], v[68:69] op_sel_hi:[1,0]
	v_pk_mul_f32 v[22:23], v[22:23], v[68:69] op_sel_hi:[1,0]
	v_pk_mul_f32 v[24:25], v[24:25], v[68:69] op_sel_hi:[1,0]
	v_pk_mul_f32 v[26:27], v[26:27], v[68:69] op_sel_hi:[1,0]
	v_pk_mul_f32 v[28:29], v[28:29], v[68:69] op_sel_hi:[1,0]
	v_pk_mul_f32 v[30:31], v[30:31], v[68:69] op_sel_hi:[1,0]
	v_pk_mul_f32 v[32:33], v[32:33], v[68:69] op_sel_hi:[1,0]
	v_pk_mul_f32 v[34:35], v[34:35], v[68:69] op_sel_hi:[1,0]
	v_pk_mul_f32 v[18:19], v[18:19], v[68:69] op_sel_hi:[1,0]
	v_pk_mul_f32 v[16:17], v[16:17], v[68:69] op_sel_hi:[1,0]
	v_pk_mul_f32 v[14:15], v[14:15], v[68:69] op_sel_hi:[1,0]
	v_pk_mul_f32 v[12:13], v[12:13], v[68:69] op_sel_hi:[1,0]
	v_pk_mul_f32 v[10:11], v[10:11], v[68:69] op_sel_hi:[1,0]
	v_pk_mul_f32 v[8:9], v[8:9], v[68:69] op_sel_hi:[1,0]
	v_pk_mul_f32 v[6:7], v[6:7], v[68:69] op_sel_hi:[1,0]
	v_pk_mul_f32 v[4:5], v[4:5], v[68:69] op_sel_hi:[1,0]
	v_cvt_pk_bf16_f32 v68, v151, v165
	v_cvt_pk_bf16_f32 v69, v167, v169
	v_cvt_pk_bf16_f32 v74, v187, v189
	v_cvt_pk_bf16_f32 v75, v191, v193
	v_mfma_f32_32x32x16_bf16 v[20:35], v[96:99], v[68:71], v[20:35]
	v_mov_b32_e32 v150, v162
	v_mov_b32_e32 v151, v163
	v_mfma_f32_32x32x16_bf16 v[4:19], v[88:91], v[68:71], v[4:19]
	v_mfma_f32_32x32x16_bf16 v[20:35], v[92:95], v[72:75], v[20:35]
	v_mfma_f32_32x32x16_bf16 v[4:19], v[84:87], v[72:75], v[4:19]

.LBB0_987:
	v_sub_f32_e32 v68, v68, v162
	v_sub_f32_e32 v69, v69, v162
	v_mul_u32_u24_e32 v0, 0x208, v159
	v_exp_f32_e32 v154, v68
	v_exp_f32_e32 v155, v69
	v_sub_f32_e32 v68, v70, v162
	v_sub_f32_e32 v69, v71, v162
	v_readlane_b32 s4, v254, 44
	v_exp_f32_e32 v156, v68
	v_exp_f32_e32 v157, v69
	v_sub_f32_e32 v68, v72, v162
	v_sub_f32_e32 v69, v73, v162
	v_add3_u32 v172, s4, v0, v220
	v_exp_f32_e32 v158, v68
	v_exp_f32_e32 v159, v69
	v_sub_f32_e32 v68, v74, v162
	v_sub_f32_e32 v69, v75, v162
	v_sub_f32_e32 v72, v76, v162
	v_sub_f32_e32 v73, v77, v162
	v_exp_f32_e32 v160, v68
	v_exp_f32_e32 v161, v69
	ds_read2_b64 v[68:71], v172 offset1:2
	v_add_u32_e32 v173, 0x4000, v172
	v_exp_f32_e32 v164, v72
	v_exp_f32_e32 v165, v73
	ds_read2_b64 v[72:75], v173 offset0:32 offset1:34
	v_cvt_pk_bf16_f32 v84, v154, v155
	v_cvt_pk_bf16_f32 v85, v156, v157
	v_cvt_pk_bf16_f32 v86, v158, v159
	v_cvt_pk_bf16_f32 v87, v160, v161
	v_sub_f32_e32 v100, v100, v162
	v_sub_f32_e32 v101, v101, v162
	v_sub_f32_e32 v102, v102, v162
	v_sub_f32_e32 v103, v103, v162
	s_waitcnt lgkmcnt(1)
	v_mfma_f32_32x32x16_bf16 v[52:67], v[68:71], v[84:87], v[52:67]
	v_add_f32_e64 v68, v78, -v162
	v_add_f32_e64 v69, v79, -v162
	v_add_f32_e64 v104, v104, -v162
	v_add_f32_e64 v105, v105, -v162
	v_exp_f32_e32 v166, v68
	v_exp_f32_e32 v167, v69
	v_sub_f32_e32 v68, v80, v162
	v_sub_f32_e32 v69, v81, v162
	v_sub_f32_e32 v106, v106, v162
	v_sub_f32_e32 v107, v107, v162
	v_exp_f32_e32 v168, v68
	v_exp_f32_e32 v169, v69
	ds_read2_b64 v[68:71], v172 offset0:4 offset1:6
	s_waitcnt lgkmcnt(1)
	v_mfma_f32_32x32x16_bf16 v[36:51], v[72:75], v[84:87], v[36:51]
	v_add_f32_e64 v72, v82, -v162
	v_add_f32_e64 v73, v83, -v162
	v_cvt_pk_bf16_f32 v74, v168, v169
	v_exp_f32_e32 v170, v72
	v_exp_f32_e32 v171, v73
	v_cvt_pk_bf16_f32 v72, v164, v165
	v_cvt_pk_bf16_f32 v73, v166, v167
	v_exp_f32_e32 v100, v100
	v_cvt_pk_bf16_f32 v75, v170, v171
	v_exp_f32_e32 v101, v101
	v_exp_f32_e32 v102, v102
	s_waitcnt lgkmcnt(0)
	v_mfma_f32_32x32x16_bf16 v[52:67], v[68:71], v[72:75], v[52:67]
	ds_read2_b64 v[68:71], v173 offset0:36 offset1:38
	v_exp_f32_e32 v103, v103
	v_exp_f32_e32 v104, v104
	v_exp_f32_e32 v105, v105
	v_exp_f32_e32 v106, v106
	v_exp_f32_e32 v107, v107
	v_sub_f32_e32 v108, v108, v162
	v_sub_f32_e32 v109, v109, v162
	s_waitcnt lgkmcnt(0)
	v_mfma_f32_32x32x16_bf16 v[36:51], v[68:71], v[72:75], v[36:51]
	ds_read_b128 v[68:71], v222
	ds_read_b128 v[174:177], v222 offset:32
	ds_read_b128 v[84:87], v222 offset:4608
	ds_read_b128 v[178:181], v222 offset:4640
	v_add_f32_e64 v110, v110, -v162
	v_add_f32_e64 v111, v111, -v162
	v_sub_f32_e32 v112, v112, v162
	v_sub_f32_e32 v113, v113, v162
	v_sub_f32_e32 v114, v114, v162
	v_sub_f32_e32 v115, v115, v162
	v_exp_f32_e32 v108, v108
	v_exp_f32_e32 v109, v109
	s_waitcnt lgkmcnt(3)
	v_mfma_f32_32x32x16_bf16 v[68:83], v[68:71], v[128:131], 0
	v_exp_f32_e32 v110, v110
	v_exp_f32_e32 v111, v111
	v_exp_f32_e32 v112, v112
	v_exp_f32_e32 v113, v113
	v_exp_f32_e32 v114, v114
	v_exp_f32_e32 v115, v115
	v_cvt_pk_bf16_f32 v228, v108, v109
	s_waitcnt lgkmcnt(1)
	v_mfma_f32_32x32x16_bf16 v[84:99], v[84:87], v[128:131], 0
	v_cvt_pk_bf16_f32 v229, v110, v111
	v_cvt_pk_bf16_f32 v230, v112, v113
	v_cvt_pk_bf16_f32 v231, v114, v115
	v_mfma_f32_32x32x16_bf16 v[68:83], v[174:177], v[124:127], v[68:83]
	ds_read_b128 v[174:177], v222 offset:64
	s_waitcnt lgkmcnt(1)
	v_mfma_f32_32x32x16_bf16 v[84:99], v[178:181], v[124:127], v[84:99]
	ds_read_b128 v[178:181], v222 offset:4672
	ds_read_b128 v[182:185], v222 offset:96
	s_waitcnt lgkmcnt(2)
	v_mfma_f32_32x32x16_bf16 v[68:83], v[174:177], v[120:123], v[68:83]
	ds_read_b128 v[174:177], v222 offset:4704
	s_waitcnt lgkmcnt(2)
	v_mfma_f32_32x32x16_bf16 v[84:99], v[178:181], v[120:123], v[84:99]
	ds_read2_b64 v[178:181], v172 offset0:8 offset1:10
	ds_read2_b64 v[186:189], v173 offset0:40 offset1:42
	ds_read2_b64 v[190:193], v172 offset0:12 offset1:14
	ds_read2_b64 v[224:227], v173 offset0:44 offset1:46
	s_waitcnt lgkmcnt(5)
	v_mfma_f32_32x32x16_bf16 v[68:83], v[182:185], v[116:119], v[68:83]
	v_cvt_pk_bf16_f32 v182, v100, v101
	v_cvt_pk_bf16_f32 v183, v102, v103
	v_cvt_pk_bf16_f32 v184, v104, v105
	v_cvt_pk_bf16_f32 v185, v106, v107
	s_waitcnt lgkmcnt(4)
	v_mfma_f32_32x32x16_bf16 v[84:99], v[174:177], v[116:119], v[84:99]
	s_waitcnt lgkmcnt(3)
	v_mfma_f32_32x32x16_bf16 v[52:67], v[178:181], v[182:185], v[52:67]
	s_nop 9
	v_maximum3_f32 v0, v69, v85, v85
	v_maximum3_f32 v0, v68, v84, v0
	v_maximum3_f32 v1, v70, v86, v86
	v_maximum3_f32 v2, v71, v87, v87
	v_maximum3_f32 v0, v0, v1, v2
	v_maximum3_f32 v1, v72, v88, v88
	v_maximum3_f32 v2, v73, v89, v89
	s_waitcnt lgkmcnt(2)
	v_mfma_f32_32x32x16_bf16 v[36:51], v[186:189], v[182:185], v[36:51]
	v_maximum3_f32 v0, v0, v1, v2
	v_maximum3_f32 v1, v74, v90, v90
	v_maximum3_f32 v2, v75, v91, v91
	v_maximum3_f32 v0, v0, v1, v2
	v_maximum3_f32 v1, v76, v92, v92
	v_maximum3_f32 v2, v77, v93, v93
	v_maximum3_f32 v0, v0, v1, v2
	v_maximum3_f32 v1, v78, v94, v94
	v_maximum3_f32 v2, v79, v95, v95
	v_maximum3_f32 v0, v0, v1, v2
	v_maximum3_f32 v1, v80, v96, v96
	v_maximum3_f32 v2, v81, v97, v97
	s_waitcnt lgkmcnt(1)
	v_mfma_f32_32x32x16_bf16 v[52:67], v[190:193], v[228:231], v[52:67]
	v_maximum3_f32 v0, v0, v1, v2
	v_maximum3_f32 v1, v82, v98, v98
	v_maximum3_f32 v2, v83, v99, v99
	v_maximum3_f32 v0, v0, v1, v2
	v_mov_b32_e32 v1, v0
	s_waitcnt lgkmcnt(0)
	v_mfma_f32_32x32x16_bf16 v[36:51], v[224:227], v[228:231], v[36:51]
	v_permlane32_swap_b32_e32 v0, v1
	s_nop 0
	v_maximum3_f32 v2, v0, v1, v1
	v_cmp_gt_f32_e32 vcc, v2, v151
	s_cbranch_vccz .LBB0_989
	v_maximum3_f32 v2, v151, v2, v2
	v_sub_f32_e32 v0, v151, v2
	v_exp_f32_e32 v162, v0
	v_mov_b32_e32 v151, v2
	v_mul_f32_e32 v153, v153, v162
	v_pk_mul_f32 v[20:21], v[20:21], v[162:163] op_sel_hi:[1,0]
	v_pk_mul_f32 v[22:23], v[22:23], v[162:163] op_sel_hi:[1,0]
	v_pk_mul_f32 v[24:25], v[24:25], v[162:163] op_sel_hi:[1,0]
	v_pk_mul_f32 v[26:27], v[26:27], v[162:163] op_sel_hi:[1,0]
	v_pk_mul_f32 v[28:29], v[28:29], v[162:163] op_sel_hi:[1,0]
	v_pk_mul_f32 v[30:31], v[30:31], v[162:163] op_sel_hi:[1,0]
	v_pk_mul_f32 v[32:33], v[32:33], v[162:163] op_sel_hi:[1,0]
	v_pk_mul_f32 v[34:35], v[34:35], v[162:163] op_sel_hi:[1,0]
	v_pk_mul_f32 v[18:19], v[18:19], v[162:163] op_sel_hi:[1,0]
	v_pk_mul_f32 v[16:17], v[16:17], v[162:163] op_sel_hi:[1,0]
	v_pk_mul_f32 v[14:15], v[14:15], v[162:163] op_sel_hi:[1,0]
	v_pk_mul_f32 v[12:13], v[12:13], v[162:163] op_sel_hi:[1,0]
	v_pk_mul_f32 v[10:11], v[10:11], v[162:163] op_sel_hi:[1,0]
	v_pk_mul_f32 v[8:9], v[8:9], v[162:163] op_sel_hi:[1,0]
	v_pk_mul_f32 v[6:7], v[6:7], v[162:163] op_sel_hi:[1,0]
	v_pk_mul_f32 v[4:5], v[4:5], v[162:163] op_sel_hi:[1,0]
	s_branch .LBB0_990

.LBB0_990:
	v_add_f32_e32 v100, v100, v154
	v_add_f32_e32 v101, v101, v155
	v_add_f32_e32 v102, v102, v156
	v_add_f32_e32 v103, v103, v157
	v_pk_add_f32 v[100:101], v[100:101], 0 op_sel_hi:[1,0]
	v_sub_f32_e32 v68, v68, v2
	v_sub_f32_e32 v69, v69, v2
	v_add_f32_e32 v100, v102, v100
	v_add_f32_e32 v101, v103, v101
	v_add_f32_e32 v102, v104, v158
	v_add_f32_e32 v103, v105, v159
	v_sub_f32_e32 v84, v84, v2
	v_sub_f32_e32 v85, v85, v2
	v_add_f32_e32 v100, v102, v100
	v_add_f32_e32 v101, v103, v101
	v_add_f32_e32 v102, v106, v160
	v_add_f32_e32 v103, v107, v161
	s_nop 0
	v_add_f32_e32 v100, v102, v100
	v_add_f32_e32 v101, v103, v101
	v_add_f32_e32 v102, v108, v164
	v_add_f32_e32 v103, v109, v165
	s_nop 0
	v_add_f32_e32 v100, v102, v100
	v_add_f32_e32 v101, v103, v101
	v_add_f32_e32 v102, v110, v166
	v_add_f32_e32 v103, v111, v167
	s_nop 0
	v_add_f32_e32 v100, v102, v100
	v_add_f32_e32 v101, v103, v101
	v_add_f32_e32 v102, v112, v168
	v_add_f32_e32 v103, v113, v169
	s_nop 0
	v_add_f32_e32 v100, v102, v100
	v_add_f32_e32 v101, v103, v101
	v_add_f32_e32 v102, v114, v170
	v_add_f32_e32 v103, v115, v171
	s_nop 0
	v_add_f32_e32 v100, v102, v100
	v_add_f32_e32 v101, v103, v101
	v_exp_f32_e32 v102, v84
	v_add_f32_e32 v0, v100, v101
	v_exp_f32_e32 v100, v68
	v_exp_f32_e32 v101, v69
	v_sub_f32_e32 v68, v70, v2
	v_sub_f32_e32 v69, v71, v2
	v_sub_f32_e32 v70, v86, v2
	v_sub_f32_e32 v71, v87, v2
	v_exp_f32_e32 v104, v68
	v_exp_f32_e32 v105, v69
	v_exp_f32_e32 v106, v70
	v_exp_f32_e32 v107, v71
	v_sub_f32_e32 v68, v72, v2
	v_sub_f32_e32 v69, v73, v2
	v_sub_f32_e32 v70, v88, v2
	v_sub_f32_e32 v71, v89, v2
	v_exp_f32_e32 v108, v68
	v_exp_f32_e32 v109, v69
	v_exp_f32_e32 v110, v70
	v_exp_f32_e32 v111, v71
	v_sub_f32_e32 v68, v74, v2
	v_sub_f32_e32 v69, v75, v2
	v_sub_f32_e32 v70, v90, v2
	v_sub_f32_e32 v71, v91, v2
	v_exp_f32_e32 v112, v68
	v_exp_f32_e32 v113, v69
	v_exp_f32_e32 v114, v70
	v_exp_f32_e32 v115, v71
	v_sub_f32_e32 v68, v76, v2
	v_sub_f32_e32 v69, v77, v2
	v_sub_f32_e32 v70, v92, v2
	v_sub_f32_e32 v71, v93, v2
	v_exp_f32_e32 v154, v68
	v_exp_f32_e32 v155, v69
	v_exp_f32_e32 v156, v70
	v_exp_f32_e32 v157, v71
	v_sub_f32_e32 v68, v78, v2
	v_sub_f32_e32 v69, v79, v2
	v_sub_f32_e32 v70, v94, v2
	v_sub_f32_e32 v71, v95, v2
	v_exp_f32_e32 v158, v68
	v_exp_f32_e32 v159, v69
	v_exp_f32_e32 v160, v70
	v_exp_f32_e32 v161, v71
	v_sub_f32_e32 v68, v80, v2
	v_sub_f32_e32 v69, v81, v2
	v_sub_f32_e32 v70, v96, v2
	v_sub_f32_e32 v71, v97, v2
	v_exp_f32_e32 v162, v68
	v_exp_f32_e32 v163, v69
	v_exp_f32_e32 v164, v70
	v_exp_f32_e32 v165, v71
	v_sub_f32_e32 v68, v82, v2
	v_sub_f32_e32 v69, v83, v2
	v_sub_f32_e32 v70, v98, v2
	v_sub_f32_e32 v71, v99, v2
	v_exp_f32_e32 v103, v85
	v_exp_f32_e32 v166, v68
	v_exp_f32_e32 v167, v69
	v_exp_f32_e32 v168, v70
	v_exp_f32_e32 v169, v71
	ds_read2_b64 v[84:87], v173 offset0:32 offset1:34
	ds_read2_b64 v[72:75], v172 offset0:8 offset1:10
	ds_read2_b64 v[68:71], v173 offset0:40 offset1:42
	ds_read2_b64 v[88:91], v172 offset1:2
	ds_read2_b64 v[92:95], v172 offset0:4 offset1:6
	ds_read2_b64 v[96:99], v173 offset0:36 offset1:38
	ds_read2_b64 v[80:83], v172 offset0:12 offset1:14
	ds_read2_b64 v[76:79], v173 offset0:44 offset1:46
	v_cvt_pk_bf16_f32 v174, v100, v101
	v_cvt_pk_bf16_f32 v175, v104, v105
	v_cvt_pk_bf16_f32 v176, v108, v109
	v_cvt_pk_bf16_f32 v177, v112, v113
	v_cvt_pk_bf16_f32 v178, v154, v155
	v_cvt_pk_bf16_f32 v179, v158, v159
	s_waitcnt lgkmcnt(4)
	v_mfma_f32_32x32x16_bf16 v[20:35], v[88:91], v[174:177], v[20:35]
	v_cvt_pk_bf16_f32 v180, v162, v163
	v_cvt_pk_bf16_f32 v181, v166, v167
	v_cvt_pk_bf16_f32 v182, v102, v103
	v_cvt_pk_bf16_f32 v183, v106, v107
	v_cvt_pk_bf16_f32 v184, v110, v111
	v_cvt_pk_bf16_f32 v185, v114, v115
	v_cvt_pk_bf16_f32 v186, v156, v157
	v_mfma_f32_32x32x16_bf16 v[4:19], v[84:87], v[174:177], v[4:19]
	v_cvt_pk_bf16_f32 v187, v160, v161
	v_cvt_pk_bf16_f32 v188, v164, v165
	v_cvt_pk_bf16_f32 v189, v168, v169
	v_add_f32_e32 v170, v152, v0
	s_waitcnt lgkmcnt(3)
	v_mfma_f32_32x32x16_bf16 v[20:35], v[92:95], v[178:181], v[20:35]
	s_waitcnt lgkmcnt(2)
	v_mfma_f32_32x32x16_bf16 v[4:19], v[96:99], v[178:181], v[4:19]
	v_mfma_f32_32x32x16_bf16 v[20:35], v[72:75], v[182:185], v[20:35]
	v_mfma_f32_32x32x16_bf16 v[4:19], v[68:71], v[182:185], v[4:19]
	s_waitcnt lgkmcnt(1)
	v_mfma_f32_32x32x16_bf16 v[20:35], v[80:83], v[186:189], v[20:35]
	s_waitcnt lgkmcnt(0)
	v_mfma_f32_32x32x16_bf16 v[4:19], v[76:79], v[186:189], v[4:19]
	ds_read_b128 v[84:87], v222 offset:13824
	ds_read_b128 v[68:71], v222 offset:9216
	ds_read_b128 v[174:177], v222 offset:9248
	ds_read_b128 v[178:181], v222 offset:13856
	ds_read_b128 v[182:185], v222 offset:9280
	ds_read_b128 v[186:189], v222 offset:13888
	ds_read_b128 v[190:193], v222 offset:9312
	ds_read_b128 v[224:227], v222 offset:13920
	s_waitcnt lgkmcnt(6)
	v_mfma_f32_32x32x16_bf16 v[68:83], v[68:71], v[144:147], 0
	v_mfma_f32_32x32x16_bf16 v[84:99], v[84:87], v[144:147], 0
	s_waitcnt lgkmcnt(5)
	v_mfma_f32_32x32x16_bf16 v[68:83], v[174:177], v[140:143], v[68:83]
	s_waitcnt lgkmcnt(4)
	v_mfma_f32_32x32x16_bf16 v[84:99], v[178:181], v[140:143], v[84:99]
	s_waitcnt lgkmcnt(3)
	v_mfma_f32_32x32x16_bf16 v[68:83], v[182:185], v[136:139], v[68:83]
	s_waitcnt lgkmcnt(2)
	v_mfma_f32_32x32x16_bf16 v[84:99], v[186:189], v[136:139], v[84:99]
	s_waitcnt lgkmcnt(1)
	v_mfma_f32_32x32x16_bf16 v[68:83], v[190:193], v[132:135], v[68:83]
	s_waitcnt lgkmcnt(0)
	v_mfma_f32_32x32x16_bf16 v[84:99], v[224:227], v[132:135], v[84:99]
	s_nop 11
	v_maximum3_f32 v0, v69, v85, v85
	v_maximum3_f32 v0, v68, v84, v0
	v_maximum3_f32 v1, v70, v86, v86
	v_maximum3_f32 v2, v71, v87, v87
	v_maximum3_f32 v0, v0, v1, v2
	v_maximum3_f32 v1, v72, v88, v88
	v_maximum3_f32 v2, v73, v89, v89
	v_maximum3_f32 v0, v0, v1, v2
	v_maximum3_f32 v1, v74, v90, v90
	v_maximum3_f32 v2, v75, v91, v91
	v_maximum3_f32 v0, v0, v1, v2
	v_maximum3_f32 v1, v76, v92, v92
	v_maximum3_f32 v2, v77, v93, v93
	v_maximum3_f32 v0, v0, v1, v2
	v_maximum3_f32 v1, v78, v94, v94
	v_maximum3_f32 v2, v79, v95, v95
	v_maximum3_f32 v0, v0, v1, v2
	v_maximum3_f32 v1, v80, v96, v96
	v_maximum3_f32 v2, v81, v97, v97
	v_maximum3_f32 v0, v0, v1, v2
	v_maximum3_f32 v1, v82, v98, v98
	v_maximum3_f32 v2, v83, v99, v99
	v_maximum3_f32 v0, v0, v1, v2
	v_mov_b32_e32 v1, v0
	s_nop 1
	v_permlane32_swap_b32_e32 v0, v1
	s_nop 0
	v_maximum3_f32 v2, v0, v1, v1
	v_cmp_gt_f32_e32 vcc, v2, v150
	s_cbranch_vccz .LBB0_992
	v_maximum3_f32 v2, v150, v2, v2
	v_sub_f32_e32 v0, v150, v2
	v_exp_f32_e32 v150, v0
	s_nop 0
	v_mul_f32_e32 v170, v170, v150
	v_pk_mul_f32 v[52:53], v[52:53], v[150:151] op_sel_hi:[1,0]
	v_pk_mul_f32 v[54:55], v[54:55], v[150:151] op_sel_hi:[1,0]
	v_pk_mul_f32 v[56:57], v[56:57], v[150:151] op_sel_hi:[1,0]
	v_pk_mul_f32 v[58:59], v[58:59], v[150:151] op_sel_hi:[1,0]
	v_pk_mul_f32 v[60:61], v[60:61], v[150:151] op_sel_hi:[1,0]
	v_pk_mul_f32 v[62:63], v[62:63], v[150:151] op_sel_hi:[1,0]
	v_pk_mul_f32 v[64:65], v[64:65], v[150:151] op_sel_hi:[1,0]
	v_pk_mul_f32 v[66:67], v[66:67], v[150:151] op_sel_hi:[1,0]
	v_pk_mul_f32 v[50:51], v[50:51], v[150:151] op_sel_hi:[1,0]
	v_pk_mul_f32 v[48:49], v[48:49], v[150:151] op_sel_hi:[1,0]
	v_pk_mul_f32 v[46:47], v[46:47], v[150:151] op_sel_hi:[1,0]
	v_pk_mul_f32 v[44:45], v[44:45], v[150:151] op_sel_hi:[1,0]
	v_pk_mul_f32 v[42:43], v[42:43], v[150:151] op_sel_hi:[1,0]
	v_pk_mul_f32 v[40:41], v[40:41], v[150:151] op_sel_hi:[1,0]
	v_pk_mul_f32 v[38:39], v[38:39], v[150:151] op_sel_hi:[1,0]
	v_pk_mul_f32 v[36:37], v[36:37], v[150:151] op_sel_hi:[1,0]
	v_mov_b32_e32 v150, v2
	s_branch .LBB0_993

.LBB0_993:
	v_add_f32_e32 v100, v102, v100
	v_add_f32_e32 v101, v103, v101
	v_add_f32_e32 v102, v106, v104
	v_add_f32_e32 v103, v107, v105
	v_pk_add_f32 v[100:101], v[100:101], 0 op_sel_hi:[1,0]
	v_sub_f32_e32 v68, v68, v2
	v_sub_f32_e32 v69, v69, v2
	v_add_f32_e32 v100, v102, v100
	v_add_f32_e32 v101, v103, v101
	v_add_f32_e32 v102, v110, v108
	v_add_f32_e32 v103, v111, v109
	v_sub_f32_e32 v84, v84, v2
	v_sub_f32_e32 v85, v85, v2
	v_add_f32_e32 v100, v102, v100
	v_add_f32_e32 v101, v103, v101
	v_add_f32_e32 v102, v114, v112
	v_add_f32_e32 v103, v115, v113
	s_nop 0
	v_add_f32_e32 v100, v102, v100
	v_add_f32_e32 v101, v103, v101
	v_add_f32_e32 v102, v156, v154
	v_add_f32_e32 v103, v157, v155
	s_nop 0
	v_add_f32_e32 v100, v102, v100
	v_add_f32_e32 v101, v103, v101
	v_add_f32_e32 v102, v160, v158
	v_add_f32_e32 v103, v161, v159
	s_nop 0
	v_add_f32_e32 v100, v102, v100
	v_add_f32_e32 v101, v103, v101
	v_add_f32_e32 v102, v164, v162
	v_add_f32_e32 v103, v165, v163
	s_nop 0
	v_add_f32_e32 v100, v102, v100
	v_add_f32_e32 v101, v103, v101
	v_add_f32_e32 v102, v168, v166
	v_add_f32_e32 v103, v169, v167
	s_nop 0
	v_add_f32_e32 v100, v102, v100
	v_add_f32_e32 v101, v103, v101
	v_exp_f32_e32 v102, v84
	v_add_f32_e32 v0, v100, v101
	v_exp_f32_e32 v100, v68
	v_exp_f32_e32 v101, v69
	v_sub_f32_e32 v68, v70, v2
	v_sub_f32_e32 v69, v71, v2
	v_sub_f32_e32 v70, v86, v2
	v_sub_f32_e32 v71, v87, v2
	v_exp_f32_e32 v104, v68
	v_exp_f32_e32 v105, v69
	v_exp_f32_e32 v106, v70
	v_exp_f32_e32 v107, v71
	v_sub_f32_e32 v68, v72, v2
	v_sub_f32_e32 v69, v73, v2
	v_sub_f32_e32 v70, v88, v2
	v_sub_f32_e32 v71, v89, v2
	v_exp_f32_e32 v108, v68
	v_exp_f32_e32 v109, v69
	v_exp_f32_e32 v110, v70
	v_exp_f32_e32 v111, v71
	v_sub_f32_e32 v68, v74, v2
	v_sub_f32_e32 v69, v75, v2
	v_sub_f32_e32 v70, v90, v2
	v_sub_f32_e32 v71, v91, v2
	v_exp_f32_e32 v112, v68
	v_exp_f32_e32 v113, v69
	v_exp_f32_e32 v114, v70
	v_exp_f32_e32 v115, v71
	v_sub_f32_e32 v68, v76, v2
	v_sub_f32_e32 v69, v77, v2
	v_sub_f32_e32 v70, v92, v2
	v_sub_f32_e32 v71, v93, v2
	v_add_f32_e32 v168, v153, v0
	v_exp_f32_e32 v152, v68
	v_exp_f32_e32 v153, v69
	v_exp_f32_e32 v154, v70
	v_exp_f32_e32 v155, v71
	v_sub_f32_e32 v68, v78, v2
	v_sub_f32_e32 v69, v79, v2
	v_sub_f32_e32 v70, v94, v2
	v_sub_f32_e32 v71, v95, v2
	v_exp_f32_e32 v156, v68
	v_exp_f32_e32 v157, v69
	v_exp_f32_e32 v158, v70
	v_exp_f32_e32 v159, v71
	v_sub_f32_e32 v68, v80, v2
	v_sub_f32_e32 v69, v81, v2
	v_sub_f32_e32 v70, v96, v2
	v_sub_f32_e32 v71, v97, v2
	v_exp_f32_e32 v160, v68
	v_exp_f32_e32 v161, v69
	v_exp_f32_e32 v162, v70
	v_exp_f32_e32 v163, v71
	v_sub_f32_e32 v68, v82, v2
	v_sub_f32_e32 v69, v83, v2
	v_sub_f32_e32 v70, v98, v2
	v_sub_f32_e32 v71, v99, v2
	v_exp_f32_e32 v103, v85
	v_exp_f32_e32 v164, v68
	v_exp_f32_e32 v165, v69
	v_exp_f32_e32 v166, v70
	v_exp_f32_e32 v167, v71
	ds_read2_b64 v[84:87], v173 offset0:48 offset1:50
	ds_read2_b64 v[72:75], v172 offset0:24 offset1:26
	ds_read2_b64 v[68:71], v173 offset0:56 offset1:58
	ds_read2_b64 v[88:91], v172 offset0:16 offset1:18
	ds_read2_b64 v[92:95], v172 offset0:20 offset1:22
	ds_read2_b64 v[96:99], v173 offset0:52 offset1:54
	ds_read2_b64 v[80:83], v172 offset0:28 offset1:30
	ds_read2_b64 v[76:79], v173 offset0:60 offset1:62
	v_cvt_pk_bf16_f32 v174, v100, v101
	v_cvt_pk_bf16_f32 v175, v104, v105
	v_cvt_pk_bf16_f32 v176, v108, v109
	v_cvt_pk_bf16_f32 v177, v112, v113
	v_cvt_pk_bf16_f32 v178, v152, v153
	v_cvt_pk_bf16_f32 v179, v156, v157
	s_waitcnt lgkmcnt(4)
	v_mfma_f32_32x32x16_bf16 v[52:67], v[88:91], v[174:177], v[52:67]
	v_cvt_pk_bf16_f32 v180, v160, v161
	v_cvt_pk_bf16_f32 v181, v164, v165
	v_cvt_pk_bf16_f32 v182, v102, v103
	v_cvt_pk_bf16_f32 v183, v106, v107
	v_cvt_pk_bf16_f32 v184, v110, v111
	v_cvt_pk_bf16_f32 v185, v114, v115
	v_cvt_pk_bf16_f32 v186, v154, v155
	v_mfma_f32_32x32x16_bf16 v[36:51], v[84:87], v[174:177], v[36:51]
	v_cvt_pk_bf16_f32 v187, v158, v159
	v_cvt_pk_bf16_f32 v188, v162, v163
	v_cvt_pk_bf16_f32 v189, v166, v167
	s_waitcnt lgkmcnt(3)
	v_mfma_f32_32x32x16_bf16 v[52:67], v[92:95], v[178:181], v[52:67]
	s_waitcnt lgkmcnt(2)
	v_mfma_f32_32x32x16_bf16 v[36:51], v[96:99], v[178:181], v[36:51]
	v_mfma_f32_32x32x16_bf16 v[52:67], v[72:75], v[182:185], v[52:67]
	v_mfma_f32_32x32x16_bf16 v[36:51], v[68:71], v[182:185], v[36:51]
	s_waitcnt lgkmcnt(1)
	v_mfma_f32_32x32x16_bf16 v[52:67], v[80:83], v[186:189], v[52:67]
	s_waitcnt lgkmcnt(0)
	v_mfma_f32_32x32x16_bf16 v[36:51], v[76:79], v[186:189], v[36:51]
	ds_read_b128 v[84:87], v222 offset:13824
	ds_read_b128 v[68:71], v222 offset:9216
	ds_read_b128 v[174:177], v222 offset:9248
	ds_read_b128 v[178:181], v222 offset:13856
	ds_read_b128 v[182:185], v222 offset:9280
	ds_read_b128 v[186:189], v222 offset:13888
	ds_read_b128 v[190:193], v222 offset:9312
	ds_read_b128 v[224:227], v222 offset:13920
	s_waitcnt lgkmcnt(6)
	v_mfma_f32_32x32x16_bf16 v[68:83], v[68:71], v[128:131], 0
	v_mfma_f32_32x32x16_bf16 v[84:99], v[84:87], v[128:131], 0
	s_waitcnt lgkmcnt(5)
	v_mfma_f32_32x32x16_bf16 v[68:83], v[174:177], v[124:127], v[68:83]
	s_waitcnt lgkmcnt(4)
	v_mfma_f32_32x32x16_bf16 v[84:99], v[178:181], v[124:127], v[84:99]
	s_waitcnt lgkmcnt(3)
	v_mfma_f32_32x32x16_bf16 v[68:83], v[182:185], v[120:123], v[68:83]
	s_waitcnt lgkmcnt(2)
	v_mfma_f32_32x32x16_bf16 v[84:99], v[186:189], v[120:123], v[84:99]
	s_waitcnt lgkmcnt(1)
	v_mfma_f32_32x32x16_bf16 v[68:83], v[190:193], v[116:119], v[68:83]
	s_waitcnt lgkmcnt(0)
	v_mfma_f32_32x32x16_bf16 v[84:99], v[224:227], v[116:119], v[84:99]
	s_nop 11
	v_maximum3_f32 v0, v69, v85, v85
	v_maximum3_f32 v0, v68, v84, v0
	v_maximum3_f32 v1, v70, v86, v86
	v_maximum3_f32 v2, v71, v87, v87
	v_maximum3_f32 v0, v0, v1, v2
	v_maximum3_f32 v1, v72, v88, v88
	v_maximum3_f32 v2, v73, v89, v89
	v_maximum3_f32 v0, v0, v1, v2
	v_maximum3_f32 v1, v74, v90, v90
	v_maximum3_f32 v2, v75, v91, v91
	v_maximum3_f32 v0, v0, v1, v2
	v_maximum3_f32 v1, v76, v92, v92
	v_maximum3_f32 v2, v77, v93, v93
	v_maximum3_f32 v0, v0, v1, v2
	v_maximum3_f32 v1, v78, v94, v94
	v_maximum3_f32 v2, v79, v95, v95
	v_maximum3_f32 v0, v0, v1, v2
	v_maximum3_f32 v1, v80, v96, v96
	v_maximum3_f32 v2, v81, v97, v97
	v_maximum3_f32 v0, v0, v1, v2
	v_maximum3_f32 v1, v82, v98, v98
	v_maximum3_f32 v2, v83, v99, v99
	v_maximum3_f32 v0, v0, v1, v2
	v_mov_b32_e32 v1, v0
	s_nop 1
	v_permlane32_swap_b32_e32 v0, v1
	s_nop 0
	v_maximum3_f32 v2, v0, v1, v1
	v_cmp_gt_f32_e32 vcc, v2, v151
	s_cbranch_vccz .LBB0_995
	v_maximum3_f32 v2, v151, v2, v2
	v_sub_f32_e32 v0, v151, v2
	v_exp_f32_e32 v174, v0
	v_mov_b32_e32 v151, v2
	v_mul_f32_e32 v168, v168, v174
	v_pk_mul_f32 v[20:21], v[20:21], v[174:175] op_sel_hi:[1,0]
	v_pk_mul_f32 v[22:23], v[22:23], v[174:175] op_sel_hi:[1,0]
	v_pk_mul_f32 v[24:25], v[24:25], v[174:175] op_sel_hi:[1,0]
	v_pk_mul_f32 v[26:27], v[26:27], v[174:175] op_sel_hi:[1,0]
	v_pk_mul_f32 v[28:29], v[28:29], v[174:175] op_sel_hi:[1,0]
	v_pk_mul_f32 v[30:31], v[30:31], v[174:175] op_sel_hi:[1,0]
	v_pk_mul_f32 v[32:33], v[32:33], v[174:175] op_sel_hi:[1,0]
	v_pk_mul_f32 v[34:35], v[34:35], v[174:175] op_sel_hi:[1,0]
	v_pk_mul_f32 v[18:19], v[18:19], v[174:175] op_sel_hi:[1,0]
	v_pk_mul_f32 v[16:17], v[16:17], v[174:175] op_sel_hi:[1,0]
	v_pk_mul_f32 v[14:15], v[14:15], v[174:175] op_sel_hi:[1,0]
	v_pk_mul_f32 v[12:13], v[12:13], v[174:175] op_sel_hi:[1,0]
	v_pk_mul_f32 v[10:11], v[10:11], v[174:175] op_sel_hi:[1,0]
	v_pk_mul_f32 v[8:9], v[8:9], v[174:175] op_sel_hi:[1,0]
	v_pk_mul_f32 v[6:7], v[6:7], v[174:175] op_sel_hi:[1,0]
	v_pk_mul_f32 v[4:5], v[4:5], v[174:175] op_sel_hi:[1,0]
	s_branch .LBB0_996

.LBB0_996:
	v_add_f32_e32 v100, v102, v100
	v_add_f32_e32 v101, v103, v101
	v_add_f32_e32 v102, v106, v104
	v_add_f32_e32 v103, v107, v105
	v_pk_add_f32 v[100:101], v[100:101], 0 op_sel_hi:[1,0]
	v_sub_f32_e32 v68, v68, v2
	v_sub_f32_e32 v69, v69, v2
	v_add_f32_e32 v100, v102, v100
	v_add_f32_e32 v101, v103, v101
	v_add_f32_e32 v102, v110, v108
	v_add_f32_e32 v103, v111, v109
	v_sub_f32_e32 v84, v84, v2
	v_sub_f32_e32 v85, v85, v2
	v_add_f32_e32 v100, v102, v100
	v_add_f32_e32 v101, v103, v101
	v_add_f32_e32 v102, v114, v112
	v_add_f32_e32 v103, v115, v113
	s_nop 0
	v_add_f32_e32 v100, v102, v100
	v_add_f32_e32 v101, v103, v101
	v_add_f32_e32 v102, v154, v152
	v_add_f32_e32 v103, v155, v153
	s_nop 0
	v_add_f32_e32 v100, v102, v100
	v_add_f32_e32 v101, v103, v101
	v_add_f32_e32 v102, v158, v156
	v_add_f32_e32 v103, v159, v157
	s_nop 0
	v_add_f32_e32 v100, v102, v100
	v_add_f32_e32 v101, v103, v101
	v_add_f32_e32 v102, v162, v160
	v_add_f32_e32 v103, v163, v161
	s_nop 0
	v_add_f32_e32 v100, v102, v100
	v_add_f32_e32 v101, v103, v101
	v_add_f32_e32 v102, v166, v164
	v_add_f32_e32 v103, v167, v165
	s_nop 0
	v_add_f32_e32 v100, v102, v100
	v_add_f32_e32 v101, v103, v101
	v_exp_f32_e32 v102, v84
	v_add_f32_e32 v0, v100, v101
	v_exp_f32_e32 v100, v68
	v_exp_f32_e32 v101, v69
	v_sub_f32_e32 v68, v70, v2
	v_sub_f32_e32 v69, v71, v2
	v_sub_f32_e32 v70, v86, v2
	v_sub_f32_e32 v71, v87, v2
	v_exp_f32_e32 v104, v68
	v_exp_f32_e32 v105, v69
	v_exp_f32_e32 v106, v70
	v_exp_f32_e32 v107, v71
	v_sub_f32_e32 v68, v72, v2
	v_sub_f32_e32 v69, v73, v2
	v_sub_f32_e32 v70, v88, v2
	v_sub_f32_e32 v71, v89, v2
	v_exp_f32_e32 v108, v68
	v_exp_f32_e32 v109, v69
	v_exp_f32_e32 v110, v70
	v_exp_f32_e32 v111, v71
	v_sub_f32_e32 v68, v74, v2
	v_sub_f32_e32 v69, v75, v2
	v_sub_f32_e32 v70, v90, v2
	v_sub_f32_e32 v71, v91, v2
	v_exp_f32_e32 v112, v68
	v_exp_f32_e32 v113, v69
	v_exp_f32_e32 v114, v70
	v_exp_f32_e32 v115, v71
	v_sub_f32_e32 v68, v76, v2
	v_sub_f32_e32 v69, v77, v2
	v_sub_f32_e32 v70, v92, v2
	v_sub_f32_e32 v71, v93, v2
	v_exp_f32_e32 v152, v68
	v_exp_f32_e32 v153, v69
	v_exp_f32_e32 v154, v70
	v_exp_f32_e32 v155, v71
	v_sub_f32_e32 v68, v78, v2
	v_sub_f32_e32 v69, v79, v2
	v_sub_f32_e32 v70, v94, v2
	v_sub_f32_e32 v71, v95, v2
	v_exp_f32_e32 v156, v68
	v_exp_f32_e32 v157, v69
	v_exp_f32_e32 v158, v70
	v_exp_f32_e32 v159, v71
	v_sub_f32_e32 v68, v80, v2
	v_sub_f32_e32 v69, v81, v2
	v_sub_f32_e32 v70, v96, v2
	v_sub_f32_e32 v71, v97, v2
	v_exp_f32_e32 v160, v68
	v_exp_f32_e32 v161, v69
	v_exp_f32_e32 v162, v70
	v_exp_f32_e32 v163, v71
	v_sub_f32_e32 v68, v82, v2
	v_sub_f32_e32 v69, v83, v2
	v_sub_f32_e32 v70, v98, v2
	v_sub_f32_e32 v71, v99, v2
	v_exp_f32_e32 v103, v85
	v_exp_f32_e32 v164, v68
	v_exp_f32_e32 v165, v69
	v_exp_f32_e32 v166, v70
	v_exp_f32_e32 v167, v71
	ds_read2_b64 v[84:87], v173 offset0:48 offset1:50
	ds_read2_b64 v[72:75], v172 offset0:24 offset1:26
	ds_read2_b64 v[68:71], v173 offset0:56 offset1:58
	ds_read2_b64 v[88:91], v172 offset0:16 offset1:18
	ds_read2_b64 v[92:95], v172 offset0:20 offset1:22
	ds_read2_b64 v[96:99], v173 offset0:52 offset1:54
	ds_read2_b64 v[80:83], v172 offset0:28 offset1:30
	ds_read2_b64 v[76:79], v173 offset0:60 offset1:62
	v_cvt_pk_bf16_f32 v174, v100, v101
	v_cvt_pk_bf16_f32 v175, v104, v105
	v_cvt_pk_bf16_f32 v176, v108, v109
	v_cvt_pk_bf16_f32 v177, v112, v113
	v_cvt_pk_bf16_f32 v178, v152, v153
	v_cvt_pk_bf16_f32 v179, v156, v157
	s_waitcnt lgkmcnt(4)
	v_mfma_f32_32x32x16_bf16 v[20:35], v[88:91], v[174:177], v[20:35]
	v_cvt_pk_bf16_f32 v180, v160, v161
	v_cvt_pk_bf16_f32 v181, v164, v165
	v_cvt_pk_bf16_f32 v182, v102, v103
	v_cvt_pk_bf16_f32 v183, v106, v107
	v_cvt_pk_bf16_f32 v184, v110, v111
	v_cvt_pk_bf16_f32 v185, v114, v115
	v_cvt_pk_bf16_f32 v186, v154, v155
	v_mfma_f32_32x32x16_bf16 v[4:19], v[84:87], v[174:177], v[4:19]
	v_cvt_pk_bf16_f32 v187, v158, v159
	v_cvt_pk_bf16_f32 v188, v162, v163
	v_cvt_pk_bf16_f32 v189, v166, v167
	v_add_f32_e32 v169, v170, v0
	s_waitcnt lgkmcnt(3)
	v_mfma_f32_32x32x16_bf16 v[20:35], v[92:95], v[178:181], v[20:35]
	s_waitcnt lgkmcnt(2)
	v_mfma_f32_32x32x16_bf16 v[4:19], v[96:99], v[178:181], v[4:19]
	v_mfma_f32_32x32x16_bf16 v[20:35], v[72:75], v[182:185], v[20:35]
	v_mfma_f32_32x32x16_bf16 v[4:19], v[68:71], v[182:185], v[4:19]
	s_waitcnt lgkmcnt(1)
	v_mfma_f32_32x32x16_bf16 v[20:35], v[80:83], v[186:189], v[20:35]
	s_waitcnt lgkmcnt(0)
	v_mfma_f32_32x32x16_bf16 v[4:19], v[76:79], v[186:189], v[4:19]
	ds_read_b128 v[84:87], v222 offset:23040
	ds_read_b128 v[68:71], v222 offset:18432
	ds_read_b128 v[174:177], v222 offset:18464
	ds_read_b128 v[178:181], v222 offset:23072
	ds_read_b128 v[182:185], v222 offset:18496
	ds_read_b128 v[186:189], v222 offset:23104
	ds_read_b128 v[190:193], v222 offset:18528
	ds_read_b128 v[224:227], v222 offset:23136
	s_waitcnt lgkmcnt(6)
	v_mfma_f32_32x32x16_bf16 v[68:83], v[68:71], v[144:147], 0
	v_mfma_f32_32x32x16_bf16 v[84:99], v[84:87], v[144:147], 0
	s_waitcnt lgkmcnt(5)
	v_mfma_f32_32x32x16_bf16 v[68:83], v[174:177], v[140:143], v[68:83]
	s_waitcnt lgkmcnt(4)
	v_mfma_f32_32x32x16_bf16 v[84:99], v[178:181], v[140:143], v[84:99]
	s_waitcnt lgkmcnt(3)
	v_mfma_f32_32x32x16_bf16 v[68:83], v[182:185], v[136:139], v[68:83]
	s_waitcnt lgkmcnt(2)
	v_mfma_f32_32x32x16_bf16 v[84:99], v[186:189], v[136:139], v[84:99]
	s_waitcnt lgkmcnt(1)
	v_mfma_f32_32x32x16_bf16 v[68:83], v[190:193], v[132:135], v[68:83]
	s_waitcnt lgkmcnt(0)
	v_mfma_f32_32x32x16_bf16 v[84:99], v[224:227], v[132:135], v[84:99]
	s_nop 11
	v_maximum3_f32 v0, v69, v85, v85
	v_maximum3_f32 v0, v68, v84, v0
	v_maximum3_f32 v1, v70, v86, v86
	v_maximum3_f32 v2, v71, v87, v87
	v_maximum3_f32 v0, v0, v1, v2
	v_maximum3_f32 v1, v72, v88, v88
	v_maximum3_f32 v2, v73, v89, v89
	v_maximum3_f32 v0, v0, v1, v2
	v_maximum3_f32 v1, v74, v90, v90
	v_maximum3_f32 v2, v75, v91, v91
	v_maximum3_f32 v0, v0, v1, v2
	v_maximum3_f32 v1, v76, v92, v92
	v_maximum3_f32 v2, v77, v93, v93
	v_maximum3_f32 v0, v0, v1, v2
	v_maximum3_f32 v1, v78, v94, v94
	v_maximum3_f32 v2, v79, v95, v95
	v_maximum3_f32 v0, v0, v1, v2
	v_maximum3_f32 v1, v80, v96, v96
	v_maximum3_f32 v2, v81, v97, v97
	v_maximum3_f32 v0, v0, v1, v2
	v_maximum3_f32 v1, v82, v98, v98
	v_maximum3_f32 v2, v83, v99, v99
	v_maximum3_f32 v0, v0, v1, v2
	v_mov_b32_e32 v1, v0
	s_nop 1
	v_permlane32_swap_b32_e32 v0, v1
	s_nop 0
	v_maximum3_f32 v2, v0, v1, v1
	v_cmp_gt_f32_e32 vcc, v2, v150
	s_cbranch_vccz .LBB0_998
	v_maximum3_f32 v2, v150, v2, v2
	v_sub_f32_e32 v0, v150, v2
	v_exp_f32_e32 v150, v0
	s_nop 0
	v_mul_f32_e32 v169, v169, v150
	v_pk_mul_f32 v[52:53], v[52:53], v[150:151] op_sel_hi:[1,0]
	v_pk_mul_f32 v[54:55], v[54:55], v[150:151] op_sel_hi:[1,0]
	v_pk_mul_f32 v[56:57], v[56:57], v[150:151] op_sel_hi:[1,0]
	v_pk_mul_f32 v[58:59], v[58:59], v[150:151] op_sel_hi:[1,0]
	v_pk_mul_f32 v[60:61], v[60:61], v[150:151] op_sel_hi:[1,0]
	v_pk_mul_f32 v[62:63], v[62:63], v[150:151] op_sel_hi:[1,0]
	v_pk_mul_f32 v[64:65], v[64:65], v[150:151] op_sel_hi:[1,0]
	v_pk_mul_f32 v[66:67], v[66:67], v[150:151] op_sel_hi:[1,0]
	v_pk_mul_f32 v[50:51], v[50:51], v[150:151] op_sel_hi:[1,0]
	v_pk_mul_f32 v[48:49], v[48:49], v[150:151] op_sel_hi:[1,0]
	v_pk_mul_f32 v[46:47], v[46:47], v[150:151] op_sel_hi:[1,0]
	v_pk_mul_f32 v[44:45], v[44:45], v[150:151] op_sel_hi:[1,0]
	v_pk_mul_f32 v[42:43], v[42:43], v[150:151] op_sel_hi:[1,0]
	v_pk_mul_f32 v[40:41], v[40:41], v[150:151] op_sel_hi:[1,0]
	v_pk_mul_f32 v[38:39], v[38:39], v[150:151] op_sel_hi:[1,0]
	v_pk_mul_f32 v[36:37], v[36:37], v[150:151] op_sel_hi:[1,0]
	v_mov_b32_e32 v150, v2
	s_branch .LBB0_999

.LBB0_999:
	v_add_f32_e32 v100, v102, v100
	v_add_f32_e32 v101, v103, v101
	v_add_f32_e32 v102, v106, v104
	v_add_f32_e32 v103, v107, v105
	v_pk_add_f32 v[100:101], v[100:101], 0 op_sel_hi:[1,0]
	v_sub_f32_e32 v68, v68, v2
	v_sub_f32_e32 v69, v69, v2
	v_add_f32_e32 v100, v102, v100
	v_add_f32_e32 v101, v103, v101
	v_add_f32_e32 v102, v110, v108
	v_add_f32_e32 v103, v111, v109
	v_sub_f32_e32 v84, v84, v2
	v_sub_f32_e32 v85, v85, v2
	v_add_f32_e32 v100, v102, v100
	v_add_f32_e32 v101, v103, v101
	v_add_f32_e32 v102, v114, v112
	v_add_f32_e32 v103, v115, v113
	s_nop 0
	v_add_f32_e32 v100, v102, v100
	v_add_f32_e32 v101, v103, v101
	v_add_f32_e32 v102, v154, v152
	v_add_f32_e32 v103, v155, v153
	s_nop 0
	v_add_f32_e32 v100, v102, v100
	v_add_f32_e32 v101, v103, v101
	v_add_f32_e32 v102, v158, v156
	v_add_f32_e32 v103, v159, v157
	s_nop 0
	v_add_f32_e32 v100, v102, v100
	v_add_f32_e32 v101, v103, v101
	v_add_f32_e32 v102, v162, v160
	v_add_f32_e32 v103, v163, v161
	s_nop 0
	v_add_f32_e32 v100, v102, v100
	v_add_f32_e32 v101, v103, v101
	v_add_f32_e32 v102, v166, v164
	v_add_f32_e32 v103, v167, v165
	s_nop 0
	v_add_f32_e32 v100, v102, v100
	v_add_f32_e32 v101, v103, v101
	v_exp_f32_e32 v102, v84
	v_add_f32_e32 v0, v100, v101
	v_exp_f32_e32 v100, v68
	v_exp_f32_e32 v101, v69
	v_sub_f32_e32 v68, v70, v2
	v_sub_f32_e32 v69, v71, v2
	v_sub_f32_e32 v70, v86, v2
	v_sub_f32_e32 v71, v87, v2
	v_exp_f32_e32 v104, v68
	v_exp_f32_e32 v105, v69
	v_exp_f32_e32 v106, v70
	v_exp_f32_e32 v107, v71
	v_sub_f32_e32 v68, v72, v2
	v_sub_f32_e32 v69, v73, v2
	v_sub_f32_e32 v70, v88, v2
	v_sub_f32_e32 v71, v89, v2
	v_exp_f32_e32 v108, v68
	v_exp_f32_e32 v109, v69
	v_exp_f32_e32 v110, v70
	v_exp_f32_e32 v111, v71
	v_sub_f32_e32 v68, v74, v2
	v_sub_f32_e32 v69, v75, v2
	v_sub_f32_e32 v70, v90, v2
	v_sub_f32_e32 v71, v91, v2
	v_exp_f32_e32 v112, v68
	v_exp_f32_e32 v113, v69
	v_exp_f32_e32 v114, v70
	v_exp_f32_e32 v115, v71
	v_sub_f32_e32 v68, v76, v2
	v_sub_f32_e32 v69, v77, v2
	v_sub_f32_e32 v70, v92, v2
	v_sub_f32_e32 v71, v93, v2
	v_exp_f32_e32 v152, v68
	v_exp_f32_e32 v153, v69
	v_exp_f32_e32 v154, v70
	v_exp_f32_e32 v155, v71
	v_sub_f32_e32 v68, v78, v2
	v_sub_f32_e32 v69, v79, v2
	v_sub_f32_e32 v70, v94, v2
	v_sub_f32_e32 v71, v95, v2
	v_exp_f32_e32 v156, v68
	v_exp_f32_e32 v157, v69
	v_exp_f32_e32 v158, v70
	v_exp_f32_e32 v159, v71
	v_sub_f32_e32 v68, v80, v2
	v_sub_f32_e32 v69, v81, v2
	v_sub_f32_e32 v70, v96, v2
	v_sub_f32_e32 v71, v97, v2
	v_exp_f32_e32 v160, v68
	v_exp_f32_e32 v161, v69
	v_exp_f32_e32 v162, v70
	v_exp_f32_e32 v163, v71
	v_sub_f32_e32 v68, v82, v2
	v_sub_f32_e32 v69, v83, v2
	v_sub_f32_e32 v70, v98, v2
	v_sub_f32_e32 v71, v99, v2
	v_exp_f32_e32 v103, v85
	v_exp_f32_e32 v164, v68
	v_exp_f32_e32 v165, v69
	v_exp_f32_e32 v166, v70
	v_exp_f32_e32 v167, v71
	ds_read2_b64 v[84:87], v173 offset0:64 offset1:66
	ds_read2_b64 v[72:75], v172 offset0:40 offset1:42
	ds_read2_b64 v[68:71], v173 offset0:72 offset1:74
	ds_read2_b64 v[88:91], v172 offset0:32 offset1:34
	ds_read2_b64 v[92:95], v172 offset0:36 offset1:38
	ds_read2_b64 v[96:99], v173 offset0:68 offset1:70
	ds_read2_b64 v[80:83], v172 offset0:44 offset1:46
	ds_read2_b64 v[76:79], v173 offset0:76 offset1:78
	v_cvt_pk_bf16_f32 v174, v100, v101
	v_cvt_pk_bf16_f32 v175, v104, v105
	v_cvt_pk_bf16_f32 v176, v108, v109
	v_cvt_pk_bf16_f32 v177, v112, v113
	v_cvt_pk_bf16_f32 v178, v152, v153
	v_cvt_pk_bf16_f32 v179, v156, v157
	s_waitcnt lgkmcnt(4)
	v_mfma_f32_32x32x16_bf16 v[52:67], v[88:91], v[174:177], v[52:67]
	v_cvt_pk_bf16_f32 v180, v160, v161
	v_cvt_pk_bf16_f32 v181, v164, v165
	v_cvt_pk_bf16_f32 v182, v102, v103
	v_cvt_pk_bf16_f32 v183, v106, v107
	v_cvt_pk_bf16_f32 v184, v110, v111
	v_cvt_pk_bf16_f32 v185, v114, v115
	v_cvt_pk_bf16_f32 v186, v154, v155
	v_mfma_f32_32x32x16_bf16 v[36:51], v[84:87], v[174:177], v[36:51]
	v_cvt_pk_bf16_f32 v187, v158, v159
	v_cvt_pk_bf16_f32 v188, v162, v163
	v_cvt_pk_bf16_f32 v189, v166, v167
	v_add_f32_e32 v170, v168, v0
	s_waitcnt lgkmcnt(3)
	v_mfma_f32_32x32x16_bf16 v[52:67], v[92:95], v[178:181], v[52:67]
	s_waitcnt lgkmcnt(2)
	v_mfma_f32_32x32x16_bf16 v[36:51], v[96:99], v[178:181], v[36:51]
	v_mfma_f32_32x32x16_bf16 v[52:67], v[72:75], v[182:185], v[52:67]
	v_mfma_f32_32x32x16_bf16 v[36:51], v[68:71], v[182:185], v[36:51]
	s_waitcnt lgkmcnt(1)
	v_mfma_f32_32x32x16_bf16 v[52:67], v[80:83], v[186:189], v[52:67]
	s_waitcnt lgkmcnt(0)
	v_mfma_f32_32x32x16_bf16 v[36:51], v[76:79], v[186:189], v[36:51]
	ds_read_b128 v[84:87], v222 offset:23040
	ds_read_b128 v[68:71], v222 offset:18432
	ds_read_b128 v[174:177], v222 offset:18464
	ds_read_b128 v[178:181], v222 offset:23072
	ds_read_b128 v[182:185], v222 offset:18496
	ds_read_b128 v[186:189], v222 offset:23104
	ds_read_b128 v[190:193], v222 offset:18528
	ds_read_b128 v[224:227], v222 offset:23136
	s_waitcnt lgkmcnt(6)
	v_mfma_f32_32x32x16_bf16 v[68:83], v[68:71], v[128:131], 0
	v_mfma_f32_32x32x16_bf16 v[84:99], v[84:87], v[128:131], 0
	s_waitcnt lgkmcnt(5)
	v_mfma_f32_32x32x16_bf16 v[68:83], v[174:177], v[124:127], v[68:83]
	s_waitcnt lgkmcnt(4)
	v_mfma_f32_32x32x16_bf16 v[84:99], v[178:181], v[124:127], v[84:99]
	s_waitcnt lgkmcnt(3)
	v_mfma_f32_32x32x16_bf16 v[68:83], v[182:185], v[120:123], v[68:83]
	s_waitcnt lgkmcnt(2)
	v_mfma_f32_32x32x16_bf16 v[84:99], v[186:189], v[120:123], v[84:99]
	s_waitcnt lgkmcnt(1)
	v_mfma_f32_32x32x16_bf16 v[68:83], v[190:193], v[116:119], v[68:83]
	s_waitcnt lgkmcnt(0)
	v_mfma_f32_32x32x16_bf16 v[84:99], v[224:227], v[116:119], v[84:99]
	s_nop 11
	v_maximum3_f32 v0, v69, v85, v85
	v_maximum3_f32 v0, v68, v84, v0
	v_maximum3_f32 v1, v70, v86, v86
	v_maximum3_f32 v2, v71, v87, v87
	v_maximum3_f32 v0, v0, v1, v2
	v_maximum3_f32 v1, v72, v88, v88
	v_maximum3_f32 v2, v73, v89, v89
	v_maximum3_f32 v0, v0, v1, v2
	v_maximum3_f32 v1, v74, v90, v90
	v_maximum3_f32 v2, v75, v91, v91
	v_maximum3_f32 v0, v0, v1, v2
	v_maximum3_f32 v1, v76, v92, v92
	v_maximum3_f32 v2, v77, v93, v93
	v_maximum3_f32 v0, v0, v1, v2
	v_maximum3_f32 v1, v78, v94, v94
	v_maximum3_f32 v2, v79, v95, v95
	v_maximum3_f32 v0, v0, v1, v2
	v_maximum3_f32 v1, v80, v96, v96
	v_maximum3_f32 v2, v81, v97, v97
	v_maximum3_f32 v0, v0, v1, v2
	v_maximum3_f32 v1, v82, v98, v98
	v_maximum3_f32 v2, v83, v99, v99
	v_maximum3_f32 v0, v0, v1, v2
	v_mov_b32_e32 v1, v0
	s_nop 1
	v_permlane32_swap_b32_e32 v0, v1
	s_nop 0
	v_maximum3_f32 v2, v0, v1, v1
	v_cmp_gt_f32_e32 vcc, v2, v151
	s_cbranch_vccz .LBB0_1001
	v_maximum3_f32 v2, v151, v2, v2
	v_sub_f32_e32 v0, v151, v2
	v_exp_f32_e32 v168, v0
	v_mov_b32_e32 v151, v2
	v_mul_f32_e32 v170, v170, v168
	v_pk_mul_f32 v[20:21], v[20:21], v[168:169] op_sel_hi:[1,0]
	v_pk_mul_f32 v[22:23], v[22:23], v[168:169] op_sel_hi:[1,0]
	v_pk_mul_f32 v[24:25], v[24:25], v[168:169] op_sel_hi:[1,0]
	v_pk_mul_f32 v[26:27], v[26:27], v[168:169] op_sel_hi:[1,0]
	v_pk_mul_f32 v[28:29], v[28:29], v[168:169] op_sel_hi:[1,0]
	v_pk_mul_f32 v[30:31], v[30:31], v[168:169] op_sel_hi:[1,0]
	v_pk_mul_f32 v[32:33], v[32:33], v[168:169] op_sel_hi:[1,0]
	v_pk_mul_f32 v[34:35], v[34:35], v[168:169] op_sel_hi:[1,0]
	v_pk_mul_f32 v[18:19], v[18:19], v[168:169] op_sel_hi:[1,0]
	v_pk_mul_f32 v[16:17], v[16:17], v[168:169] op_sel_hi:[1,0]
	v_pk_mul_f32 v[14:15], v[14:15], v[168:169] op_sel_hi:[1,0]
	v_pk_mul_f32 v[12:13], v[12:13], v[168:169] op_sel_hi:[1,0]
	v_pk_mul_f32 v[10:11], v[10:11], v[168:169] op_sel_hi:[1,0]
	v_pk_mul_f32 v[8:9], v[8:9], v[168:169] op_sel_hi:[1,0]
	v_pk_mul_f32 v[6:7], v[6:7], v[168:169] op_sel_hi:[1,0]
	v_pk_mul_f32 v[4:5], v[4:5], v[168:169] op_sel_hi:[1,0]
	s_branch .LBB0_1002

.LBB0_1002:
	v_add_f32_e32 v100, v102, v100
	v_add_f32_e32 v101, v103, v101
	v_add_f32_e32 v102, v106, v104
	v_add_f32_e32 v103, v107, v105
	v_pk_add_f32 v[100:101], v[100:101], 0 op_sel_hi:[1,0]
	v_sub_f32_e32 v68, v68, v2
	v_sub_f32_e32 v69, v69, v2
	v_add_f32_e32 v100, v102, v100
	v_add_f32_e32 v101, v103, v101
	v_add_f32_e32 v102, v110, v108
	v_add_f32_e32 v103, v111, v109
	v_sub_f32_e32 v84, v84, v2
	v_sub_f32_e32 v85, v85, v2
	v_add_f32_e32 v100, v102, v100
	v_add_f32_e32 v101, v103, v101
	v_add_f32_e32 v102, v114, v112
	v_add_f32_e32 v103, v115, v113
	s_nop 0
	v_add_f32_e32 v100, v102, v100
	v_add_f32_e32 v101, v103, v101
	v_add_f32_e32 v102, v154, v152
	v_add_f32_e32 v103, v155, v153
	s_nop 0
	v_add_f32_e32 v100, v102, v100
	v_add_f32_e32 v101, v103, v101
	v_add_f32_e32 v102, v158, v156
	v_add_f32_e32 v103, v159, v157
	s_nop 0
	v_add_f32_e32 v100, v102, v100
	v_add_f32_e32 v101, v103, v101
	v_add_f32_e32 v102, v162, v160
	v_add_f32_e32 v103, v163, v161
	s_nop 0
	v_add_f32_e32 v100, v102, v100
	v_add_f32_e32 v101, v103, v101
	v_add_f32_e32 v102, v166, v164
	v_add_f32_e32 v103, v167, v165
	s_nop 0
	v_add_f32_e32 v100, v102, v100
	v_add_f32_e32 v101, v103, v101
	v_exp_f32_e32 v102, v84
	v_add_f32_e32 v0, v100, v101
	v_exp_f32_e32 v100, v68
	v_exp_f32_e32 v101, v69
	v_sub_f32_e32 v68, v70, v2
	v_sub_f32_e32 v69, v71, v2
	v_sub_f32_e32 v70, v86, v2
	v_sub_f32_e32 v71, v87, v2
	v_exp_f32_e32 v104, v68
	v_exp_f32_e32 v105, v69
	v_exp_f32_e32 v106, v70
	v_exp_f32_e32 v107, v71
	v_sub_f32_e32 v68, v72, v2
	v_sub_f32_e32 v69, v73, v2
	v_sub_f32_e32 v70, v88, v2
	v_sub_f32_e32 v71, v89, v2
	v_exp_f32_e32 v108, v68
	v_exp_f32_e32 v109, v69
	v_exp_f32_e32 v110, v70
	v_exp_f32_e32 v111, v71
	v_sub_f32_e32 v68, v74, v2
	v_sub_f32_e32 v69, v75, v2
	v_sub_f32_e32 v70, v90, v2
	v_sub_f32_e32 v71, v91, v2
	v_exp_f32_e32 v112, v68
	v_exp_f32_e32 v113, v69
	v_exp_f32_e32 v114, v70
	v_exp_f32_e32 v115, v71
	v_sub_f32_e32 v68, v76, v2
	v_sub_f32_e32 v69, v77, v2
	v_sub_f32_e32 v70, v92, v2
	v_sub_f32_e32 v71, v93, v2
	v_exp_f32_e32 v152, v68
	v_exp_f32_e32 v153, v69
	v_exp_f32_e32 v154, v70
	v_exp_f32_e32 v155, v71
	v_sub_f32_e32 v68, v78, v2
	v_sub_f32_e32 v69, v79, v2
	v_sub_f32_e32 v70, v94, v2
	v_sub_f32_e32 v71, v95, v2
	v_exp_f32_e32 v156, v68
	v_exp_f32_e32 v157, v69
	v_exp_f32_e32 v158, v70
	v_exp_f32_e32 v159, v71
	v_sub_f32_e32 v68, v80, v2
	v_sub_f32_e32 v69, v81, v2
	v_sub_f32_e32 v70, v96, v2
	v_sub_f32_e32 v71, v97, v2
	v_exp_f32_e32 v160, v68
	v_exp_f32_e32 v161, v69
	v_exp_f32_e32 v162, v70
	v_exp_f32_e32 v163, v71
	v_sub_f32_e32 v68, v82, v2
	v_sub_f32_e32 v69, v83, v2
	v_sub_f32_e32 v70, v98, v2
	v_sub_f32_e32 v71, v99, v2
	v_exp_f32_e32 v103, v85
	v_exp_f32_e32 v164, v68
	v_exp_f32_e32 v165, v69
	v_exp_f32_e32 v166, v70
	v_exp_f32_e32 v167, v71
	ds_read2_b64 v[84:87], v173 offset0:64 offset1:66
	ds_read2_b64 v[72:75], v172 offset0:40 offset1:42
	ds_read2_b64 v[68:71], v173 offset0:72 offset1:74
	ds_read2_b64 v[88:91], v172 offset0:32 offset1:34
	ds_read2_b64 v[92:95], v172 offset0:36 offset1:38
	ds_read2_b64 v[96:99], v173 offset0:68 offset1:70
	ds_read2_b64 v[80:83], v172 offset0:44 offset1:46
	ds_read2_b64 v[76:79], v173 offset0:76 offset1:78
	v_cvt_pk_bf16_f32 v174, v100, v101
	v_cvt_pk_bf16_f32 v175, v104, v105
	v_cvt_pk_bf16_f32 v176, v108, v109
	v_cvt_pk_bf16_f32 v177, v112, v113
	v_cvt_pk_bf16_f32 v178, v152, v153
	v_cvt_pk_bf16_f32 v179, v156, v157
	s_waitcnt lgkmcnt(4)
	v_mfma_f32_32x32x16_bf16 v[20:35], v[88:91], v[174:177], v[20:35]
	v_cvt_pk_bf16_f32 v180, v160, v161
	v_cvt_pk_bf16_f32 v181, v164, v165
	v_cvt_pk_bf16_f32 v182, v102, v103
	v_cvt_pk_bf16_f32 v183, v106, v107
	v_cvt_pk_bf16_f32 v184, v110, v111
	v_cvt_pk_bf16_f32 v185, v114, v115
	v_cvt_pk_bf16_f32 v186, v154, v155
	v_mfma_f32_32x32x16_bf16 v[4:19], v[84:87], v[174:177], v[4:19]
	v_cvt_pk_bf16_f32 v187, v158, v159
	v_cvt_pk_bf16_f32 v188, v162, v163
	v_cvt_pk_bf16_f32 v189, v166, v167
	v_add_f32_e32 v168, v169, v0
	s_waitcnt lgkmcnt(3)
	v_mfma_f32_32x32x16_bf16 v[20:35], v[92:95], v[178:181], v[20:35]
	s_waitcnt lgkmcnt(2)
	v_mfma_f32_32x32x16_bf16 v[4:19], v[96:99], v[178:181], v[4:19]
	v_mfma_f32_32x32x16_bf16 v[20:35], v[72:75], v[182:185], v[20:35]
	v_mfma_f32_32x32x16_bf16 v[4:19], v[68:71], v[182:185], v[4:19]
	s_waitcnt lgkmcnt(1)
	v_mfma_f32_32x32x16_bf16 v[20:35], v[80:83], v[186:189], v[20:35]
	s_waitcnt lgkmcnt(0)
	v_mfma_f32_32x32x16_bf16 v[4:19], v[76:79], v[186:189], v[4:19]
	ds_read_b128 v[84:87], v222 offset:32256
	ds_read_b128 v[68:71], v222 offset:27648
	ds_read_b128 v[174:177], v222 offset:27680
	ds_read_b128 v[178:181], v222 offset:32288
	ds_read_b128 v[182:185], v222 offset:27712
	ds_read_b128 v[186:189], v222 offset:32320
	ds_read_b128 v[190:193], v222 offset:27744
	ds_read_b128 v[224:227], v222 offset:32352
	s_waitcnt lgkmcnt(6)
	v_mfma_f32_32x32x16_bf16 v[68:83], v[68:71], v[144:147], 0
	v_mfma_f32_32x32x16_bf16 v[84:99], v[84:87], v[144:147], 0
	s_waitcnt lgkmcnt(5)
	v_mfma_f32_32x32x16_bf16 v[68:83], v[174:177], v[140:143], v[68:83]
	s_waitcnt lgkmcnt(4)
	v_mfma_f32_32x32x16_bf16 v[84:99], v[178:181], v[140:143], v[84:99]
	s_waitcnt lgkmcnt(3)
	v_mfma_f32_32x32x16_bf16 v[68:83], v[182:185], v[136:139], v[68:83]
	s_waitcnt lgkmcnt(2)
	v_mfma_f32_32x32x16_bf16 v[84:99], v[186:189], v[136:139], v[84:99]
	s_waitcnt lgkmcnt(1)
	v_mfma_f32_32x32x16_bf16 v[68:83], v[190:193], v[132:135], v[68:83]
	s_waitcnt lgkmcnt(0)
	v_mfma_f32_32x32x16_bf16 v[84:99], v[224:227], v[132:135], v[84:99]
	s_nop 11
	v_maximum3_f32 v0, v69, v85, v85
	v_maximum3_f32 v0, v68, v84, v0
	v_maximum3_f32 v1, v70, v86, v86
	v_maximum3_f32 v2, v71, v87, v87
	v_maximum3_f32 v0, v0, v1, v2
	v_maximum3_f32 v1, v72, v88, v88
	v_maximum3_f32 v2, v73, v89, v89
	v_maximum3_f32 v0, v0, v1, v2
	v_maximum3_f32 v1, v74, v90, v90
	v_maximum3_f32 v2, v75, v91, v91
	v_maximum3_f32 v0, v0, v1, v2
	v_maximum3_f32 v1, v76, v92, v92
	v_maximum3_f32 v2, v77, v93, v93
	v_maximum3_f32 v0, v0, v1, v2
	v_maximum3_f32 v1, v78, v94, v94
	v_maximum3_f32 v2, v79, v95, v95
	v_maximum3_f32 v0, v0, v1, v2
	v_maximum3_f32 v1, v80, v96, v96
	v_maximum3_f32 v2, v81, v97, v97
	v_maximum3_f32 v0, v0, v1, v2
	v_maximum3_f32 v1, v82, v98, v98
	v_maximum3_f32 v2, v83, v99, v99
	v_maximum3_f32 v0, v0, v1, v2
	v_mov_b32_e32 v1, v0
	s_nop 1
	v_permlane32_swap_b32_e32 v0, v1
	s_nop 0
	v_maximum3_f32 v2, v0, v1, v1
	v_cmp_gt_f32_e32 vcc, v2, v150
	s_cbranch_vccz .LBB0_1004
	v_maximum3_f32 v0, v150, v2, v2
	v_sub_f32_e32 v1, v150, v0
	v_exp_f32_e32 v2, v1
	v_mov_b32_e32 v150, v0
	v_mul_f32_e32 v168, v168, v2
	v_pk_mul_f32 v[52:53], v[52:53], v[2:3] op_sel_hi:[1,0]
	v_pk_mul_f32 v[54:55], v[54:55], v[2:3] op_sel_hi:[1,0]
	v_pk_mul_f32 v[56:57], v[56:57], v[2:3] op_sel_hi:[1,0]
	v_pk_mul_f32 v[58:59], v[58:59], v[2:3] op_sel_hi:[1,0]
	v_pk_mul_f32 v[60:61], v[60:61], v[2:3] op_sel_hi:[1,0]
	v_pk_mul_f32 v[62:63], v[62:63], v[2:3] op_sel_hi:[1,0]
	v_pk_mul_f32 v[64:65], v[64:65], v[2:3] op_sel_hi:[1,0]
	v_pk_mul_f32 v[66:67], v[66:67], v[2:3] op_sel_hi:[1,0]
	v_pk_mul_f32 v[50:51], v[50:51], v[2:3] op_sel_hi:[1,0]
	v_pk_mul_f32 v[48:49], v[48:49], v[2:3] op_sel_hi:[1,0]
	v_pk_mul_f32 v[46:47], v[46:47], v[2:3] op_sel_hi:[1,0]
	v_pk_mul_f32 v[44:45], v[44:45], v[2:3] op_sel_hi:[1,0]
	v_pk_mul_f32 v[42:43], v[42:43], v[2:3] op_sel_hi:[1,0]
	v_pk_mul_f32 v[40:41], v[40:41], v[2:3] op_sel_hi:[1,0]
	v_pk_mul_f32 v[38:39], v[38:39], v[2:3] op_sel_hi:[1,0]
	v_pk_mul_f32 v[36:37], v[36:37], v[2:3] op_sel_hi:[1,0]
.LBB0_1004:
	v_add_f32_e32 v100, v102, v100
	v_add_f32_e32 v101, v103, v101
	v_add_f32_e32 v102, v106, v104
	v_add_f32_e32 v103, v107, v105
	v_pk_add_f32 v[100:101], v[100:101], 0 op_sel_hi:[1,0]
	v_sub_f32_e32 v68, v68, v150
	v_sub_f32_e32 v69, v69, v150
	v_add_f32_e32 v100, v102, v100
	v_add_f32_e32 v101, v103, v101
	v_add_f32_e32 v102, v110, v108
	v_add_f32_e32 v103, v111, v109
	v_sub_f32_e32 v84, v84, v150
	v_sub_f32_e32 v85, v85, v150
	v_add_f32_e32 v100, v102, v100
	v_add_f32_e32 v101, v103, v101
	v_add_f32_e32 v102, v114, v112
	v_add_f32_e32 v103, v115, v113
	s_nop 0
	v_add_f32_e32 v100, v102, v100
	v_add_f32_e32 v101, v103, v101
	v_add_f32_e32 v102, v154, v152
	v_add_f32_e32 v103, v155, v153
	s_nop 0
	v_add_f32_e32 v100, v102, v100
	v_add_f32_e32 v101, v103, v101
	v_add_f32_e32 v102, v158, v156
	v_add_f32_e32 v103, v159, v157
	s_nop 0
	v_add_f32_e32 v100, v102, v100
	v_add_f32_e32 v101, v103, v101
	v_add_f32_e32 v102, v162, v160
	v_add_f32_e32 v103, v163, v161
	s_nop 0
	v_add_f32_e32 v100, v102, v100
	v_add_f32_e32 v101, v103, v101
	v_add_f32_e32 v102, v166, v164
	v_add_f32_e32 v103, v167, v165
	s_nop 0
	v_add_f32_e32 v100, v102, v100
	v_add_f32_e32 v101, v103, v101
	v_exp_f32_e32 v102, v84
	v_add_f32_e32 v0, v100, v101
	v_exp_f32_e32 v100, v68
	v_exp_f32_e32 v101, v69
	v_sub_f32_e32 v68, v70, v150
	v_sub_f32_e32 v69, v71, v150
	v_sub_f32_e32 v70, v86, v150
	v_sub_f32_e32 v71, v87, v150
	v_exp_f32_e32 v104, v68
	v_exp_f32_e32 v105, v69
	v_exp_f32_e32 v106, v70
	v_exp_f32_e32 v107, v71
	v_sub_f32_e32 v68, v72, v150
	v_sub_f32_e32 v69, v73, v150
	v_sub_f32_e32 v70, v88, v150
	v_sub_f32_e32 v71, v89, v150
	v_exp_f32_e32 v108, v68
	v_exp_f32_e32 v109, v69
	v_exp_f32_e32 v110, v70
	v_exp_f32_e32 v111, v71
	v_sub_f32_e32 v68, v74, v150
	v_sub_f32_e32 v69, v75, v150
	v_sub_f32_e32 v70, v90, v150
	v_sub_f32_e32 v71, v91, v150
	v_exp_f32_e32 v112, v68
	v_exp_f32_e32 v113, v69
	v_exp_f32_e32 v114, v70
	v_exp_f32_e32 v115, v71
	v_sub_f32_e32 v68, v76, v150
	v_sub_f32_e32 v69, v77, v150
	v_sub_f32_e32 v70, v92, v150
	v_sub_f32_e32 v71, v93, v150
	v_exp_f32_e32 v132, v68
	v_exp_f32_e32 v133, v69
	v_exp_f32_e32 v134, v70
	v_exp_f32_e32 v135, v71
	v_sub_f32_e32 v68, v78, v150
	v_sub_f32_e32 v69, v79, v150
	v_sub_f32_e32 v70, v94, v150
	v_sub_f32_e32 v71, v95, v150
	v_exp_f32_e32 v136, v68
	v_exp_f32_e32 v137, v69
	v_exp_f32_e32 v138, v70
	v_exp_f32_e32 v139, v71
	v_sub_f32_e32 v68, v80, v150
	v_sub_f32_e32 v69, v81, v150
	v_sub_f32_e32 v70, v96, v150
	v_sub_f32_e32 v71, v97, v150
	v_exp_f32_e32 v140, v68
	v_exp_f32_e32 v141, v69
	v_exp_f32_e32 v142, v70
	v_exp_f32_e32 v143, v71
	v_sub_f32_e32 v68, v82, v150
	v_sub_f32_e32 v69, v83, v150
	v_sub_f32_e32 v70, v98, v150
	v_sub_f32_e32 v71, v99, v150
	v_exp_f32_e32 v103, v85
	v_exp_f32_e32 v144, v68
	v_exp_f32_e32 v145, v69
	v_exp_f32_e32 v146, v70
	v_exp_f32_e32 v147, v71
	ds_read2_b64 v[84:87], v173 offset0:80 offset1:82
	ds_read2_b64 v[72:75], v172 offset0:56 offset1:58
	ds_read2_b64 v[68:71], v173 offset0:88 offset1:90
	ds_read2_b64 v[88:91], v172 offset0:48 offset1:50
	ds_read2_b64 v[92:95], v172 offset0:52 offset1:54
	ds_read2_b64 v[96:99], v173 offset0:84 offset1:86
	ds_read2_b64 v[80:83], v172 offset0:60 offset1:62
	ds_read2_b64 v[76:79], v173 offset0:92 offset1:94
	v_cvt_pk_bf16_f32 v154, v100, v101
	v_cvt_pk_bf16_f32 v155, v104, v105
	v_cvt_pk_bf16_f32 v156, v108, v109
	v_cvt_pk_bf16_f32 v157, v112, v113
	v_cvt_pk_bf16_f32 v158, v132, v133
	v_cvt_pk_bf16_f32 v159, v136, v137
	s_waitcnt lgkmcnt(4)
	v_mfma_f32_32x32x16_bf16 v[52:67], v[88:91], v[154:157], v[52:67]
	v_cvt_pk_bf16_f32 v160, v140, v141
	v_cvt_pk_bf16_f32 v161, v144, v145
	v_cvt_pk_bf16_f32 v162, v102, v103
	v_cvt_pk_bf16_f32 v163, v106, v107
	v_cvt_pk_bf16_f32 v164, v110, v111
	v_cvt_pk_bf16_f32 v165, v114, v115
	v_cvt_pk_bf16_f32 v174, v134, v135
	v_mfma_f32_32x32x16_bf16 v[36:51], v[84:87], v[154:157], v[36:51]
	v_cvt_pk_bf16_f32 v175, v138, v139
	v_cvt_pk_bf16_f32 v176, v142, v143
	v_cvt_pk_bf16_f32 v177, v146, v147
	v_add_f32_e32 v152, v170, v0
	s_waitcnt lgkmcnt(3)
	v_mfma_f32_32x32x16_bf16 v[52:67], v[92:95], v[158:161], v[52:67]
	s_waitcnt lgkmcnt(2)
	v_mfma_f32_32x32x16_bf16 v[36:51], v[96:99], v[158:161], v[36:51]
	v_mfma_f32_32x32x16_bf16 v[52:67], v[72:75], v[162:165], v[52:67]
	v_mfma_f32_32x32x16_bf16 v[36:51], v[68:71], v[162:165], v[36:51]
	s_waitcnt lgkmcnt(1)
	v_mfma_f32_32x32x16_bf16 v[52:67], v[80:83], v[174:177], v[52:67]
	s_waitcnt lgkmcnt(0)
	v_mfma_f32_32x32x16_bf16 v[36:51], v[76:79], v[174:177], v[36:51]
	ds_read_b128 v[84:87], v222 offset:32256
	ds_read_b128 v[68:71], v222 offset:27648
	ds_read_b128 v[154:157], v222 offset:27680
	ds_read_b128 v[158:161], v222 offset:32288
	ds_read_b128 v[162:165], v222 offset:27712
	ds_read_b128 v[174:177], v222 offset:32320
	ds_read_b128 v[178:181], v222 offset:27744
	ds_read_b128 v[182:185], v222 offset:32352
	s_waitcnt lgkmcnt(6)
	v_mfma_f32_32x32x16_bf16 v[68:83], v[68:71], v[128:131], 0
	v_mfma_f32_32x32x16_bf16 v[84:99], v[84:87], v[128:131], 0
	s_waitcnt lgkmcnt(5)
	v_mfma_f32_32x32x16_bf16 v[68:83], v[154:157], v[124:127], v[68:83]
	s_waitcnt lgkmcnt(4)
	v_mfma_f32_32x32x16_bf16 v[84:99], v[158:161], v[124:127], v[84:99]
	s_waitcnt lgkmcnt(3)
	v_mfma_f32_32x32x16_bf16 v[68:83], v[162:165], v[120:123], v[68:83]
	s_waitcnt lgkmcnt(2)
	v_mfma_f32_32x32x16_bf16 v[84:99], v[174:177], v[120:123], v[84:99]
	s_waitcnt lgkmcnt(1)
	v_mfma_f32_32x32x16_bf16 v[68:83], v[178:181], v[116:119], v[68:83]
	s_waitcnt lgkmcnt(0)
	v_mfma_f32_32x32x16_bf16 v[84:99], v[182:185], v[116:119], v[84:99]
	s_nop 11
	v_maximum3_f32 v0, v69, v85, v85
	v_maximum3_f32 v0, v68, v84, v0
	v_maximum3_f32 v1, v70, v86, v86
	v_maximum3_f32 v2, v71, v87, v87
	v_maximum3_f32 v0, v0, v1, v2
	v_maximum3_f32 v1, v72, v88, v88
	v_maximum3_f32 v2, v73, v89, v89
	v_maximum3_f32 v0, v0, v1, v2
	v_maximum3_f32 v1, v74, v90, v90
	v_maximum3_f32 v2, v75, v91, v91
	v_maximum3_f32 v0, v0, v1, v2
	v_maximum3_f32 v1, v76, v92, v92
	v_maximum3_f32 v2, v77, v93, v93
	v_maximum3_f32 v0, v0, v1, v2
	v_maximum3_f32 v1, v78, v94, v94
	v_maximum3_f32 v2, v79, v95, v95
	v_maximum3_f32 v0, v0, v1, v2
	v_maximum3_f32 v1, v80, v96, v96
	v_maximum3_f32 v2, v81, v97, v97
	v_maximum3_f32 v0, v0, v1, v2
	v_maximum3_f32 v1, v82, v98, v98
	v_maximum3_f32 v2, v83, v99, v99
	v_maximum3_f32 v0, v0, v1, v2
	v_mov_b32_e32 v1, v0
	s_nop 1
	v_permlane32_swap_b32_e32 v0, v1
	s_nop 0
	v_maximum3_f32 v2, v0, v1, v1
	v_cmp_gt_f32_e32 vcc, v2, v151
	s_cbranch_vccz .LBB0_1006
	v_maximum3_f32 v2, v151, v2, v2
	v_sub_f32_e32 v0, v151, v2
	v_exp_f32_e32 v116, v0
	s_nop 0
	v_mul_f32_e32 v152, v152, v116
	v_pk_mul_f32 v[20:21], v[20:21], v[116:117] op_sel_hi:[1,0]
	v_pk_mul_f32 v[22:23], v[22:23], v[116:117] op_sel_hi:[1,0]
	v_pk_mul_f32 v[24:25], v[24:25], v[116:117] op_sel_hi:[1,0]
	v_pk_mul_f32 v[26:27], v[26:27], v[116:117] op_sel_hi:[1,0]
	v_pk_mul_f32 v[28:29], v[28:29], v[116:117] op_sel_hi:[1,0]
	v_pk_mul_f32 v[30:31], v[30:31], v[116:117] op_sel_hi:[1,0]
	v_pk_mul_f32 v[32:33], v[32:33], v[116:117] op_sel_hi:[1,0]
	v_pk_mul_f32 v[34:35], v[34:35], v[116:117] op_sel_hi:[1,0]
	v_pk_mul_f32 v[18:19], v[18:19], v[116:117] op_sel_hi:[1,0]
	v_pk_mul_f32 v[16:17], v[16:17], v[116:117] op_sel_hi:[1,0]
	v_pk_mul_f32 v[14:15], v[14:15], v[116:117] op_sel_hi:[1,0]
	v_pk_mul_f32 v[12:13], v[12:13], v[116:117] op_sel_hi:[1,0]
	v_pk_mul_f32 v[10:11], v[10:11], v[116:117] op_sel_hi:[1,0]
	v_pk_mul_f32 v[8:9], v[8:9], v[116:117] op_sel_hi:[1,0]
	v_pk_mul_f32 v[6:7], v[6:7], v[116:117] op_sel_hi:[1,0]
	v_pk_mul_f32 v[4:5], v[4:5], v[116:117] op_sel_hi:[1,0]
	s_branch .LBB0_1007

.LBB0_1007:
	v_add_f32_e32 v100, v102, v100
	v_add_f32_e32 v101, v103, v101
	v_add_f32_e32 v104, v106, v104
	v_add_f32_e32 v105, v107, v105
	v_pk_add_f32 v[100:101], v[100:101], 0 op_sel_hi:[1,0]
	v_add_f32_e32 v108, v110, v108
	v_add_f32_e32 v109, v111, v109
	v_add_f32_e32 v100, v104, v100
	v_add_f32_e32 v101, v105, v101
	v_add_f32_e32 v112, v114, v112
	v_add_f32_e32 v113, v115, v113
	v_add_f32_e32 v100, v108, v100
	v_add_f32_e32 v101, v109, v101
	v_add_f32_e32 v122, v134, v132
	v_add_f32_e32 v123, v135, v133
	v_add_f32_e32 v100, v112, v100
	v_add_f32_e32 v101, v113, v101
	v_add_f32_e32 v120, v138, v136
	v_add_f32_e32 v121, v139, v137
	v_add_f32_e32 v100, v122, v100
	v_add_f32_e32 v101, v123, v101
	v_add_f32_e32 v118, v142, v140
	v_add_f32_e32 v119, v143, v141
	v_add_f32_e32 v100, v120, v100
	v_add_f32_e32 v101, v121, v101
	v_add_f32_e32 v116, v146, v144
	v_add_f32_e32 v117, v147, v145
	v_add_f32_e32 v100, v118, v100
	v_add_f32_e32 v101, v119, v101
	v_sub_f32_e32 v68, v68, v2
	v_sub_f32_e32 v69, v69, v2
	v_add_f32_e32 v100, v116, v100
	v_add_f32_e32 v101, v117, v101
	v_sub_f32_e32 v84, v84, v2
	v_sub_f32_e32 v85, v85, v2
	v_add_f32_e32 v0, v100, v101
	v_exp_f32_e32 v100, v68
	v_exp_f32_e32 v101, v69
	v_exp_f32_e32 v84, v84
	v_exp_f32_e32 v85, v85
	v_sub_f32_e32 v70, v70, v2
	v_sub_f32_e32 v71, v71, v2
	v_sub_f32_e32 v86, v86, v2
	v_sub_f32_e32 v87, v87, v2
	v_exp_f32_e32 v102, v70
	v_exp_f32_e32 v103, v71
	v_exp_f32_e32 v86, v86
	v_exp_f32_e32 v87, v87
	v_add_f32_e32 v68, v84, v100
	v_add_f32_e32 v69, v85, v101
	v_cvt_pk_bf16_f32 v100, v100, v101
	v_pk_add_f32 v[68:69], v[68:69], 0 op_sel_hi:[1,0]
	v_add_f32_e32 v70, v86, v102
	v_add_f32_e32 v71, v87, v103
	v_cvt_pk_bf16_f32 v101, v102, v103
	v_add_f32_e32 v68, v70, v68
	v_add_f32_e32 v69, v71, v69
	v_sub_f32_e32 v70, v72, v2
	v_sub_f32_e32 v71, v73, v2
	v_sub_f32_e32 v72, v88, v2
	v_sub_f32_e32 v73, v89, v2
	v_exp_f32_e32 v88, v70
	v_exp_f32_e32 v89, v71
	v_exp_f32_e32 v104, v72
	v_exp_f32_e32 v105, v73
	v_sub_f32_e32 v72, v90, v2
	v_sub_f32_e32 v73, v91, v2
	v_cvt_pk_bf16_f32 v102, v88, v89
	v_exp_f32_e32 v106, v72
	v_add_f32_e32 v70, v104, v88
	v_add_f32_e32 v71, v105, v89
	v_exp_f32_e32 v107, v73
	v_add_f32_e32 v68, v70, v68
	v_add_f32_e32 v69, v71, v69
	v_sub_f32_e32 v70, v74, v2
	v_sub_f32_e32 v71, v75, v2
	v_sub_f32_e32 v72, v92, v2
	v_sub_f32_e32 v73, v93, v2
	v_exp_f32_e32 v90, v70
	v_exp_f32_e32 v91, v71
	v_exp_f32_e32 v92, v72
	v_exp_f32_e32 v93, v73
	v_sub_f32_e32 v72, v94, v2
	v_sub_f32_e32 v73, v95, v2
	v_add_f32_e32 v70, v106, v90
	v_add_f32_e32 v71, v107, v91
	v_exp_f32_e32 v126, v72
	v_add_f32_e32 v68, v70, v68
	v_add_f32_e32 v69, v71, v69
	v_sub_f32_e32 v70, v76, v2
	v_sub_f32_e32 v71, v77, v2
	v_exp_f32_e32 v127, v73
	v_exp_f32_e32 v122, v70
	v_exp_f32_e32 v123, v71
	v_sub_f32_e32 v72, v96, v2
	v_sub_f32_e32 v73, v97, v2
	v_cvt_pk_bf16_f32 v103, v90, v91
	v_exp_f32_e32 v130, v72
	v_add_f32_e32 v70, v92, v122
	v_add_f32_e32 v71, v93, v123
	v_exp_f32_e32 v131, v73
	v_add_f32_e32 v68, v70, v68
	v_add_f32_e32 v69, v71, v69
	v_sub_f32_e32 v70, v78, v2
	v_sub_f32_e32 v71, v79, v2
	v_sub_f32_e32 v72, v98, v2
	v_sub_f32_e32 v73, v99, v2
	v_exp_f32_e32 v124, v70
	v_exp_f32_e32 v125, v71
	v_exp_f32_e32 v134, v72
	v_exp_f32_e32 v135, v73
	v_add_f32_e32 v108, v168, v0
	v_add_f32_e32 v70, v126, v124
	v_add_f32_e32 v71, v127, v125
	v_cvt_pk_bf16_f32 v122, v122, v123
	v_add_f32_e32 v68, v70, v68
	v_add_f32_e32 v69, v71, v69
	v_sub_f32_e32 v70, v80, v2
	v_sub_f32_e32 v71, v81, v2
	v_cvt_pk_bf16_f32 v123, v124, v125
	v_exp_f32_e32 v128, v70
	v_exp_f32_e32 v129, v71
	v_cvt_pk_bf16_f32 v88, v84, v85
	v_cvt_pk_bf16_f32 v89, v86, v87
	v_cvt_pk_bf16_f32 v90, v104, v105
	v_add_f32_e32 v70, v130, v128
	v_add_f32_e32 v71, v131, v129
	v_cvt_pk_bf16_f32 v124, v128, v129
	v_add_f32_e32 v68, v70, v68
	v_add_f32_e32 v69, v71, v69
	v_sub_f32_e32 v70, v82, v2
	v_sub_f32_e32 v71, v83, v2
	v_cvt_pk_bf16_f32 v91, v106, v107
	v_exp_f32_e32 v132, v70
	v_exp_f32_e32 v133, v71
	v_cvt_pk_bf16_f32 v84, v92, v93
	v_cvt_pk_bf16_f32 v85, v126, v127
	v_cvt_pk_bf16_f32 v86, v130, v131
	v_add_f32_e32 v70, v134, v132
	v_add_f32_e32 v71, v135, v133
	v_cvt_pk_bf16_f32 v125, v132, v133
	v_add_f32_e32 v68, v70, v68
	v_add_f32_e32 v69, v71, v69
	v_cvt_pk_bf16_f32 v87, v134, v135
	v_add_f32_e32 v0, v68, v69
	ds_read2_b64 v[96:99], v173 offset0:80 offset1:82
	ds_read2_b64 v[80:83], v172 offset0:56 offset1:58
	ds_read2_b64 v[76:79], v173 offset0:88 offset1:90
	ds_read2_b64 v[110:113], v172 offset0:48 offset1:50
	ds_read2_b64 v[114:117], v172 offset0:52 offset1:54
	ds_read2_b64 v[118:121], v173 offset0:84 offset1:86
	ds_read2_b64 v[72:75], v172 offset0:60 offset1:62
	ds_read2_b64 v[68:71], v173 offset0:92 offset1:94
	s_waitcnt lgkmcnt(7)
	v_mfma_f32_32x32x16_bf16 v[4:19], v[96:99], v[100:103], v[4:19]
	v_add_f32_e32 v94, v152, v0
	ds_bpermute_b32 v0, v221, v108
	v_lshlrev_b32_e32 v2, 1, v220
	s_waitcnt lgkmcnt(0)
	v_add_f32_e32 v0, v108, v0
	v_mfma_f32_32x32x16_bf16 v[4:19], v[118:121], v[122:125], v[4:19]
	v_div_scale_f32 v1, s[4:5], v0, v0, 1.0
	v_readlane_b32 s5, v255, 3
	v_readlane_b32 s4, v255, 0
	s_ashr_i32 s5, s5, 2
	s_lshl_b32 s4, s4, 8
	s_andn2_b32 s5, s5, 63
	v_mfma_f32_32x32x16_bf16 v[20:35], v[110:113], v[100:103], v[20:35]
	s_add_i32 s4, s5, s4
	s_ashr_i32 s5, s4, 31
	v_mfma_f32_32x32x16_bf16 v[4:19], v[76:79], v[88:91], v[4:19]
	v_mfma_f32_32x32x16_bf16 v[20:35], v[114:117], v[122:125], v[20:35]
	v_mfma_f32_32x32x16_bf16 v[4:19], v[68:71], v[84:87], v[4:19]
	v_lshlrev_b64 v[68:69], 12, v[148:149]
	v_lshl_add_u64 v[68:69], s[70:71], 0, v[68:69]
	v_lshl_add_u64 v[68:69], v[68:69], 0, v[2:3]
	v_rcp_f32_e32 v2, v1
	v_lshl_add_u64 v[68:69], s[4:5], 1, v[68:69]
	v_fma_f32 v70, -v1, v2, 1.0
	v_mfma_f32_32x32x16_bf16 v[20:35], v[80:83], v[88:91], v[20:35]
	v_fmac_f32_e32 v2, v70, v2
	v_div_scale_f32 v70, vcc, 1.0, v0, 1.0
	v_mul_f32_e32 v71, v70, v2
	v_mfma_f32_32x32x16_bf16 v[20:35], v[72:75], v[84:87], v[20:35]
	v_fma_f32 v72, -v1, v71, v70
	v_fmac_f32_e32 v71, v72, v2
	v_fma_f32 v1, -v1, v71, v70
	v_div_fmas_f32 v1, v1, v2, v71
	v_div_fixup_f32 v2, v1, v0, 1.0
	ds_bpermute_b32 v0, v221, v94
	v_pk_mul_f32 v[52:53], v[52:53], v[2:3] op_sel_hi:[1,0]
	v_pk_mul_f32 v[54:55], v[54:55], v[2:3] op_sel_hi:[1,0]
	v_pk_mul_f32 v[38:39], v[38:39], v[2:3] op_sel_hi:[1,0]
	v_pk_mul_f32 v[70:71], v[36:37], v[2:3] op_sel_hi:[1,0]
	v_cvt_pk_bf16_f32 v36, v52, v53
	v_cvt_pk_bf16_f32 v37, v54, v55
	v_cvt_pk_bf16_f32 v53, v38, v39
	v_pk_mul_f32 v[38:39], v[56:57], v[2:3] op_sel_hi:[1,0]
	v_pk_mul_f32 v[54:55], v[58:59], v[2:3] op_sel_hi:[1,0]
	v_cvt_pk_bf16_f32 v38, v38, v39
	v_cvt_pk_bf16_f32 v39, v54, v55
	v_pk_mul_f32 v[40:41], v[40:41], v[2:3] op_sel_hi:[1,0]
	v_pk_mul_f32 v[42:43], v[42:43], v[2:3] op_sel_hi:[1,0]
	v_permlane32_swap_b32_e32 v36, v38
	v_permlane32_swap_b32_e32 v37, v39
	s_waitcnt lgkmcnt(0)
	v_add_f32_e32 v0, v94, v0
	v_cvt_pk_bf16_f32 v54, v40, v41
	v_cvt_pk_bf16_f32 v55, v42, v43
	global_store_dwordx4 v[68:69], v[36:39], off
	v_pk_mul_f32 v[40:41], v[44:45], v[2:3] op_sel_hi:[1,0]
	v_pk_mul_f32 v[42:43], v[46:47], v[2:3] op_sel_hi:[1,0]
	v_pk_mul_f32 v[36:37], v[60:61], v[2:3] op_sel_hi:[1,0]
	v_pk_mul_f32 v[38:39], v[62:63], v[2:3] op_sel_hi:[1,0]
	v_div_scale_f32 v1, s[4:5], v0, v0, 1.0
	v_cvt_pk_bf16_f32 v36, v36, v37
	v_cvt_pk_bf16_f32 v37, v38, v39
	v_cvt_pk_bf16_f32 v40, v40, v41
	v_cvt_pk_bf16_f32 v41, v42, v43
	v_pk_mul_f32 v[38:39], v[64:65], v[2:3] op_sel_hi:[1,0]
	v_pk_mul_f32 v[42:43], v[66:67], v[2:3] op_sel_hi:[1,0]
	v_pk_mul_f32 v[44:45], v[48:49], v[2:3] op_sel_hi:[1,0]
	v_pk_mul_f32 v[46:47], v[50:51], v[2:3] op_sel_hi:[1,0]
	v_rcp_f32_e32 v2, v1
	v_cvt_pk_bf16_f32 v38, v38, v39
	v_cvt_pk_bf16_f32 v39, v42, v43
	s_nop 0
	v_permlane32_swap_b32_e32 v36, v38
	v_permlane32_swap_b32_e32 v37, v39
	global_store_dwordx4 v[68:69], v[36:39], off offset:32
	v_cvt_pk_bf16_f32 v52, v70, v71
	v_cvt_pk_bf16_f32 v42, v44, v45
	v_fma_f32 v36, -v1, v2, 1.0
	v_fmac_f32_e32 v2, v36, v2
	v_div_scale_f32 v36, vcc, 1.0, v0, 1.0
	v_mul_f32_e32 v37, v36, v2
	v_fma_f32 v38, -v1, v37, v36
	v_fmac_f32_e32 v37, v38, v2
	v_fma_f32 v1, -v1, v37, v36
	v_div_fmas_f32 v1, v1, v2, v37
	v_div_fixup_f32 v2, v1, v0, 1.0
	v_pk_mul_f32 v[20:21], v[20:21], v[2:3] op_sel_hi:[1,0]
	v_pk_mul_f32 v[22:23], v[22:23], v[2:3] op_sel_hi:[1,0]
	v_pk_mul_f32 v[6:7], v[6:7], v[2:3] op_sel_hi:[1,0]
	v_pk_mul_f32 v[36:37], v[4:5], v[2:3] op_sel_hi:[1,0]
	v_cvt_pk_bf16_f32 v4, v20, v21
	v_cvt_pk_bf16_f32 v5, v22, v23
	v_cvt_pk_bf16_f32 v21, v6, v7
	v_pk_mul_f32 v[6:7], v[24:25], v[2:3] op_sel_hi:[1,0]
	v_pk_mul_f32 v[22:23], v[26:27], v[2:3] op_sel_hi:[1,0]
	v_cvt_pk_bf16_f32 v6, v6, v7
	v_cvt_pk_bf16_f32 v7, v22, v23
	v_pk_mul_f32 v[8:9], v[8:9], v[2:3] op_sel_hi:[1,0]
	v_pk_mul_f32 v[10:11], v[10:11], v[2:3] op_sel_hi:[1,0]
	v_permlane32_swap_b32_e32 v4, v6
	v_permlane32_swap_b32_e32 v5, v7
	v_cvt_pk_bf16_f32 v22, v8, v9
	v_cvt_pk_bf16_f32 v23, v10, v11
	global_store_dwordx4 v[68:69], v[4:7], off offset:256
	v_pk_mul_f32 v[8:9], v[12:13], v[2:3] op_sel_hi:[1,0]
	v_pk_mul_f32 v[10:11], v[14:15], v[2:3] op_sel_hi:[1,0]
	v_pk_mul_f32 v[4:5], v[28:29], v[2:3] op_sel_hi:[1,0]
	v_pk_mul_f32 v[6:7], v[30:31], v[2:3] op_sel_hi:[1,0]
	v_cvt_pk_bf16_f32 v4, v4, v5
	v_cvt_pk_bf16_f32 v5, v6, v7
	v_cvt_pk_bf16_f32 v8, v8, v9
	v_cvt_pk_bf16_f32 v9, v10, v11
	v_pk_mul_f32 v[6:7], v[32:33], v[2:3] op_sel_hi:[1,0]
	v_pk_mul_f32 v[10:11], v[34:35], v[2:3] op_sel_hi:[1,0]
	v_pk_mul_f32 v[12:13], v[16:17], v[2:3] op_sel_hi:[1,0]
	v_pk_mul_f32 v[14:15], v[18:19], v[2:3] op_sel_hi:[1,0]
	v_cvt_pk_bf16_f32 v43, v46, v47
	v_cvt_pk_bf16_f32 v20, v36, v37
	v_cvt_pk_bf16_f32 v6, v6, v7
	v_cvt_pk_bf16_f32 v7, v10, v11
	v_cvt_pk_bf16_f32 v10, v12, v13
	v_cvt_pk_bf16_f32 v11, v14, v15
	v_permlane32_swap_b32_e32 v52, v54
	v_permlane32_swap_b32_e32 v53, v55
	v_permlane32_swap_b32_e32 v40, v42
	v_permlane32_swap_b32_e32 v41, v43
	v_permlane32_swap_b32_e32 v20, v22
	v_permlane32_swap_b32_e32 v21, v23
	v_permlane32_swap_b32_e32 v4, v6
	v_permlane32_swap_b32_e32 v5, v7
	v_permlane32_swap_b32_e32 v8, v10
	v_permlane32_swap_b32_e32 v9, v11
	global_store_dwordx4 v[68:69], v[52:55], off offset:64
	global_store_dwordx4 v[68:69], v[40:43], off offset:96
	global_store_dwordx4 v[68:69], v[20:23], off offset:320
	global_store_dwordx4 v[68:69], v[4:7], off offset:288
	global_store_dwordx4 v[68:69], v[8:11], off offset:352
	s_mov_b64 s[4:5], 0

.LBB0_1114:
	v_sub_f32_e32 v50, v158, v2
	v_sub_f32_e32 v51, v159, v2
	v_sub_f32_e32 v156, v156, v2
	v_sub_f32_e32 v157, v157, v2
	v_exp_f32_e32 v66, v50
	v_exp_f32_e32 v67, v51
	v_exp_f32_e32 v50, v156
	v_exp_f32_e32 v51, v157
	v_sub_f32_e32 v52, v52, v2
	v_sub_f32_e32 v53, v53, v2
	v_sub_f32_e32 v36, v36, v2
	v_sub_f32_e32 v37, v37, v2
	v_exp_f32_e32 v52, v52
	v_exp_f32_e32 v53, v53
	v_exp_f32_e32 v36, v36
	v_exp_f32_e32 v37, v37
	v_sub_f32_e32 v54, v54, v2
	v_sub_f32_e32 v55, v55, v2
	v_sub_f32_e32 v38, v38, v2
	v_sub_f32_e32 v39, v39, v2
	v_exp_f32_e32 v54, v54
	v_exp_f32_e32 v55, v55
	v_exp_f32_e32 v38, v38
	v_exp_f32_e32 v39, v39
	v_add_f32_e32 v156, v50, v66
	v_add_f32_e32 v157, v51, v67
	v_add_f32_e32 v158, v36, v52
	v_add_f32_e32 v159, v37, v53
	v_pk_add_f32 v[156:157], v[156:157], 0 op_sel_hi:[1,0]
	v_sub_f32_e32 v56, v56, v2
	v_sub_f32_e32 v57, v57, v2
	v_add_f32_e32 v156, v158, v156
	v_add_f32_e32 v157, v159, v157
	v_add_f32_e32 v158, v38, v54
	v_add_f32_e32 v159, v39, v55
	v_sub_f32_e32 v40, v40, v2
	v_sub_f32_e32 v41, v41, v2
	v_add_f32_e32 v156, v158, v156
	v_add_f32_e32 v157, v159, v157
	v_exp_f32_e32 v56, v56
	v_exp_f32_e32 v57, v57
	v_exp_f32_e32 v158, v40
	v_exp_f32_e32 v159, v41
	v_sub_f32_e32 v58, v58, v2
	v_sub_f32_e32 v59, v59, v2
	v_sub_f32_e32 v42, v42, v2
	v_sub_f32_e32 v43, v43, v2
	v_exp_f32_e32 v58, v58
	v_add_f32_e32 v40, v158, v56
	v_add_f32_e32 v41, v159, v57
	v_exp_f32_e32 v59, v59
	v_add_f32_e32 v40, v40, v156
	v_add_f32_e32 v41, v41, v157
	v_exp_f32_e32 v156, v42
	v_exp_f32_e32 v157, v43
	v_sub_f32_e32 v44, v44, v2
	v_sub_f32_e32 v45, v45, v2
	s_add_i32 s5, s78, 2
	v_exp_f32_e32 v194, v44
	v_add_f32_e32 v42, v156, v58
	v_add_f32_e32 v43, v157, v59
	v_exp_f32_e32 v195, v45
	v_add_f32_e32 v40, v42, v40
	v_add_f32_e32 v41, v43, v41
	v_sub_f32_e32 v42, v60, v2
	v_sub_f32_e32 v43, v61, v2
	v_sub_f32_e32 v44, v46, v2
	v_sub_f32_e32 v45, v47, v2
	v_exp_f32_e32 v60, v42
	v_exp_f32_e32 v61, v43
	s_add_i32 s4, s78, -2
	v_add_u32_e32 v189, 0xf8, v189
	v_add_u32_e32 v190, 0x2d00, v190
	v_add_f32_e32 v42, v194, v60
	v_add_f32_e32 v43, v195, v61
	v_add_u32_e32 v191, 0xa0, v191
	v_add_f32_e32 v40, v42, v40
	v_add_f32_e32 v41, v43, v41
	v_sub_f32_e32 v42, v62, v2
	v_sub_f32_e32 v43, v63, v2
	v_exp_f32_e32 v62, v44
	v_exp_f32_e32 v46, v42
	v_exp_f32_e32 v47, v43
	v_exp_f32_e32 v63, v45
	v_sub_f32_e32 v44, v48, v2
	v_sub_f32_e32 v45, v49, v2
	v_add_u32_e32 v192, 0xa0, v192
	s_cmp_lt_u32 s4, s9
	v_add_f32_e32 v42, v62, v46
	v_add_f32_e32 v43, v63, v47
	v_cvt_pk_bf16_f32 v46, v46, v47
	v_add_f32_e32 v40, v42, v40
	v_add_f32_e32 v41, v43, v41
	v_sub_f32_e32 v42, v64, v2
	v_sub_f32_e32 v43, v65, v2
	v_exp_f32_e32 v64, v44
	v_exp_f32_e32 v48, v42
	v_exp_f32_e32 v49, v43
	v_exp_f32_e32 v65, v45
	v_cvt_pk_bf16_f32 v44, v58, v59
	v_cvt_pk_bf16_f32 v45, v60, v61
	v_cvt_pk_bf16_f32 v47, v48, v49
	v_add_f32_e32 v42, v64, v48
	v_add_f32_e32 v43, v65, v49
	v_cvt_pk_bf16_f32 v48, v50, v51
	v_add_f32_e32 v40, v42, v40
	v_add_f32_e32 v41, v43, v41
	v_cvt_pk_bf16_f32 v42, v54, v55
	v_add_f32_e32 v0, v40, v41
	v_cvt_pk_bf16_f32 v40, v66, v67
	v_cvt_pk_bf16_f32 v41, v52, v53
	v_cvt_pk_bf16_f32 v43, v56, v57
	v_cvt_pk_bf16_f32 v49, v36, v37
	v_cvt_pk_bf16_f32 v50, v38, v39
	s_waitcnt lgkmcnt(11)
	v_mfma_f32_32x32x16_bf16 v[20:35], v[128:131], v[40:43], v[20:35]
	v_cvt_pk_bf16_f32 v51, v158, v159
	v_cvt_pk_bf16_f32 v36, v156, v157
	v_cvt_pk_bf16_f32 v37, v194, v195
	v_cvt_pk_bf16_f32 v38, v62, v63
	v_cvt_pk_bf16_f32 v39, v64, v65
	v_add_f32_e32 v164, v164, v0
	s_waitcnt lgkmcnt(10)
	v_mfma_f32_32x32x16_bf16 v[4:19], v[124:127], v[40:43], v[4:19]
	s_waitcnt lgkmcnt(6)
	v_mfma_f32_32x32x16_bf16 v[20:35], v[120:123], v[44:47], v[20:35]
	s_waitcnt lgkmcnt(4)
	v_mfma_f32_32x32x16_bf16 v[4:19], v[116:119], v[44:47], v[4:19]
	v_mfma_f32_32x32x16_bf16 v[20:35], v[112:115], v[48:51], v[20:35]
	v_mfma_f32_32x32x16_bf16 v[4:19], v[108:111], v[48:51], v[4:19]
	s_waitcnt lgkmcnt(2)
	v_mfma_f32_32x32x16_bf16 v[20:35], v[104:107], v[36:39], v[20:35]
	s_waitcnt lgkmcnt(0)
	v_mfma_f32_32x32x16_bf16 v[4:19], v[100:103], v[36:39], v[4:19]
	s_cbranch_scc0 .LBB0_1117
	s_mov_b32 s78, s5
	s_branch .LBB0_1047

.LBB0_1168:
	v_sub_f32_e32 v68, v68, v2
	v_sub_f32_e32 v69, v69, v2
	v_sub_f32_e32 v36, v36, v2
	v_sub_f32_e32 v37, v37, v2
	v_exp_f32_e32 v68, v68
	v_exp_f32_e32 v69, v69
	v_exp_f32_e32 v84, v36
	v_exp_f32_e32 v85, v37
	v_sub_f32_e32 v36, v70, v2
	v_sub_f32_e32 v37, v71, v2
	v_sub_f32_e32 v38, v38, v2
	v_sub_f32_e32 v39, v39, v2
	v_exp_f32_e32 v70, v36
	v_exp_f32_e32 v71, v37
	v_exp_f32_e32 v86, v38
	v_exp_f32_e32 v87, v39
	v_sub_f32_e32 v72, v72, v2
	v_sub_f32_e32 v73, v73, v2
	v_sub_f32_e32 v40, v40, v2
	v_sub_f32_e32 v41, v41, v2
	v_exp_f32_e32 v72, v72
	v_exp_f32_e32 v73, v73
	v_exp_f32_e32 v40, v40
	v_exp_f32_e32 v41, v41
	v_sub_f32_e32 v74, v74, v2
	v_sub_f32_e32 v75, v75, v2
	v_add_f32_e32 v36, v84, v68
	v_add_f32_e32 v37, v85, v69
	v_exp_f32_e32 v74, v74
	v_exp_f32_e32 v75, v75
	v_pk_add_f32 v[36:37], v[36:37], 0 op_sel_hi:[1,0]
	v_add_f32_e32 v38, v86, v70
	v_add_f32_e32 v39, v87, v71
	v_sub_f32_e32 v42, v42, v2
	v_sub_f32_e32 v43, v43, v2
	v_add_f32_e32 v36, v38, v36
	v_add_f32_e32 v37, v39, v37
	v_add_f32_e32 v38, v40, v72
	v_add_f32_e32 v39, v41, v73
	v_exp_f32_e32 v42, v42
	v_add_f32_e32 v100, v38, v36
	v_add_f32_e32 v101, v39, v37
	v_sub_f32_e32 v36, v76, v2
	v_sub_f32_e32 v37, v77, v2
	v_cvt_pk_bf16_f32 v38, v72, v73
	v_exp_f32_e32 v76, v36
	v_exp_f32_e32 v77, v37
	v_cvt_pk_bf16_f32 v36, v68, v69
	v_cvt_pk_bf16_f32 v37, v70, v71
	v_cvt_pk_bf16_f32 v39, v74, v75
	v_sub_f32_e32 v68, v78, v2
	v_sub_f32_e32 v69, v79, v2
	v_sub_f32_e32 v70, v80, v2
	v_sub_f32_e32 v71, v81, v2
	s_waitcnt lgkmcnt(7)
	v_mfma_f32_32x32x16_bf16 v[20:35], v[104:107], v[36:39], v[20:35]
	v_exp_f32_e32 v68, v68
	v_exp_f32_e32 v69, v69
	v_exp_f32_e32 v70, v70
	v_exp_f32_e32 v71, v71
	v_exp_f32_e32 v43, v43
	v_sub_f32_e32 v44, v44, v2
	v_sub_f32_e32 v45, v45, v2
	v_sub_f32_e32 v46, v46, v2
	v_sub_f32_e32 v47, v47, v2
	s_waitcnt lgkmcnt(5)
	v_mfma_f32_32x32x16_bf16 v[4:19], v[96:99], v[36:39], v[4:19]
	v_add_f32_e64 v36, v82, -v2
	v_add_f32_e64 v37, v83, -v2
	v_cvt_pk_bf16_f32 v38, v70, v71
	v_exp_f32_e32 v72, v36
	v_exp_f32_e32 v73, v37
	v_cvt_pk_bf16_f32 v36, v76, v77
	v_cvt_pk_bf16_f32 v37, v68, v69
	v_exp_f32_e32 v44, v44
	v_cvt_pk_bf16_f32 v39, v72, v73
	v_exp_f32_e32 v45, v45
	v_exp_f32_e32 v46, v46
	v_mfma_f32_32x32x16_bf16 v[20:35], v[92:95], v[36:39], v[20:35]
	v_exp_f32_e32 v47, v47
	v_add_f32_e32 v102, v42, v74
	v_add_f32_e32 v103, v43, v75
	v_add_f32_e32 v76, v44, v76
	v_add_f32_e32 v77, v45, v77
	v_add_f32_e32 v74, v102, v100
	v_add_f32_e32 v75, v103, v101
	v_add_f32_e32 v68, v46, v68
	v_add_f32_e32 v69, v47, v69
	v_add_f32_e32 v74, v76, v74
	v_add_f32_e32 v75, v77, v75
	v_lshlrev_b32_e32 v1, 2, v155
	s_waitcnt lgkmcnt(2)
	v_mfma_f32_32x32x16_bf16 v[4:19], v[88:91], v[36:39], v[4:19]
	v_add_f32_e64 v36, v48, -v2
	v_add_f32_e64 v37, v49, -v2
	v_cvt_pk_bf16_f32 v38, v40, v41
	v_exp_f32_e32 v48, v36
	v_exp_f32_e32 v49, v37
	v_sub_f32_e32 v40, v50, v2
	v_sub_f32_e32 v41, v51, v2
	v_cvt_pk_bf16_f32 v39, v42, v43
	v_exp_f32_e32 v40, v40
	v_exp_f32_e32 v41, v41
	v_add_f32_e32 v42, v68, v74
	v_add_f32_e32 v43, v69, v75
	v_add_f32_e32 v50, v48, v70
	v_add_f32_e32 v51, v49, v71
	v_cvt_pk_bf16_f32 v36, v84, v85
	v_cvt_pk_bf16_f32 v37, v86, v87
	v_add_f32_e32 v42, v50, v42
	v_add_f32_e32 v43, v51, v43
	v_add_f32_e32 v50, v40, v72
	v_add_f32_e32 v51, v41, v73
	v_mfma_f32_32x32x16_bf16 v[20:35], v[64:67], v[36:39], v[20:35]
	v_xor_b32_e32 v1, 0x80, v1
	s_or_b32 s6, s84, s90
	v_mfma_f32_32x32x16_bf16 v[4:19], v[60:63], v[36:39], v[4:19]
	v_add_f32_e64 v36, v50, v42
	v_add_f32_e64 v37, v51, v43
	v_cvt_pk_bf16_f32 v38, v48, v49
	v_add_f32_e32 v0, v36, v37
	v_add_f32_e32 v0, v112, v0
	ds_bpermute_b32 v1, v1, v0
	v_cvt_pk_bf16_f32 v36, v44, v45
	v_cvt_pk_bf16_f32 v37, v46, v47
	v_cvt_pk_bf16_f32 v39, v40, v41
	s_waitcnt lgkmcnt(0)
	v_add_f32_e32 v0, v0, v1
	v_div_scale_f32 v1, s[4:5], v0, v0, 1.0
	v_rcp_f32_e32 v2, v1
	v_mfma_f32_32x32x16_bf16 v[20:35], v[56:59], v[36:39], v[20:35]
	s_mov_b64 s[4:5], 0xd000400
	v_mfma_f32_32x32x16_bf16 v[4:19], v[52:55], v[36:39], v[4:19]
	v_fma_f32 v36, -v1, v2, 1.0
	v_fmac_f32_e32 v2, v36, v2
	v_div_scale_f32 v36, vcc, 1.0, v0, 1.0
	v_mul_f32_e32 v37, v36, v2
	v_fma_f32 v38, -v1, v37, v36
	v_fmac_f32_e32 v37, v38, v2
	v_fma_f32 v1, -v1, v37, v36
	v_lshlrev_b64 v[38:39], 12, v[132:133]
	v_div_fmas_f32 v1, v1, v2, v37
	v_lshl_add_u64 v[38:39], s[10:11], 0, v[38:39]
	v_div_fixup_f32 v36, v1, v0, 1.0
	v_lshl_add_u64 v[38:39], v[38:39], 0, s[20:21]
	v_lshlrev_b32_e32 v2, 1, v137
	v_lshl_add_u64 v[38:39], v[38:39], 0, v[2:3]
	v_pk_mul_f32 v[20:21], v[20:21], v[36:37] op_sel_hi:[1,0]
	v_pk_mul_f32 v[22:23], v[22:23], v[36:37] op_sel_hi:[1,0]
	v_pk_mul_f32 v[6:7], v[6:7], v[36:37] op_sel_hi:[1,0]
	v_lshl_add_u64 v[40:41], v[38:39], 0, s[4:5]
	v_pk_mul_f32 v[42:43], v[4:5], v[36:37] op_sel_hi:[1,0]
	v_cvt_pk_bf16_f32 v4, v20, v21
	v_cvt_pk_bf16_f32 v5, v22, v23
	v_cvt_pk_bf16_f32 v21, v6, v7
	v_pk_mul_f32 v[6:7], v[24:25], v[36:37] op_sel_hi:[1,0]
	v_pk_mul_f32 v[22:23], v[26:27], v[36:37] op_sel_hi:[1,0]
	v_pk_mul_f32 v[8:9], v[8:9], v[36:37] op_sel_hi:[1,0]
	s_mov_b32 s4, 0xd000000
	v_cvt_pk_bf16_f32 v6, v6, v7
	v_cvt_pk_bf16_f32 v7, v22, v23
	v_cvt_pk_bf16_f32 v22, v8, v9
	v_add_co_u32_e32 v8, vcc, s4, v38
	v_pk_mul_f32 v[10:11], v[10:11], v[36:37] op_sel_hi:[1,0]
	v_permlane32_swap_b32_e32 v4, v6
	v_permlane32_swap_b32_e32 v5, v7
	v_addc_co_u32_e32 v9, vcc, 0, v39, vcc
	v_readlane_b32 s4, v254, 58
	v_cvt_pk_bf16_f32 v23, v10, v11
	global_store_dwordx4 v[8:9], v[4:7], off offset:1024
	v_pk_mul_f32 v[8:9], v[12:13], v[36:37] op_sel_hi:[1,0]
	v_pk_mul_f32 v[10:11], v[14:15], v[36:37] op_sel_hi:[1,0]
	v_pk_mul_f32 v[4:5], v[28:29], v[36:37] op_sel_hi:[1,0]
	v_pk_mul_f32 v[6:7], v[30:31], v[36:37] op_sel_hi:[1,0]
	v_readlane_b32 s5, v254, 59
	v_cvt_pk_bf16_f32 v4, v4, v5
	v_cvt_pk_bf16_f32 v5, v6, v7
	v_cvt_pk_bf16_f32 v8, v8, v9
	v_cvt_pk_bf16_f32 v9, v10, v11
	v_pk_mul_f32 v[6:7], v[32:33], v[36:37] op_sel_hi:[1,0]
	v_pk_mul_f32 v[10:11], v[34:35], v[36:37] op_sel_hi:[1,0]
	v_pk_mul_f32 v[12:13], v[16:17], v[36:37] op_sel_hi:[1,0]
	v_pk_mul_f32 v[14:15], v[18:19], v[36:37] op_sel_hi:[1,0]
	s_and_b64 s[4:5], s[4:5], exec
	v_cvt_pk_bf16_f32 v20, v42, v43
	v_cvt_pk_bf16_f32 v6, v6, v7
	v_cvt_pk_bf16_f32 v7, v10, v11
	v_cvt_pk_bf16_f32 v10, v12, v13
	v_cvt_pk_bf16_f32 v11, v14, v15
	s_cselect_b32 s6, s36, s6
	v_permlane32_swap_b32_e32 v20, v22
	v_permlane32_swap_b32_e32 v21, v23
	v_permlane32_swap_b32_e32 v4, v6
	v_permlane32_swap_b32_e32 v5, v7
	v_permlane32_swap_b32_e32 v8, v10
	v_permlane32_swap_b32_e32 v9, v11
	s_cmpk_gt_i32 s6, 0x7f
	s_mov_b64 s[4:5], -1
	global_store_dwordx4 v[40:41], v[20:23], off offset:64
	global_store_dwordx4 v[40:41], v[4:7], off offset:32
	global_store_dwordx4 v[40:41], v[8:11], off offset:96
	s_cbranch_scc0 .LBB0_1188
	s_mov_b64 s[4:5], s[0:1]
	v_mov_b32_e32 v128, v202
	s_add_i32 s7, s6, 0xffffff80
	s_lshl_b32 s5, s7, 5
	v_readfirstlane_b32 s4, v128
	s_ashr_i32 s4, s4, 1
	v_lshlrev_b32_e32 v1, 4, v128
	s_and_b32 s20, s5, 0x7fffff00
	s_andn2_b32 s4, s4, 31
	v_and_b32_e32 v2, 0x70, v1
	v_add_u32_e32 v1, 0x200, v128
	v_and_b32_e32 v52, 31, v128
	s_add_i32 s4, s4, s20
	v_ashrrev_i32_e32 v42, 3, v1
	v_or_b32_e32 v124, s4, v52
	s_lshl_b64 s[4:5], s[20:21], 10
	v_min_i32_e32 v1, 0xff, v42
	s_add_u32 s8, s87, s4
	v_ashrrev_i32_e32 v4, 31, v1
	s_addc_u32 s5, s74, s5
	s_lshl_b32 s4, s7, 6
	v_add_u32_sdwa v4, v1, v4 dst_sel:DWORD dst_unused:UNUSED_PAD src0_sel:DWORD src1_sel:BYTE_3
	s_and_b32 s7, s4, 0x1c0
	v_and_b32_e32 v4, 0xffffff00, v4
	s_lshl_b32 s20, s7, 1
	v_sub_u32_e32 v4, v1, v4
	v_add_u32_e32 v1, 0x400, v128
	s_add_u32 s8, s8, s20
	v_ashrrev_i32_e32 v40, 3, v1
	s_addc_u32 s9, s5, 0
	v_min_i32_e32 v1, 0xff, v40
	s_mov_b32 s5, s21
	v_ashrrev_i32_e32 v6, 31, v1
	s_lshl_b64 s[4:5], s[4:5], 9
	v_ashrrev_i32_e32 v16, 4, v128
	v_add_u32_sdwa v6, v1, v6 dst_sel:DWORD dst_unused:UNUSED_PAD src0_sel:DWORD src1_sel:BYTE_3
	s_add_u32 s4, s10, s4
	v_ashrrev_i32_e32 v17, 31, v16
	v_lshlrev_b32_e32 v0, 3, v128
	v_and_b32_e32 v6, 0xffffff00, v6
	s_addc_u32 s5, s11, s5
	v_lshlrev_b64 v[14:15], 9, v[16:17]
	v_sub_u32_e32 v6, v1, v6
	v_add_u32_e32 v1, 0x600, v128
	v_lshl_add_u64 v[14:15], s[4:5], 0, v[14:15]
	v_and_b32_e32 v20, 0x78, v0
	v_mov_b32_e32 v21, v3
	v_ashrrev_i32_e32 v41, 3, v1
	v_lshl_add_u64 v[32:33], v[14:15], 0, v[20:21]
	s_mov_b64 s[4:5], 0x7c00000
	v_min_i32_e32 v1, 0xff, v41
	v_lshl_add_u64 v[30:31], v[32:33], 0, s[4:5]
	s_mov_b32 s4, 0x7c00000
	v_ashrrev_i32_e32 v12, 31, v1
	v_add_co_u32_e32 v24, vcc, s4, v32
	s_mov_b64 s[4:5], 0x7c04000
	v_add_u32_sdwa v12, v1, v12 dst_sel:DWORD dst_unused:UNUSED_PAD src0_sel:DWORD src1_sel:BYTE_3
	v_addc_co_u32_e32 v25, vcc, 0, v33, vcc
	v_lshl_add_u64 v[36:37], v[32:33], 0, s[4:5]
	s_mov_b32 s4, 0x7c04000
	v_and_b32_e32 v12, 0xffffff00, v12
	v_add_co_u32_e32 v32, vcc, s4, v32
	v_ashrrev_i32_e32 v125, 31, v124
	v_readlane_b32 s4, v254, 62
	v_sub_u32_e32 v12, v1, v12
	v_lshlrev_b64 v[38:39], 10, v[124:125]
	v_readlane_b32 s5, v254, 63
	v_bfe_u32 v53, v128, 5, 1
	v_ashrrev_i32_e32 v5, 31, v4
	v_ashrrev_i32_e32 v7, 31, v6
	v_ashrrev_i32_e32 v13, 31, v12
	v_lshl_add_u64 v[38:39], s[4:5], 0, v[38:39]
	v_lshl_add_u64 v[18:19], s[8:9], 0, v[2:3]
	v_lshlrev_b64 v[4:5], 10, v[4:5]
	v_lshlrev_b64 v[6:7], 10, v[6:7]
	v_lshlrev_b64 v[12:13], 10, v[12:13]
	v_lshl_add_u64 v[44:45], v[38:39], 0, s[20:21]
	v_lshlrev_b32_e32 v38, 4, v53
	v_mov_b32_e32 v39, v3
	v_lshl_add_u64 v[4:5], v[18:19], 0, v[4:5]
	v_lshl_add_u64 v[6:7], v[18:19], 0, v[6:7]
	v_lshl_add_u64 v[12:13], v[18:19], 0, v[12:13]
	v_addc_co_u32_e32 v33, vcc, 0, v33, vcc
	v_lshl_add_u64 v[44:45], v[44:45], 0, v[38:39]
	s_barrier
	global_load_dwordx4 v[8:11], v[4:5], off
	s_nop 0
	global_load_dwordx4 v[4:7], v[6:7], off
	s_nop 0
	global_load_dwordx4 v[12:15], v[12:13], off
	s_nop 0
	global_load_dwordx2 v[22:23], v[30:31], off offset:128
	s_nop 0
	global_load_dwordx2 v[24:25], v[24:25], off
	s_nop 0
	global_load_dwordx2 v[26:27], v[30:31], off offset:256
	global_load_dwordx2 v[28:29], v[36:37], off offset:128
	s_nop 0
	global_load_dwordx2 v[30:31], v[30:31], off offset:384
	s_nop 0
	global_load_dwordx2 v[32:33], v[32:33], off
	s_nop 0
	global_load_dwordx2 v[34:35], v[36:37], off offset:256
	s_nop 0
	global_load_dwordx2 v[36:37], v[36:37], off offset:384
	s_nop 0
	global_load_dwordx4 v[96:99], v[44:45], off
	global_load_dwordx4 v[92:95], v[44:45], off offset:32
	global_load_dwordx4 v[88:91], v[44:45], off offset:64
	global_load_dwordx4 v[84:87], v[44:45], off offset:96
	v_ashrrev_i32_e32 v17, 3, v128
	s_movk_i32 s4, 0x100
	v_add_u32_e32 v2, 0, v2
	v_cmp_gt_i32_e32 vcc, s4, v17
	s_and_saveexec_b64 s[4:5], vcc
	s_cbranch_execz .LBB0_1171
	v_ashrrev_i32_e32 v0, 31, v17
	v_add_u32_sdwa v0, v17, v0 dst_sel:DWORD dst_unused:UNUSED_PAD src0_sel:DWORD src1_sel:BYTE_3
	v_and_b32_e32 v0, 0xffffff00, v0
	v_sub_u32_e32 v44, v17, v0
	v_ashrrev_i32_e32 v45, 31, v44
	v_lshlrev_b64 v[44:45], 10, v[44:45]
	v_lshl_add_u64 v[18:19], v[18:19], 0, v[44:45]
	global_load_dwordx4 v[44:47], v[18:19], off
	s_movk_i32 s7, 0x90
	v_mad_u64_u32 v[18:19], s[8:9], v17, s7, v[2:3]
	s_waitcnt vmcnt(0)
	ds_write_b128 v18, v[44:47]

.LBB0_1206:
	v_sub_f32_e32 v68, v68, v2
	v_sub_f32_e32 v69, v69, v2
	v_sub_f32_e32 v36, v36, v2
	v_sub_f32_e32 v37, v37, v2
	v_exp_f32_e32 v68, v68
	v_exp_f32_e32 v69, v69
	v_exp_f32_e32 v84, v36
	v_exp_f32_e32 v85, v37
	v_sub_f32_e32 v36, v70, v2
	v_sub_f32_e32 v37, v71, v2
	v_sub_f32_e32 v38, v38, v2
	v_sub_f32_e32 v39, v39, v2
	v_exp_f32_e32 v70, v36
	v_exp_f32_e32 v71, v37
	v_exp_f32_e32 v86, v38
	v_exp_f32_e32 v87, v39
	v_sub_f32_e32 v72, v72, v2
	v_sub_f32_e32 v73, v73, v2
	v_sub_f32_e32 v40, v40, v2
	v_sub_f32_e32 v41, v41, v2
	v_exp_f32_e32 v72, v72
	v_exp_f32_e32 v73, v73
	v_exp_f32_e32 v40, v40
	v_exp_f32_e32 v41, v41
	v_sub_f32_e32 v74, v74, v2
	v_sub_f32_e32 v75, v75, v2
	v_add_f32_e32 v36, v84, v68
	v_add_f32_e32 v37, v85, v69
	v_exp_f32_e32 v74, v74
	v_exp_f32_e32 v75, v75
	v_pk_add_f32 v[36:37], v[36:37], 0 op_sel_hi:[1,0]
	v_add_f32_e32 v38, v86, v70
	v_add_f32_e32 v39, v87, v71
	v_sub_f32_e32 v42, v42, v2
	v_sub_f32_e32 v43, v43, v2
	v_add_f32_e32 v36, v38, v36
	v_add_f32_e32 v37, v39, v37
	v_add_f32_e32 v38, v40, v72
	v_add_f32_e32 v39, v41, v73
	v_exp_f32_e32 v42, v42
	v_add_f32_e32 v100, v38, v36
	v_add_f32_e32 v101, v39, v37
	v_sub_f32_e32 v36, v76, v2
	v_sub_f32_e32 v37, v77, v2
	v_cvt_pk_bf16_f32 v38, v72, v73
	v_exp_f32_e32 v76, v36
	v_exp_f32_e32 v77, v37
	v_cvt_pk_bf16_f32 v36, v68, v69
	v_cvt_pk_bf16_f32 v37, v70, v71
	v_cvt_pk_bf16_f32 v39, v74, v75
	v_sub_f32_e32 v68, v78, v2
	v_sub_f32_e32 v69, v79, v2
	v_sub_f32_e32 v70, v80, v2
	v_sub_f32_e32 v71, v81, v2
	s_waitcnt lgkmcnt(7)
	v_mfma_f32_32x32x16_bf16 v[20:35], v[104:107], v[36:39], v[20:35]
	v_exp_f32_e32 v68, v68
	v_exp_f32_e32 v69, v69
	v_exp_f32_e32 v70, v70
	v_exp_f32_e32 v71, v71
	v_exp_f32_e32 v43, v43
	v_sub_f32_e32 v44, v44, v2
	v_sub_f32_e32 v45, v45, v2
	v_sub_f32_e32 v46, v46, v2
	v_sub_f32_e32 v47, v47, v2
	s_waitcnt lgkmcnt(5)
	v_mfma_f32_32x32x16_bf16 v[4:19], v[96:99], v[36:39], v[4:19]
	v_add_f32_e64 v36, v82, -v2
	v_add_f32_e64 v37, v83, -v2
	v_cvt_pk_bf16_f32 v38, v70, v71
	v_exp_f32_e32 v72, v36
	v_exp_f32_e32 v73, v37
	v_cvt_pk_bf16_f32 v36, v76, v77
	v_cvt_pk_bf16_f32 v37, v68, v69
	v_exp_f32_e32 v44, v44
	v_cvt_pk_bf16_f32 v39, v72, v73
	v_exp_f32_e32 v45, v45
	v_exp_f32_e32 v46, v46
	v_mfma_f32_32x32x16_bf16 v[20:35], v[92:95], v[36:39], v[20:35]
	v_exp_f32_e32 v47, v47
	v_add_f32_e32 v102, v42, v74
	v_add_f32_e32 v103, v43, v75
	v_add_f32_e32 v76, v44, v76
	v_add_f32_e32 v77, v45, v77
	v_add_f32_e32 v74, v102, v100
	v_add_f32_e32 v75, v103, v101
	v_add_f32_e32 v68, v46, v68
	v_add_f32_e32 v69, v47, v69
	v_add_f32_e32 v74, v76, v74
	v_add_f32_e32 v75, v77, v75
	v_lshlrev_b32_e32 v1, 2, v127
	s_waitcnt lgkmcnt(2)
	v_mfma_f32_32x32x16_bf16 v[4:19], v[88:91], v[36:39], v[4:19]
	v_add_f32_e64 v36, v48, -v2
	v_add_f32_e64 v37, v49, -v2
	v_cvt_pk_bf16_f32 v38, v40, v41
	v_exp_f32_e32 v48, v36
	v_exp_f32_e32 v49, v37
	v_sub_f32_e32 v40, v50, v2
	v_sub_f32_e32 v41, v51, v2
	v_cvt_pk_bf16_f32 v39, v42, v43
	v_exp_f32_e32 v40, v40
	v_exp_f32_e32 v41, v41
	v_add_f32_e32 v42, v68, v74
	v_add_f32_e32 v43, v69, v75
	v_add_f32_e32 v50, v48, v70
	v_add_f32_e32 v51, v49, v71
	v_cvt_pk_bf16_f32 v36, v84, v85
	v_cvt_pk_bf16_f32 v37, v86, v87
	v_add_f32_e32 v42, v50, v42
	v_add_f32_e32 v43, v51, v43
	v_add_f32_e32 v50, v40, v72
	v_add_f32_e32 v51, v41, v73
	v_mfma_f32_32x32x16_bf16 v[20:35], v[64:67], v[36:39], v[20:35]
	v_xor_b32_e32 v1, 0x80, v1
	v_mfma_f32_32x32x16_bf16 v[4:19], v[60:63], v[36:39], v[4:19]
	v_add_f32_e64 v36, v50, v42
	v_add_f32_e64 v37, v51, v43
	v_cvt_pk_bf16_f32 v38, v48, v49
	v_add_f32_e32 v0, v36, v37
	v_add_f32_e32 v0, v112, v0
	ds_bpermute_b32 v1, v1, v0
	v_cvt_pk_bf16_f32 v36, v44, v45
	v_cvt_pk_bf16_f32 v37, v46, v47
	v_cvt_pk_bf16_f32 v39, v40, v41
	s_waitcnt lgkmcnt(0)
	v_add_f32_e32 v0, v0, v1
	v_div_scale_f32 v1, s[4:5], v0, v0, 1.0
	v_rcp_f32_e32 v2, v1
	v_mfma_f32_32x32x16_bf16 v[20:35], v[56:59], v[36:39], v[20:35]
	s_lshl_b32 s4, s7, 6
	s_lshl_b32 s20, s4, 1
	v_mfma_f32_32x32x16_bf16 v[4:19], v[52:55], v[36:39], v[4:19]
	v_fma_f32 v36, -v1, v2, 1.0
	v_fmac_f32_e32 v2, v36, v2
	v_div_scale_f32 v36, vcc, 1.0, v0, 1.0
	v_mul_f32_e32 v37, v36, v2
	v_fma_f32 v38, -v1, v37, v36
	v_fmac_f32_e32 v37, v38, v2
	v_fma_f32 v1, -v1, v37, v36
	v_div_fmas_f32 v1, v1, v2, v37
	v_div_fixup_f32 v36, v1, v0, 1.0
	v_lshlrev_b64 v[38:39], 12, v[124:125]
	v_pk_mul_f32 v[20:21], v[20:21], v[36:37] op_sel_hi:[1,0]
	v_pk_mul_f32 v[22:23], v[22:23], v[36:37] op_sel_hi:[1,0]
	v_pk_mul_f32 v[6:7], v[6:7], v[36:37] op_sel_hi:[1,0]
	v_lshl_add_u64 v[38:39], s[70:71], 0, v[38:39]
	v_pk_mul_f32 v[40:41], v[4:5], v[36:37] op_sel_hi:[1,0]
	v_cvt_pk_bf16_f32 v4, v20, v21
	v_cvt_pk_bf16_f32 v5, v22, v23
	v_cvt_pk_bf16_f32 v21, v6, v7
	v_pk_mul_f32 v[6:7], v[24:25], v[36:37] op_sel_hi:[1,0]
	v_pk_mul_f32 v[22:23], v[26:27], v[36:37] op_sel_hi:[1,0]
	v_lshl_add_u64 v[38:39], v[38:39], 0, s[20:21]
	v_lshlrev_b32_e32 v2, 1, v126
	v_cvt_pk_bf16_f32 v6, v6, v7
	v_cvt_pk_bf16_f32 v7, v22, v23
	v_lshl_add_u64 v[38:39], v[38:39], 0, v[2:3]
	v_pk_mul_f32 v[8:9], v[8:9], v[36:37] op_sel_hi:[1,0]
	v_pk_mul_f32 v[10:11], v[10:11], v[36:37] op_sel_hi:[1,0]
	v_permlane32_swap_b32_e32 v4, v6
	v_permlane32_swap_b32_e32 v5, v7
	v_cvt_pk_bf16_f32 v22, v8, v9
	v_cvt_pk_bf16_f32 v23, v10, v11
	global_store_dwordx4 v[38:39], v[4:7], off
	v_pk_mul_f32 v[8:9], v[12:13], v[36:37] op_sel_hi:[1,0]
	v_pk_mul_f32 v[10:11], v[14:15], v[36:37] op_sel_hi:[1,0]
	v_pk_mul_f32 v[4:5], v[28:29], v[36:37] op_sel_hi:[1,0]
	v_pk_mul_f32 v[6:7], v[30:31], v[36:37] op_sel_hi:[1,0]
	v_cvt_pk_bf16_f32 v4, v4, v5
	v_cvt_pk_bf16_f32 v5, v6, v7
	v_cvt_pk_bf16_f32 v8, v8, v9
	v_cvt_pk_bf16_f32 v9, v10, v11
	v_pk_mul_f32 v[6:7], v[32:33], v[36:37] op_sel_hi:[1,0]
	v_pk_mul_f32 v[10:11], v[34:35], v[36:37] op_sel_hi:[1,0]
	v_pk_mul_f32 v[12:13], v[16:17], v[36:37] op_sel_hi:[1,0]
	v_pk_mul_f32 v[14:15], v[18:19], v[36:37] op_sel_hi:[1,0]
	v_cvt_pk_bf16_f32 v20, v40, v41
	v_cvt_pk_bf16_f32 v6, v6, v7
	v_cvt_pk_bf16_f32 v7, v10, v11
	v_cvt_pk_bf16_f32 v10, v12, v13
	v_cvt_pk_bf16_f32 v11, v14, v15
	v_permlane32_swap_b32_e32 v20, v22
	v_permlane32_swap_b32_e32 v21, v23
	v_permlane32_swap_b32_e32 v4, v6
	v_permlane32_swap_b32_e32 v5, v7
	v_permlane32_swap_b32_e32 v8, v10
	v_permlane32_swap_b32_e32 v9, v11
	global_store_dwordx4 v[38:39], v[20:23], off offset:64
	global_store_dwordx4 v[38:39], v[4:7], off offset:32
	global_store_dwordx4 v[38:39], v[8:11], off offset:96
	s_cbranch_execnz .LBB0_1248
	s_branch .LBB0_1217

.LBB0_1214:
	v_sub_f32_e32 v68, v68, v2
	v_sub_f32_e32 v69, v69, v2
	v_sub_f32_e32 v36, v36, v2
	v_sub_f32_e32 v37, v37, v2
	v_exp_f32_e32 v68, v68
	v_exp_f32_e32 v69, v69
	v_exp_f32_e32 v84, v36
	v_exp_f32_e32 v85, v37
	v_sub_f32_e32 v36, v70, v2
	v_sub_f32_e32 v37, v71, v2
	v_sub_f32_e32 v38, v38, v2
	v_sub_f32_e32 v39, v39, v2
	v_exp_f32_e32 v70, v36
	v_exp_f32_e32 v71, v37
	v_exp_f32_e32 v86, v38
	v_exp_f32_e32 v87, v39
	v_sub_f32_e32 v72, v72, v2
	v_sub_f32_e32 v73, v73, v2
	v_sub_f32_e32 v40, v40, v2
	v_sub_f32_e32 v41, v41, v2
	v_exp_f32_e32 v72, v72
	v_exp_f32_e32 v73, v73
	v_exp_f32_e32 v40, v40
	v_exp_f32_e32 v41, v41
	v_sub_f32_e32 v74, v74, v2
	v_sub_f32_e32 v75, v75, v2
	v_add_f32_e32 v36, v84, v68
	v_add_f32_e32 v37, v85, v69
	v_exp_f32_e32 v74, v74
	v_exp_f32_e32 v75, v75
	v_pk_add_f32 v[36:37], v[36:37], 0 op_sel_hi:[1,0]
	v_add_f32_e32 v38, v86, v70
	v_add_f32_e32 v39, v87, v71
	v_sub_f32_e32 v42, v42, v2
	v_sub_f32_e32 v43, v43, v2
	v_add_f32_e32 v36, v38, v36
	v_add_f32_e32 v37, v39, v37
	v_add_f32_e32 v38, v40, v72
	v_add_f32_e32 v39, v41, v73
	v_exp_f32_e32 v42, v42
	v_add_f32_e32 v100, v38, v36
	v_add_f32_e32 v101, v39, v37
	v_sub_f32_e32 v36, v76, v2
	v_sub_f32_e32 v37, v77, v2
	v_cvt_pk_bf16_f32 v38, v72, v73
	v_exp_f32_e32 v76, v36
	v_exp_f32_e32 v77, v37
	v_cvt_pk_bf16_f32 v36, v68, v69
	v_cvt_pk_bf16_f32 v37, v70, v71
	v_cvt_pk_bf16_f32 v39, v74, v75
	v_sub_f32_e32 v68, v78, v2
	v_sub_f32_e32 v69, v79, v2
	v_sub_f32_e32 v70, v80, v2
	v_sub_f32_e32 v71, v81, v2
	s_waitcnt lgkmcnt(7)
	v_mfma_f32_32x32x16_bf16 v[20:35], v[104:107], v[36:39], v[20:35]
	v_exp_f32_e32 v68, v68
	v_exp_f32_e32 v69, v69
	v_exp_f32_e32 v70, v70
	v_exp_f32_e32 v71, v71
	v_exp_f32_e32 v43, v43
	v_sub_f32_e32 v44, v44, v2
	v_sub_f32_e32 v45, v45, v2
	v_sub_f32_e32 v46, v46, v2
	v_sub_f32_e32 v47, v47, v2
	s_waitcnt lgkmcnt(5)
	v_mfma_f32_32x32x16_bf16 v[4:19], v[96:99], v[36:39], v[4:19]
	v_add_f32_e64 v36, v82, -v2
	v_add_f32_e64 v37, v83, -v2
	v_cvt_pk_bf16_f32 v38, v70, v71
	v_exp_f32_e32 v72, v36
	v_exp_f32_e32 v73, v37
	v_cvt_pk_bf16_f32 v36, v76, v77
	v_cvt_pk_bf16_f32 v37, v68, v69
	v_exp_f32_e32 v44, v44
	v_cvt_pk_bf16_f32 v39, v72, v73
	v_exp_f32_e32 v45, v45
	v_exp_f32_e32 v46, v46
	v_mfma_f32_32x32x16_bf16 v[20:35], v[92:95], v[36:39], v[20:35]
	v_exp_f32_e32 v47, v47
	v_add_f32_e32 v102, v42, v74
	v_add_f32_e32 v103, v43, v75
	v_add_f32_e32 v76, v44, v76
	v_add_f32_e32 v77, v45, v77
	v_add_f32_e32 v74, v102, v100
	v_add_f32_e32 v75, v103, v101
	v_add_f32_e32 v68, v46, v68
	v_add_f32_e32 v69, v47, v69
	v_add_f32_e32 v74, v76, v74
	v_add_f32_e32 v75, v77, v75
	v_lshlrev_b32_e32 v1, 2, v127
	s_waitcnt lgkmcnt(2)
	v_mfma_f32_32x32x16_bf16 v[4:19], v[88:91], v[36:39], v[4:19]
	v_add_f32_e64 v36, v48, -v2
	v_add_f32_e64 v37, v49, -v2
	v_cvt_pk_bf16_f32 v38, v40, v41
	v_exp_f32_e32 v48, v36
	v_exp_f32_e32 v49, v37
	v_sub_f32_e32 v40, v50, v2
	v_sub_f32_e32 v41, v51, v2
	v_cvt_pk_bf16_f32 v39, v42, v43
	v_exp_f32_e32 v40, v40
	v_exp_f32_e32 v41, v41
	v_add_f32_e32 v42, v68, v74
	v_add_f32_e32 v43, v69, v75
	v_add_f32_e32 v50, v48, v70
	v_add_f32_e32 v51, v49, v71
	v_cvt_pk_bf16_f32 v36, v84, v85
	v_cvt_pk_bf16_f32 v37, v86, v87
	v_add_f32_e32 v42, v50, v42
	v_add_f32_e32 v43, v51, v43
	v_add_f32_e32 v50, v40, v72
	v_add_f32_e32 v51, v41, v73
	v_mfma_f32_32x32x16_bf16 v[20:35], v[64:67], v[36:39], v[20:35]
	v_xor_b32_e32 v1, 0x80, v1
	v_mfma_f32_32x32x16_bf16 v[4:19], v[60:63], v[36:39], v[4:19]
	v_add_f32_e64 v36, v50, v42
	v_add_f32_e64 v37, v51, v43
	v_cvt_pk_bf16_f32 v38, v48, v49
	v_add_f32_e32 v0, v36, v37
	v_add_f32_e32 v0, v112, v0
	ds_bpermute_b32 v1, v1, v0
	v_cvt_pk_bf16_f32 v36, v44, v45
	v_cvt_pk_bf16_f32 v37, v46, v47
	v_cvt_pk_bf16_f32 v39, v40, v41
	s_waitcnt lgkmcnt(0)
	v_add_f32_e32 v0, v0, v1
	v_div_scale_f32 v1, s[4:5], v0, v0, 1.0
	v_rcp_f32_e32 v2, v1
	v_mfma_f32_32x32x16_bf16 v[20:35], v[56:59], v[36:39], v[20:35]
	s_lshl_b32 s4, s7, 6
	s_lshl_b32 s20, s4, 1
	v_mfma_f32_32x32x16_bf16 v[4:19], v[52:55], v[36:39], v[4:19]
	v_fma_f32 v36, -v1, v2, 1.0
	v_fmac_f32_e32 v2, v36, v2
	v_div_scale_f32 v36, vcc, 1.0, v0, 1.0
	v_mul_f32_e32 v37, v36, v2
	v_fma_f32 v38, -v1, v37, v36
	v_fmac_f32_e32 v37, v38, v2
	v_fma_f32 v1, -v1, v37, v36
	v_div_fmas_f32 v1, v1, v2, v37
	v_div_fixup_f32 v36, v1, v0, 1.0
	v_lshlrev_b64 v[38:39], 12, v[124:125]
	v_pk_mul_f32 v[20:21], v[20:21], v[36:37] op_sel_hi:[1,0]
	v_pk_mul_f32 v[22:23], v[22:23], v[36:37] op_sel_hi:[1,0]
	v_pk_mul_f32 v[6:7], v[6:7], v[36:37] op_sel_hi:[1,0]
	v_lshl_add_u64 v[38:39], s[70:71], 0, v[38:39]
	v_pk_mul_f32 v[40:41], v[4:5], v[36:37] op_sel_hi:[1,0]
	v_cvt_pk_bf16_f32 v4, v20, v21
	v_cvt_pk_bf16_f32 v5, v22, v23
	v_cvt_pk_bf16_f32 v21, v6, v7
	v_pk_mul_f32 v[6:7], v[24:25], v[36:37] op_sel_hi:[1,0]
	v_pk_mul_f32 v[22:23], v[26:27], v[36:37] op_sel_hi:[1,0]
	v_lshl_add_u64 v[38:39], v[38:39], 0, s[20:21]
	v_lshlrev_b32_e32 v2, 1, v126
	v_cvt_pk_bf16_f32 v6, v6, v7
	v_cvt_pk_bf16_f32 v7, v22, v23
	v_lshl_add_u64 v[38:39], v[38:39], 0, v[2:3]
	v_pk_mul_f32 v[8:9], v[8:9], v[36:37] op_sel_hi:[1,0]
	v_pk_mul_f32 v[10:11], v[10:11], v[36:37] op_sel_hi:[1,0]
	v_permlane32_swap_b32_e32 v4, v6
	v_permlane32_swap_b32_e32 v5, v7
	v_cvt_pk_bf16_f32 v22, v8, v9
	v_cvt_pk_bf16_f32 v23, v10, v11
	global_store_dwordx4 v[38:39], v[4:7], off
	v_pk_mul_f32 v[8:9], v[12:13], v[36:37] op_sel_hi:[1,0]
	v_pk_mul_f32 v[10:11], v[14:15], v[36:37] op_sel_hi:[1,0]
	v_pk_mul_f32 v[4:5], v[28:29], v[36:37] op_sel_hi:[1,0]
	v_pk_mul_f32 v[6:7], v[30:31], v[36:37] op_sel_hi:[1,0]
	v_cvt_pk_bf16_f32 v4, v4, v5
	v_cvt_pk_bf16_f32 v5, v6, v7
	v_cvt_pk_bf16_f32 v8, v8, v9
	v_cvt_pk_bf16_f32 v9, v10, v11
	v_pk_mul_f32 v[6:7], v[32:33], v[36:37] op_sel_hi:[1,0]
	v_pk_mul_f32 v[10:11], v[34:35], v[36:37] op_sel_hi:[1,0]
	v_pk_mul_f32 v[12:13], v[16:17], v[36:37] op_sel_hi:[1,0]
	v_pk_mul_f32 v[14:15], v[18:19], v[36:37] op_sel_hi:[1,0]
	v_cvt_pk_bf16_f32 v20, v40, v41
	v_cvt_pk_bf16_f32 v6, v6, v7
	v_cvt_pk_bf16_f32 v7, v10, v11
	v_cvt_pk_bf16_f32 v10, v12, v13
	v_cvt_pk_bf16_f32 v11, v14, v15
	v_permlane32_swap_b32_e32 v20, v22
	v_permlane32_swap_b32_e32 v21, v23
	v_permlane32_swap_b32_e32 v4, v6
	v_permlane32_swap_b32_e32 v5, v7
	v_permlane32_swap_b32_e32 v8, v10
	v_permlane32_swap_b32_e32 v9, v11
	global_store_dwordx4 v[38:39], v[20:23], off offset:64
	global_store_dwordx4 v[38:39], v[4:7], off offset:32
	global_store_dwordx4 v[38:39], v[8:11], off offset:96
